# static priority for the younger wave half (wr=1) in the five GEMM phases, per-segment priority flips removed from the K-loops
# baseline (speedup 1.0000x reference)
; __device__ __forceinline__ f32x4 zero4_pk() { f32x2_z a, b; asm volatile("v_pk_mov_b32 %0, 0, 0" : "=v"(a)); asm volatile("v_pk_mov_b32 %0, 0, 0" : "=v"(b)); return (f32x4){a.x, a.y, b.x, b.y}; }
; template <class Epi, class Sched, bool ALIGN_EPI = false, bool SP2 = false>
; __device__ __forceinline__ void gemm_phase(PG8_LAS unsigned char* lds, const Gemm g, const Sched& S, const Epi& E, int wave_u) {
;     ...
;     Unit cur, nxt; int ui = 0;
;     if (!S.next(0, cur)) return;
;     f32x4 acc[2][2][4][2];
; #pragma unroll
;     for (int a = 0; a < 2; ++a)
; #pragma unroll
;         for (int b = 0; b < 2; ++b)
; #pragma unroll
;             for (int m = 0; m < 4; ++m)
; #pragma unroll
;                 for (int n = 0; n < 2; ++n) acc[a][b][m][n] = zero4_pk();
;     bf16x8 At[4][2], B0[2][2], B1[2][2];
;     const char* cA = (const char*)g.A + (size_t)cur.pm * tstep; const char* cB = (const char*)g.Bt + (size_t)cur.pn * tstep;
.LBB0_134:
	v_readlane_b32 s0, v255, 41
	v_readlane_b32 s1, v255, 42
	s_mov_b32 s1, s3
	v_writelane_b32 v255, s0, 41
	v_readlane_b32 s2, v250, 19
	s_nop 0
	v_writelane_b32 v255, s1, 42
	s_lshl_b64 s[0:1], s[0:1], 20
	s_add_u32 s14, s2, s0
	v_readlane_b32 s0, v250, 20
	s_addc_u32 s15, s0, s1
	s_andn2_b64 vcc, exec, s[10:11]
	s_cbranch_vccnz .LBB0_188
; __device__ __forceinline__ f32x4 zero4_pk() { f32x2_z a, b; asm volatile("v_pk_mov_b32 %0, 0, 0" : "=v"(a)); asm volatile("v_pk_mov_b32 %0, 0, 0" : "=v"(b)); return (f32x4){a.x, a.y, b.x, b.y}; }
; #define PG8_STAGE(bufoff, gbase, voff) do { _Pragma("unroll") for (int _i = 0; _i < 2; ++_i) \
;         glds16_asm((const char*)(gbase) + (voff)[_i], ldsb + (unsigned)((bufoff) + _i * 8192)); } while (0)
; #define PG8_BAR __builtin_amdgcn_s_barrier()
; template <class Epi, class Sched, bool ALIGN_EPI = false, bool SP2 = false>
; __device__ __forceinline__ void gemm_phase(PG8_LAS unsigned char* lds, const Gemm g, const Sched& S, const Epi& E, int wave_u) {
;     ...
; #pragma unroll
;     for (int i = 0; i < 2; ++i) { int R, C; stage_rc(tid * 16 + i * 8192, R, C); const int Rb = Epi::PERM ? ((R & ~31) + perm32(R & 31)) : R;
;         voffA[i] = (unsigned)(R * K + C) * 2u; voffB[i] = (unsigned)(Rb * K + C) * 2u; }
;     const size_t kstep = (size_t)(BK * 2);
;     const size_t hstep = (size_t)HALF * K * 2;
;     const size_t tstep = 2 * hstep;
;     const unsigned ldsw = (unsigned)wid * 1024u;
;     const unsigned ldsb = (unsigned)__builtin_amdgcn_readfirstlane((int)((unsigned)(size_t)lds + ldsw));
;     const int aoff = lds_byte(wr * 64 + fr, fq * 8), boff = lds_byte(wc * 32 + fr, fq * 8);
;     ...
;     const unsigned evb = (unsigned)__builtin_amdgcn_readfirstlane((int)((unsigned)(size_t)lds + (unsigned)EPV_OFF + (unsigned)wid * 256u));
;     Unit cur, nxt; int ui = 0;
;     if (!S.next(0, cur)) return;
;     f32x4 acc[2][2][4][2];
; #pragma unroll
;     for (int a = 0; a < 2; ++a)
; #pragma unroll
;         for (int b = 0; b < 2; ++b)
; #pragma unroll
;             for (int m = 0; m < 4; ++m)
; #pragma unroll
;                 for (int n = 0; n < 2; ++n) acc[a][b][m][n] = zero4_pk();
;     bf16x8 At[4][2], B0[2][2], B1[2][2];
;     const char* cA = (const char*)g.A + (size_t)cur.pm * tstep; const char* cB = (const char*)g.Bt + (size_t)cur.pn * tstep;
;     S.a_ready(cur);
;     epi_prefetch(E, cur.pm, cur.pn, evb, tid);
;     if constexpr (SP2) {
;         PG8_STAGE(PG8_SB(0, 0), cB, voffB); PG8_STAGE(PG8_SB(0, 1), cB + hstep, voffB); PG8_STAGE(PG8_SA(0, 0), cA, voffA); PG8_STAGE(PG8_SA(0, 1), cA + hstep, voffA);
;         if (wr == 1) PG8_BAR;
	s_waitcnt vmcnt(0)
	v_bfe_i32 v3, v130, 27, 1
	v_lshlrev_b32_e32 v0, 4, v130
	v_lshrrev_b32_e32 v3, 22, v3
	v_add_u32_e32 v3, v0, v3
	v_and_b32_e32 v3, 0xfffffc00, v3
	v_sub_u32_e32 v3, v0, v3
	v_ashrrev_i32_e32 v131, 31, v130
	v_lshrrev_b32_e32 v4, 4, v3
	v_lshrrev_b32_e32 v2, 26, v131
	v_bitop3_b32 v3, v4, v3, 32 bitop3:0x6c
	v_add_u32_e32 v2, v130, v2
	v_ashrrev_i32_e32 v5, 31, v3
	v_ashrrev_i32_e32 v2, 6, v2
	v_lshrrev_b32_e32 v5, 26, v5
	v_lshlrev_b32_e32 v4, 3, v2
	v_add_u32_e32 v5, v3, v5
	v_and_b32_e32 v4, -16, v4
	v_ashrrev_i32_e32 v6, 6, v5
	v_and_b32_e32 v5, 0xc0, v5
	v_add_u32_e32 v4, v6, v4
	v_sub_u32_e32 v3, v3, v5
	v_mov_b32_e32 v8, 1
	v_lshlrev_b32_e32 v2, 5, v2
	v_ashrrev_i16_sdwa v3, v8, sext(v3) dst_sel:DWORD dst_unused:UNUSED_PAD src0_sel:DWORD src1_sel:BYTE_0
	v_lshlrev_b32_e32 v5, 1, v4
	v_lshrrev_b32_e32 v7, 2, v4
	v_and_b32_e32 v6, 3, v6
	s_mov_b32 s1, 0x1fffe0
	v_and_b32_e32 v2, 32, v2
	v_bfe_i32 v3, v3, 0, 16
	v_and_b32_e32 v5, 24, v5
	v_and_b32_e32 v7, 4, v7
	v_and_or_b32 v6, v4, s1, v6
	v_or3_b32 v5, v6, v7, v5
	v_add_lshl_u32 v2, v2, v3, 1
	v_add_u32_e32 v0, 0x2000, v0
	v_lshl_add_u32 v170, v4, 11, v2
	v_lshl_add_u32 v172, v5, 11, v2
	v_ashrrev_i32_e32 v2, 31, v0
	v_lshrrev_b32_e32 v2, 22, v2
	v_add_u32_e32 v2, v0, v2
	v_ashrrev_i32_e32 v2, 10, v2
	v_mul_i32_i24_e32 v3, 0x400, v2
	v_sub_u32_e32 v0, v0, v3
	v_lshrrev_b32_e32 v3, 4, v0
	v_bitop3_b32 v0, v3, v0, 32 bitop3:0x6c
	v_ashrrev_i32_e32 v4, 31, v0
	v_lshrrev_b32_e32 v4, 26, v4
	v_lshlrev_b32_e32 v3, 3, v2
	v_add_u32_e32 v4, v0, v4
	v_and_b32_e32 v3, -16, v3
	v_ashrrev_i32_e32 v5, 6, v4
	v_add_u32_e32 v3, v5, v3
	v_and_b32_e32 v5, 3, v5
	v_and_or_b32 v5, v3, s1, v5
	s_lshl_b32 s1, s23, 10
	s_add_i32 s2, s1, 0
	s_lshl_b32 s1, s23, 8
	s_add_i32 s1, s1, 0
	s_ashr_i32 s13, s12, 31
	s_ashr_i32 s35, s34, 31
	s_ashr_i32 s0, s22, 8
	v_and_b32_e32 v4, 0xc0, v4
	s_add_i32 s7, s1, 0x20400
	s_lshl_b64 s[10:11], s[12:13], 19
	s_lshl_b64 s[16:17], s[34:35], 19
	v_readlane_b32 s18, v255, 43
	v_sub_u32_e32 v0, v0, v4
	v_readlane_b32 s19, v255, 44
	s_add_u32 s64, s18, s16
	v_lshlrev_b32_e32 v2, 5, v2
	v_ashrrev_i16_sdwa v0, v8, sext(v0) dst_sel:DWORD dst_unused:UNUSED_PAD src0_sel:DWORD src1_sel:BYTE_0
	v_lshlrev_b32_e32 v4, 1, v3
	v_lshrrev_b32_e32 v6, 2, v3
	s_addc_u32 s65, s19, s17
	s_lshl_b64 s[16:17], s[12:13], 11
	v_and_b32_e32 v2, 32, v2
	v_bfe_i32 v0, v0, 0, 16
	v_and_b32_e32 v4, 24, v4
	v_and_b32_e32 v6, 4, v6
	s_add_u32 s16, s30, s16
	v_or3_b32 v4, v5, v6, v4
	v_add_lshl_u32 v0, v2, v0, 1
	s_addc_u32 s17, s31, s17
	v_lshlrev_b64 v[132:133], 2, v[130:131]
	v_lshl_add_u32 v174, v3, 11, v0
	v_lshl_add_u32 v176, v4, 11, v0
	v_pk_mov_b32 v[122:123], 0, 0
	v_pk_mov_b32 v[124:125], 0, 0
	v_pk_mov_b32 v[114:115], 0, 0
	v_pk_mov_b32 v[116:117], 0, 0
	v_pk_mov_b32 v[102:103], 0, 0
	v_pk_mov_b32 v[104:105], 0, 0
	v_pk_mov_b32 v[98:99], 0, 0
	v_pk_mov_b32 v[100:101], 0, 0
	v_pk_mov_b32 v[86:87], 0, 0
	v_pk_mov_b32 v[88:89], 0, 0
	v_pk_mov_b32 v[82:83], 0, 0
	v_pk_mov_b32 v[84:85], 0, 0
	v_pk_mov_b32 v[70:71], 0, 0
	v_pk_mov_b32 v[72:73], 0, 0
	v_pk_mov_b32 v[66:67], 0, 0
	v_pk_mov_b32 v[68:69], 0, 0
	v_pk_mov_b32 v[126:127], 0, 0
	v_pk_mov_b32 v[128:129], 0, 0
	v_pk_mov_b32 v[118:119], 0, 0
	v_pk_mov_b32 v[120:121], 0, 0
	v_pk_mov_b32 v[110:111], 0, 0
	v_pk_mov_b32 v[112:113], 0, 0
	v_pk_mov_b32 v[106:107], 0, 0
	v_pk_mov_b32 v[108:109], 0, 0
	v_pk_mov_b32 v[94:95], 0, 0
	v_pk_mov_b32 v[96:97], 0, 0
	v_pk_mov_b32 v[90:91], 0, 0
	v_pk_mov_b32 v[92:93], 0, 0
	v_pk_mov_b32 v[78:79], 0, 0
	v_pk_mov_b32 v[80:81], 0, 0
	v_pk_mov_b32 v[74:75], 0, 0
	v_pk_mov_b32 v[76:77], 0, 0
	v_pk_mov_b32 v[54:55], 0, 0
	v_pk_mov_b32 v[56:57], 0, 0
	v_pk_mov_b32 v[50:51], 0, 0
	v_pk_mov_b32 v[52:53], 0, 0
	v_pk_mov_b32 v[38:39], 0, 0
	v_pk_mov_b32 v[40:41], 0, 0
	v_pk_mov_b32 v[34:35], 0, 0
	v_pk_mov_b32 v[36:37], 0, 0
	v_pk_mov_b32 v[22:23], 0, 0
	v_pk_mov_b32 v[24:25], 0, 0
	v_pk_mov_b32 v[18:19], 0, 0
	v_pk_mov_b32 v[20:21], 0, 0
	v_pk_mov_b32 v[6:7], 0, 0
	v_pk_mov_b32 v[8:9], 0, 0
	v_pk_mov_b32 v[2:3], 0, 0
	v_pk_mov_b32 v[4:5], 0, 0
	v_pk_mov_b32 v[62:63], 0, 0
	v_pk_mov_b32 v[64:65], 0, 0
	v_pk_mov_b32 v[58:59], 0, 0
	v_pk_mov_b32 v[60:61], 0, 0
	v_pk_mov_b32 v[46:47], 0, 0
	v_pk_mov_b32 v[48:49], 0, 0
	v_pk_mov_b32 v[42:43], 0, 0
	v_pk_mov_b32 v[44:45], 0, 0
	v_pk_mov_b32 v[30:31], 0, 0
	v_pk_mov_b32 v[32:33], 0, 0
	v_pk_mov_b32 v[26:27], 0, 0
	v_pk_mov_b32 v[28:29], 0, 0
	v_pk_mov_b32 v[14:15], 0, 0
	v_pk_mov_b32 v[16:17], 0, 0
	v_pk_mov_b32 v[10:11], 0, 0
	v_pk_mov_b32 v[12:13], 0, 0
	v_lshl_add_u64 v[134:135], s[16:17], 0, v[132:133]
	s_mov_b32 s13, m0
	s_mov_b32 m0, s7
	s_nop 0
	global_load_lds_dword v[134:135], off
	s_mov_b32 m0, s13
	s_movk_i32 s13, 0x100
	v_cmp_gt_i32_e32 vcc, s13, v130
	v_readlane_b32 s16, v255, 45
	v_mov_b32_e32 v135, v1
	v_cndmask_b32_e64 v134, v219, 0, vcc
	v_readlane_b32 s17, v255, 46
	s_add_i32 s1, s1, 0x20c00
	s_add_i32 s20, s2, 0x10000
	v_lshl_add_u64 v[134:135], s[16:17], 0, v[134:135]
	s_lshl_b32 s16, s34, 8
	s_ashr_i32 s17, s16, 31
	v_lshl_add_u64 v[136:137], s[16:17], 2, v[134:135]
	v_lshl_add_u64 v[136:137], v[136:137], 0, v[132:133]
	s_mov_b32 s13, m0
	s_mov_b32 m0, s1
	s_nop 0
	global_load_lds_dword v[136:137], off
	s_mov_b32 m0, s13
	v_mov_b32_e32 v173, v1
	s_add_i32 s21, s2, 0x12000
	v_lshl_add_u64 v[136:137], s[64:65], 0, v[172:173]
	s_mov_b32 s1, m0
	s_mov_b32 m0, s20
	s_nop 0
	global_load_lds_dwordx4 v[136:137], off
	s_mov_b32 m0, s1
	v_mov_b32_e32 v177, v1
	s_add_u32 s16, s64, 0x40000
	v_lshl_add_u64 v[136:137], s[64:65], 0, v[176:177]
	s_mov_b32 s1, m0
	s_mov_b32 m0, s21
	s_nop 0
	global_load_lds_dwordx4 v[136:137], off
	s_mov_b32 m0, s1
	s_addc_u32 s17, s65, 0
	s_add_i32 s35, s2, 0x14000
	s_add_i32 s40, s2, 0x16000
	v_lshl_add_u64 v[136:137], s[16:17], 0, v[172:173]
	s_mov_b32 s1, m0
	s_mov_b32 m0, s35
	s_nop 0
	global_load_lds_dwordx4 v[136:137], off
	s_mov_b32 m0, s1
	s_add_u32 s88, s70, s10
	v_lshl_add_u64 v[136:137], s[16:17], 0, v[176:177]
	s_mov_b32 s1, m0
	s_mov_b32 m0, s40
	s_nop 0
	global_load_lds_dwordx4 v[136:137], off
	s_mov_b32 m0, s1
	s_addc_u32 s89, s71, s11
	v_mov_b32_e32 v171, v1
	s_add_i32 s41, s2, 0x2000
	v_lshl_add_u64 v[136:137], s[88:89], 0, v[170:171]
	s_mov_b32 s1, m0
	s_mov_b32 m0, s2
	s_nop 0
	global_load_lds_dwordx4 v[136:137], off
	s_mov_b32 m0, s1
	v_mov_b32_e32 v175, v1
	s_add_u32 s10, s88, 0x40000
	v_lshl_add_u64 v[136:137], s[88:89], 0, v[174:175]
	s_mov_b32 s1, m0
	s_mov_b32 m0, s41
	s_nop 0
	global_load_lds_dwordx4 v[136:137], off
	s_mov_b32 m0, s1
	s_addc_u32 s11, s89, 0
	s_add_i32 s52, s2, 0x4000
	v_lshl_add_u64 v[136:137], s[10:11], 0, v[170:171]
	s_mov_b32 s1, m0
	s_mov_b32 m0, s52
	s_nop 0
	global_load_lds_dwordx4 v[136:137], off
	s_mov_b32 m0, s1
	v_lshl_add_u64 v[136:137], s[10:11], 0, v[174:175]
	s_add_i32 s58, s2, 0x6000
	s_mov_b32 s1, m0
	s_mov_b32 m0, s58
	s_nop 0
	global_load_lds_dwordx4 v[136:137], off
	s_mov_b32 m0, s1
	s_cmp_eq_u32 s0, 1
	v_mov_b32_e32 v215, 1
	s_cselect_b64 s[16:17], -1, 0
	s_cmp_lg_u32 s0, 1
	s_cbranch_scc1 .LBB0_137
	s_setprio 1
	s_barrier

; #define PG8_STAGE(bufoff, gbase, voff) do { _Pragma("unroll") for (int _i = 0; _i < 2; ++_i) \
;         glds16_asm((const char*)(gbase) + (voff)[_i], ldsb + (unsigned)((bufoff) + _i * 8192)); } while (0)
; #define PG8_LDA(dst, b, h) do { _Pragma("unroll") for (int m = 0; m < 4; ++m) _Pragma("unroll") for (int k = 0; k < 2; ++k) dst[m][k] = *(const PG8_LAS bf16x8*)(lds + PG8_SA(b, h) + aoff + m * 2048 + k * 1024); } while (0)
; #define PG8_LDB(dst, b, h) do { _Pragma("unroll") for (int n = 0; n < 2; ++n) _Pragma("unroll") for (int k = 0; k < 2; ++k) dst[n][k] = *(const PG8_LAS bf16x8*)(lds + PG8_SB(b, h) + boff + n * 2048 + k * 1024); } while (0)
; #define PG8_MMA(ai, bj, At, Bt) do { __builtin_amdgcn_s_setprio(1); _Pragma("unroll") for (int m = 0; m < 4; ++m) _Pragma("unroll") for (int n = 0; n < 2; ++n) _Pragma("unroll") for (int k = 0; k < 2; ++k) \
;         acc[ai][bj][m][n] = __builtin_amdgcn_mfma_f32_16x16x32_bf16(Bt[n][k], At[m][k], acc[ai][bj][m][n], 0, 0, 0); __builtin_amdgcn_s_setprio(0); } while (0)
; #define PG8_WAIT_V(n) asm volatile("s_waitcnt vmcnt(" #n ")" ::: "memory")
; #define PG8_BAR __builtin_amdgcn_s_barrier()
; template <class Epi, class Sched, bool ALIGN_EPI = false, bool SP2 = false>
; __device__ __forceinline__ void gemm_phase(PG8_LAS unsigned char* lds, const Gemm g, const Sched& S, const Epi& E, int wave_u) {
;     ...
;             PG8_LDB(B0, 0, 0); PG8_LDB(B1, 0, 1); PG8_SCHED; PG8_LDA(At, 0, 0); PG8_STAGE(PG8_SA(1, 1), a1 + hstep, voffA);
;             PG8_WAIT_V(8); PG8_WAIT_L(0); PG8_BAR; PG8_MMA(0, 0, At, B0); PG8_MMA(0, 1, At, B1); PG8_BAR; PG8_SCHED;
;             PG8_LDA(At, 0, 1); PG8_STAGE(PG8_SB(0, 0), b2, voffB); PG8_STAGE(PG8_SB(0, 1), b2 + hstep, voffB); PG8_STAGE(PG8_SA(0, 0), a2, voffA);
;             PG8_WAIT_V(8); PG8_WAIT_L(0); PG8_BAR; PG8_MMA(1, 0, At, B0); PG8_MMA(1, 1, At, B1); PG8_BAR; PG8_SCHED;
;             PG8_LDB(B0, 1, 0); PG8_LDB(B1, 1, 1); PG8_SCHED; PG8_LDA(At, 1, 0); PG8_STAGE(PG8_SA(0, 1), a2 + hstep, voffA);
;             PG8_WAIT_V(8); PG8_WAIT_L(0); PG8_BAR; PG8_MMA(0, 0, At, B0); PG8_MMA(0, 1, At, B1); PG8_BAR; PG8_SCHED;
;             PG8_LDA(At, 1, 1); PG8_STAGE(PG8_SB(1, 0), b3, voffB); PG8_STAGE(PG8_SB(1, 1), b3 + hstep, voffB); PG8_STAGE(PG8_SA(1, 0), a3, voffA);
;             PG8_WAIT_V(8); PG8_WAIT_L(0); PG8_BAR; PG8_MMA(1, 0, At, B0); PG8_MMA(1, 1, At, B1); PG8_BAR; PG8_SCHED;
.LBB0_143:
	v_add_u32_e32 v0, 0x10000, v203
	s_waitcnt lgkmcnt(0)
	ds_read_b128 v[134:137], v0
	ds_read_b128 v[138:141], v0 offset:1024
	ds_read_b128 v[142:145], v0 offset:2048
	ds_read_b128 v[146:149], v0 offset:3072
	v_add_u32_e32 v0, 0x14000, v203
	s_add_u32 s1, s88, 0xfffc0080
	ds_read_b128 v[150:153], v0
	ds_read_b128 v[154:157], v0 offset:1024
	ds_read_b128 v[158:161], v0 offset:2048
	ds_read_b128 v[162:165], v0 offset:3072
	s_addc_u32 s46, s89, -1
	s_and_b64 s[44:45], s[44:45], exec
	s_cselect_b32 s56, s90, s1
	s_cselect_b32 s57, s53, s46
	s_cselect_b32 s45, s25, s65
	s_cselect_b32 s44, s91, s64
	s_add_u32 s46, s56, 0x80
	s_addc_u32 s47, s57, 0
	s_add_u32 s48, s44, 0x80
	s_addc_u32 s49, s45, 0
	ds_read_b128 v[166:169], v204
	ds_read_b128 v[182:185], v204 offset:1024
	ds_read_b128 v[186:189], v204 offset:2048
	ds_read_b128 v[206:209], v204 offset:3072
	ds_read_b128 v[210:213], v204 offset:4096
	ds_read_b128 v[224:227], v204 offset:5120
	ds_read_b128 v[228:231], v204 offset:6144
	ds_read_b128 v[232:235], v204 offset:7168
	v_lshl_add_u64 v[236:237], s[88:89], 0, v[170:171]
	s_mov_b32 s1, m0
	s_mov_b32 m0, s78
	s_nop 0
	global_load_lds_dwordx4 v[236:237], off
	s_mov_b32 m0, s1
	v_lshl_add_u64 v[236:237], s[88:89], 0, v[174:175]
	s_mov_b32 s1, m0
	s_mov_b32 m0, s79
	s_nop 0
	global_load_lds_dwordx4 v[236:237], off
	s_mov_b32 m0, s1
	s_waitcnt vmcnt(8)
	s_waitcnt lgkmcnt(0)
	s_barrier
	s_waitcnt lgkmcnt(7)
	v_mfma_f32_16x16x32_bf16 v[122:125], v[134:137], v[166:169], v[122:125]
	v_mfma_f32_16x16x32_bf16 v[114:117], v[142:145], v[166:169], v[114:117]
	s_waitcnt lgkmcnt(5)
	v_mfma_f32_16x16x32_bf16 v[102:105], v[134:137], v[186:189], v[102:105]
	v_mfma_f32_16x16x32_bf16 v[98:101], v[142:145], v[186:189], v[98:101]
	s_waitcnt lgkmcnt(3)
	v_mfma_f32_16x16x32_bf16 v[86:89], v[134:137], v[210:213], v[86:89]
	v_mfma_f32_16x16x32_bf16 v[82:85], v[142:145], v[210:213], v[82:85]
	s_waitcnt lgkmcnt(1)
	v_mfma_f32_16x16x32_bf16 v[70:73], v[134:137], v[228:231], v[70:73]
	v_mfma_f32_16x16x32_bf16 v[66:69], v[142:145], v[228:231], v[66:69]
	v_mfma_f32_16x16x32_bf16 v[122:125], v[138:141], v[182:185], v[122:125]
	v_mfma_f32_16x16x32_bf16 v[114:117], v[146:149], v[182:185], v[114:117]
	v_mfma_f32_16x16x32_bf16 v[102:105], v[138:141], v[206:209], v[102:105]
	v_mfma_f32_16x16x32_bf16 v[98:101], v[146:149], v[206:209], v[98:101]
	v_mfma_f32_16x16x32_bf16 v[86:89], v[138:141], v[224:227], v[86:89]
	v_mfma_f32_16x16x32_bf16 v[82:85], v[146:149], v[224:227], v[82:85]
	s_waitcnt lgkmcnt(0)
	v_mfma_f32_16x16x32_bf16 v[70:73], v[138:141], v[232:235], v[70:73]
	v_mfma_f32_16x16x32_bf16 v[66:69], v[146:149], v[232:235], v[66:69]
	v_mfma_f32_16x16x32_bf16 v[126:129], v[150:153], v[166:169], v[126:129]
	v_mfma_f32_16x16x32_bf16 v[118:121], v[158:161], v[166:169], v[118:121]
	v_mfma_f32_16x16x32_bf16 v[110:113], v[150:153], v[186:189], v[110:113]
	v_mfma_f32_16x16x32_bf16 v[106:109], v[158:161], v[186:189], v[106:109]
	v_mfma_f32_16x16x32_bf16 v[94:97], v[150:153], v[210:213], v[94:97]
	v_mfma_f32_16x16x32_bf16 v[90:93], v[158:161], v[210:213], v[90:93]
	v_mfma_f32_16x16x32_bf16 v[78:81], v[150:153], v[228:231], v[78:81]
	v_mfma_f32_16x16x32_bf16 v[74:77], v[158:161], v[228:231], v[74:77]
	v_mfma_f32_16x16x32_bf16 v[126:129], v[154:157], v[182:185], v[126:129]
	v_mfma_f32_16x16x32_bf16 v[118:121], v[162:165], v[182:185], v[118:121]
	v_mfma_f32_16x16x32_bf16 v[110:113], v[154:157], v[206:209], v[110:113]
	v_mfma_f32_16x16x32_bf16 v[106:109], v[162:165], v[206:209], v[106:109]
	v_mfma_f32_16x16x32_bf16 v[94:97], v[154:157], v[224:227], v[94:97]
	v_mfma_f32_16x16x32_bf16 v[90:93], v[162:165], v[224:227], v[90:93]
	v_mfma_f32_16x16x32_bf16 v[78:81], v[154:157], v[232:235], v[78:81]
	v_mfma_f32_16x16x32_bf16 v[74:77], v[162:165], v[232:235], v[74:77]
	s_barrier
	ds_read_b128 v[166:169], v204 offset:16384
	ds_read_b128 v[182:185], v204 offset:17408
	ds_read_b128 v[186:189], v204 offset:18432
	ds_read_b128 v[206:209], v204 offset:19456
	ds_read_b128 v[210:213], v204 offset:20480
	ds_read_b128 v[224:227], v204 offset:21504
	ds_read_b128 v[228:231], v204 offset:22528
	ds_read_b128 v[232:235], v204 offset:23552
	v_lshl_add_u64 v[236:237], s[44:45], 0, v[172:173]
	s_mov_b32 s1, m0
	s_mov_b32 m0, s20
	s_nop 0
	global_load_lds_dwordx4 v[236:237], off
	s_mov_b32 m0, s1
	s_add_u32 vcc_lo, s44, 0x40000
	v_lshl_add_u64 v[236:237], s[44:45], 0, v[176:177]
	s_mov_b32 s1, m0
	s_mov_b32 m0, s21
	s_nop 0
	global_load_lds_dwordx4 v[236:237], off
	s_mov_b32 m0, s1
	s_addc_u32 vcc_hi, s45, 0
	v_lshl_add_u64 v[236:237], vcc, 0, v[172:173]
	s_mov_b32 s1, m0
	s_mov_b32 m0, s35
	s_nop 0
	global_load_lds_dwordx4 v[236:237], off
	s_mov_b32 m0, s1
	v_lshl_add_u64 v[236:237], vcc, 0, v[176:177]
	s_mov_b32 s1, m0
	s_mov_b32 m0, s40
	s_nop 0
	global_load_lds_dwordx4 v[236:237], off
	s_mov_b32 m0, s1
	v_lshl_add_u64 v[236:237], s[56:57], 0, v[170:171]
	s_mov_b32 s1, m0
	s_mov_b32 m0, s2
	s_nop 0
	global_load_lds_dwordx4 v[236:237], off
	s_mov_b32 m0, s1
	v_lshl_add_u64 v[236:237], s[56:57], 0, v[174:175]
	s_mov_b32 s1, m0
	s_mov_b32 m0, s41
	s_nop 0
	global_load_lds_dwordx4 v[236:237], off
	s_mov_b32 m0, s1
	s_waitcnt vmcnt(8)
	s_waitcnt lgkmcnt(0)
	s_barrier
; #define PG8_STAGE(bufoff, gbase, voff) do { _Pragma("unroll") for (int _i = 0; _i < 2; ++_i) \
;         glds16_asm((const char*)(gbase) + (voff)[_i], ldsb + (unsigned)((bufoff) + _i * 8192)); } while (0)
; #define PG8_LDA(dst, b, h) do { _Pragma("unroll") for (int m = 0; m < 4; ++m) _Pragma("unroll") for (int k = 0; k < 2; ++k) dst[m][k] = *(const PG8_LAS bf16x8*)(lds + PG8_SA(b, h) + aoff + m * 2048 + k * 1024); } while (0)
; #define PG8_LDB(dst, b, h) do { _Pragma("unroll") for (int n = 0; n < 2; ++n) _Pragma("unroll") for (int k = 0; k < 2; ++k) dst[n][k] = *(const PG8_LAS bf16x8*)(lds + PG8_SB(b, h) + boff + n * 2048 + k * 1024); } while (0)
; #define PG8_MMA(ai, bj, At, Bt) do { __builtin_amdgcn_s_setprio(1); _Pragma("unroll") for (int m = 0; m < 4; ++m) _Pragma("unroll") for (int n = 0; n < 2; ++n) _Pragma("unroll") for (int k = 0; k < 2; ++k) \
;         acc[ai][bj][m][n] = __builtin_amdgcn_mfma_f32_16x16x32_bf16(Bt[n][k], At[m][k], acc[ai][bj][m][n], 0, 0, 0); __builtin_amdgcn_s_setprio(0); } while (0)
; #define PG8_WAIT_V(n) asm volatile("s_waitcnt vmcnt(" #n ")" ::: "memory")
; #define PG8_BAR __builtin_amdgcn_s_barrier()
; template <class Epi, class Sched, bool ALIGN_EPI = false, bool SP2 = false>
; __device__ __forceinline__ void gemm_phase(PG8_LAS unsigned char* lds, const Gemm g, const Sched& S, const Epi& E, int wave_u) {
;     ...
;             PG8_LDB(B0, 0, 0); PG8_LDB(B1, 0, 1); PG8_SCHED; PG8_LDA(At, 0, 0); PG8_STAGE(PG8_SA(1, 1), a1 + hstep, voffA);
;             PG8_WAIT_V(8); PG8_WAIT_L(0); PG8_BAR; PG8_MMA(0, 0, At, B0); PG8_MMA(0, 1, At, B1); PG8_BAR; PG8_SCHED;
;             PG8_LDA(At, 0, 1); PG8_STAGE(PG8_SB(0, 0), b2, voffB); PG8_STAGE(PG8_SB(0, 1), b2 + hstep, voffB); PG8_STAGE(PG8_SA(0, 0), a2, voffA);
;             PG8_WAIT_V(8); PG8_WAIT_L(0); PG8_BAR; PG8_MMA(1, 0, At, B0); PG8_MMA(1, 1, At, B1); PG8_BAR; PG8_SCHED;
;             PG8_LDB(B0, 1, 0); PG8_LDB(B1, 1, 1); PG8_SCHED; PG8_LDA(At, 1, 0); PG8_STAGE(PG8_SA(0, 1), a2 + hstep, voffA);
;             PG8_WAIT_V(8); PG8_WAIT_L(0); PG8_BAR; PG8_MMA(0, 0, At, B0); PG8_MMA(0, 1, At, B1); PG8_BAR; PG8_SCHED;
;             PG8_LDA(At, 1, 1); PG8_STAGE(PG8_SB(1, 0), b3, voffB); PG8_STAGE(PG8_SB(1, 1), b3 + hstep, voffB); PG8_STAGE(PG8_SA(1, 0), a3, voffA);
;             PG8_WAIT_V(8); PG8_WAIT_L(0); PG8_BAR; PG8_MMA(1, 0, At, B0); PG8_MMA(1, 1, At, B1); PG8_BAR; PG8_SCHED;
	s_waitcnt lgkmcnt(7)
	v_mfma_f32_16x16x32_bf16 v[54:57], v[134:137], v[166:169], v[54:57]
	v_mfma_f32_16x16x32_bf16 v[50:53], v[142:145], v[166:169], v[50:53]
	s_waitcnt lgkmcnt(5)
	v_mfma_f32_16x16x32_bf16 v[38:41], v[134:137], v[186:189], v[38:41]
	v_mfma_f32_16x16x32_bf16 v[34:37], v[142:145], v[186:189], v[34:37]
	s_waitcnt lgkmcnt(3)
	v_mfma_f32_16x16x32_bf16 v[22:25], v[134:137], v[210:213], v[22:25]
	v_mfma_f32_16x16x32_bf16 v[18:21], v[142:145], v[210:213], v[18:21]
	s_waitcnt lgkmcnt(1)
	v_mfma_f32_16x16x32_bf16 v[6:9], v[134:137], v[228:231], v[6:9]
	v_mfma_f32_16x16x32_bf16 v[2:5], v[142:145], v[228:231], v[2:5]
	v_mfma_f32_16x16x32_bf16 v[54:57], v[138:141], v[182:185], v[54:57]
	v_mfma_f32_16x16x32_bf16 v[50:53], v[146:149], v[182:185], v[50:53]
	v_mfma_f32_16x16x32_bf16 v[38:41], v[138:141], v[206:209], v[38:41]
	v_mfma_f32_16x16x32_bf16 v[34:37], v[146:149], v[206:209], v[34:37]
	v_mfma_f32_16x16x32_bf16 v[22:25], v[138:141], v[224:227], v[22:25]
	v_mfma_f32_16x16x32_bf16 v[18:21], v[146:149], v[224:227], v[18:21]
	s_waitcnt lgkmcnt(0)
	v_mfma_f32_16x16x32_bf16 v[6:9], v[138:141], v[232:235], v[6:9]
	v_mfma_f32_16x16x32_bf16 v[2:5], v[146:149], v[232:235], v[2:5]
	v_mfma_f32_16x16x32_bf16 v[62:65], v[150:153], v[166:169], v[62:65]
	v_mfma_f32_16x16x32_bf16 v[58:61], v[158:161], v[166:169], v[58:61]
	v_mfma_f32_16x16x32_bf16 v[46:49], v[150:153], v[186:189], v[46:49]
	v_mfma_f32_16x16x32_bf16 v[42:45], v[158:161], v[186:189], v[42:45]
	v_mfma_f32_16x16x32_bf16 v[30:33], v[150:153], v[210:213], v[30:33]
	v_mfma_f32_16x16x32_bf16 v[26:29], v[158:161], v[210:213], v[26:29]
	v_mfma_f32_16x16x32_bf16 v[14:17], v[150:153], v[228:231], v[14:17]
	v_mfma_f32_16x16x32_bf16 v[10:13], v[158:161], v[228:231], v[10:13]
	v_mfma_f32_16x16x32_bf16 v[62:65], v[154:157], v[182:185], v[62:65]
	v_mfma_f32_16x16x32_bf16 v[58:61], v[162:165], v[182:185], v[58:61]
	v_mfma_f32_16x16x32_bf16 v[46:49], v[154:157], v[206:209], v[46:49]
	v_mfma_f32_16x16x32_bf16 v[42:45], v[162:165], v[206:209], v[42:45]
	v_mfma_f32_16x16x32_bf16 v[30:33], v[154:157], v[224:227], v[30:33]
	v_mfma_f32_16x16x32_bf16 v[26:29], v[162:165], v[224:227], v[26:29]
	v_mfma_f32_16x16x32_bf16 v[14:17], v[154:157], v[232:235], v[14:17]
	v_mfma_f32_16x16x32_bf16 v[10:13], v[162:165], v[232:235], v[10:13]
	s_barrier
	v_add_u32_e32 v0, 0x18000, v203
	ds_read_b128 v[134:137], v0
	ds_read_b128 v[138:141], v0 offset:1024
	ds_read_b128 v[142:145], v0 offset:2048
	ds_read_b128 v[146:149], v0 offset:3072
	v_add_u32_e32 v0, 0x1c000, v203
	ds_read_b128 v[150:153], v0
	ds_read_b128 v[154:157], v0 offset:1024
	ds_read_b128 v[158:161], v0 offset:2048
	ds_read_b128 v[162:165], v0 offset:3072
	ds_read_b128 v[166:169], v204 offset:32768
	ds_read_b128 v[182:185], v204 offset:33792
	ds_read_b128 v[186:189], v204 offset:34816
	ds_read_b128 v[206:209], v204 offset:35840
	ds_read_b128 v[210:213], v204 offset:36864
	ds_read_b128 v[224:227], v204 offset:37888
	ds_read_b128 v[228:231], v204 offset:38912
	ds_read_b128 v[232:235], v204 offset:39936
	s_add_u32 s56, s56, 0x40000
	s_addc_u32 s57, s57, 0
	v_lshl_add_u64 v[236:237], s[56:57], 0, v[170:171]
	s_mov_b32 s1, m0
	s_mov_b32 m0, s52
	s_nop 0
	global_load_lds_dwordx4 v[236:237], off
	s_mov_b32 m0, s1
	v_lshl_add_u64 v[236:237], s[56:57], 0, v[174:175]
	s_mov_b32 s1, m0
	s_mov_b32 m0, s58
	s_nop 0
	global_load_lds_dwordx4 v[236:237], off
	s_mov_b32 m0, s1
	s_waitcnt vmcnt(8)
	s_waitcnt lgkmcnt(0)
	s_barrier
	s_waitcnt lgkmcnt(7)
	v_mfma_f32_16x16x32_bf16 v[122:125], v[134:137], v[166:169], v[122:125]
	v_mfma_f32_16x16x32_bf16 v[114:117], v[142:145], v[166:169], v[114:117]
	s_waitcnt lgkmcnt(5)
	v_mfma_f32_16x16x32_bf16 v[102:105], v[134:137], v[186:189], v[102:105]
	v_mfma_f32_16x16x32_bf16 v[98:101], v[142:145], v[186:189], v[98:101]
	s_waitcnt lgkmcnt(3)
	v_mfma_f32_16x16x32_bf16 v[86:89], v[134:137], v[210:213], v[86:89]
	v_mfma_f32_16x16x32_bf16 v[82:85], v[142:145], v[210:213], v[82:85]
	s_waitcnt lgkmcnt(1)
	v_mfma_f32_16x16x32_bf16 v[70:73], v[134:137], v[228:231], v[70:73]
	v_mfma_f32_16x16x32_bf16 v[66:69], v[142:145], v[228:231], v[66:69]
	v_mfma_f32_16x16x32_bf16 v[122:125], v[138:141], v[182:185], v[122:125]
	v_mfma_f32_16x16x32_bf16 v[114:117], v[146:149], v[182:185], v[114:117]
	v_mfma_f32_16x16x32_bf16 v[102:105], v[138:141], v[206:209], v[102:105]
	v_mfma_f32_16x16x32_bf16 v[98:101], v[146:149], v[206:209], v[98:101]
	v_mfma_f32_16x16x32_bf16 v[86:89], v[138:141], v[224:227], v[86:89]
	v_mfma_f32_16x16x32_bf16 v[82:85], v[146:149], v[224:227], v[82:85]
	s_waitcnt lgkmcnt(0)
	v_mfma_f32_16x16x32_bf16 v[70:73], v[138:141], v[232:235], v[70:73]
	v_mfma_f32_16x16x32_bf16 v[66:69], v[146:149], v[232:235], v[66:69]
	v_mfma_f32_16x16x32_bf16 v[126:129], v[150:153], v[166:169], v[126:129]
	v_mfma_f32_16x16x32_bf16 v[118:121], v[158:161], v[166:169], v[118:121]
	v_mfma_f32_16x16x32_bf16 v[110:113], v[150:153], v[186:189], v[110:113]
	v_mfma_f32_16x16x32_bf16 v[106:109], v[158:161], v[186:189], v[106:109]
	v_mfma_f32_16x16x32_bf16 v[94:97], v[150:153], v[210:213], v[94:97]
	v_mfma_f32_16x16x32_bf16 v[90:93], v[158:161], v[210:213], v[90:93]
	v_mfma_f32_16x16x32_bf16 v[78:81], v[150:153], v[228:231], v[78:81]
	v_mfma_f32_16x16x32_bf16 v[74:77], v[158:161], v[228:231], v[74:77]
	v_mfma_f32_16x16x32_bf16 v[126:129], v[154:157], v[182:185], v[126:129]
	v_mfma_f32_16x16x32_bf16 v[118:121], v[162:165], v[182:185], v[118:121]
	v_mfma_f32_16x16x32_bf16 v[110:113], v[154:157], v[206:209], v[110:113]
	v_mfma_f32_16x16x32_bf16 v[106:109], v[162:165], v[206:209], v[106:109]
	v_mfma_f32_16x16x32_bf16 v[94:97], v[154:157], v[224:227], v[94:97]
	v_mfma_f32_16x16x32_bf16 v[90:93], v[162:165], v[224:227], v[90:93]
	v_mfma_f32_16x16x32_bf16 v[78:81], v[154:157], v[232:235], v[78:81]
	v_mfma_f32_16x16x32_bf16 v[74:77], v[162:165], v[232:235], v[74:77]
	s_barrier
; #define PG8_STAGE(bufoff, gbase, voff) do { _Pragma("unroll") for (int _i = 0; _i < 2; ++_i) \
;         glds16_asm((const char*)(gbase) + (voff)[_i], ldsb + (unsigned)((bufoff) + _i * 8192)); } while (0)
; #define PG8_LDA(dst, b, h) do { _Pragma("unroll") for (int m = 0; m < 4; ++m) _Pragma("unroll") for (int k = 0; k < 2; ++k) dst[m][k] = *(const PG8_LAS bf16x8*)(lds + PG8_SA(b, h) + aoff + m * 2048 + k * 1024); } while (0)
; #define PG8_LDB(dst, b, h) do { _Pragma("unroll") for (int n = 0; n < 2; ++n) _Pragma("unroll") for (int k = 0; k < 2; ++k) dst[n][k] = *(const PG8_LAS bf16x8*)(lds + PG8_SB(b, h) + boff + n * 2048 + k * 1024); } while (0)
; #define PG8_MMA(ai, bj, At, Bt) do { __builtin_amdgcn_s_setprio(1); _Pragma("unroll") for (int m = 0; m < 4; ++m) _Pragma("unroll") for (int n = 0; n < 2; ++n) _Pragma("unroll") for (int k = 0; k < 2; ++k) \
;         acc[ai][bj][m][n] = __builtin_amdgcn_mfma_f32_16x16x32_bf16(Bt[n][k], At[m][k], acc[ai][bj][m][n], 0, 0, 0); __builtin_amdgcn_s_setprio(0); } while (0)
; #define PG8_WAIT_V(n) asm volatile("s_waitcnt vmcnt(" #n ")" ::: "memory")
; #define PG8_BAR __builtin_amdgcn_s_barrier()
; template <class Epi, class Sched, bool ALIGN_EPI = false, bool SP2 = false>
; __device__ __forceinline__ void gemm_phase(PG8_LAS unsigned char* lds, const Gemm g, const Sched& S, const Epi& E, int wave_u) {
;     ...
;             PG8_LDB(B0, 0, 0); PG8_LDB(B1, 0, 1); PG8_SCHED; PG8_LDA(At, 0, 0); PG8_STAGE(PG8_SA(1, 1), a1 + hstep, voffA);
;             PG8_WAIT_V(8); PG8_WAIT_L(0); PG8_BAR; PG8_MMA(0, 0, At, B0); PG8_MMA(0, 1, At, B1); PG8_BAR; PG8_SCHED;
;             PG8_LDA(At, 0, 1); PG8_STAGE(PG8_SB(0, 0), b2, voffB); PG8_STAGE(PG8_SB(0, 1), b2 + hstep, voffB); PG8_STAGE(PG8_SA(0, 0), a2, voffA);
;             PG8_WAIT_V(8); PG8_WAIT_L(0); PG8_BAR; PG8_MMA(1, 0, At, B0); PG8_MMA(1, 1, At, B1); PG8_BAR; PG8_SCHED;
;             PG8_LDB(B0, 1, 0); PG8_LDB(B1, 1, 1); PG8_SCHED; PG8_LDA(At, 1, 0); PG8_STAGE(PG8_SA(0, 1), a2 + hstep, voffA);
;             PG8_WAIT_V(8); PG8_WAIT_L(0); PG8_BAR; PG8_MMA(0, 0, At, B0); PG8_MMA(0, 1, At, B1); PG8_BAR; PG8_SCHED;
;             PG8_LDA(At, 1, 1); PG8_STAGE(PG8_SB(1, 0), b3, voffB); PG8_STAGE(PG8_SB(1, 1), b3 + hstep, voffB); PG8_STAGE(PG8_SA(1, 0), a3, voffA);
;             PG8_WAIT_V(8); PG8_WAIT_L(0); PG8_BAR; PG8_MMA(1, 0, At, B0); PG8_MMA(1, 1, At, B1); PG8_BAR; PG8_SCHED;
	ds_read_b128 v[166:169], v204 offset:49152
	ds_read_b128 v[182:185], v204 offset:50176
	ds_read_b128 v[186:189], v204 offset:51200
	ds_read_b128 v[206:209], v204 offset:52224
	ds_read_b128 v[210:213], v204 offset:53248
	ds_read_b128 v[224:227], v204 offset:54272
	ds_read_b128 v[228:231], v204 offset:55296
	ds_read_b128 v[232:235], v204 offset:56320
	v_lshl_add_u64 v[236:237], s[48:49], 0, v[172:173]
	s_mov_b32 s1, m0
	s_mov_b32 m0, s60
	s_nop 0
	global_load_lds_dwordx4 v[236:237], off
	s_mov_b32 m0, s1
	s_add_u32 s44, s44, 0x40080
	v_lshl_add_u64 v[236:237], s[48:49], 0, v[176:177]
	s_mov_b32 s1, m0
	s_mov_b32 m0, s61
	s_nop 0
	global_load_lds_dwordx4 v[236:237], off
	s_mov_b32 m0, s1
	s_addc_u32 s45, s45, 0
	v_lshl_add_u64 v[236:237], s[44:45], 0, v[172:173]
	s_mov_b32 s1, m0
	s_mov_b32 m0, s67
	s_nop 0
	global_load_lds_dwordx4 v[236:237], off
	s_mov_b32 m0, s1
	v_lshl_add_u64 v[236:237], s[44:45], 0, v[176:177]
	s_mov_b32 s1, m0
	s_mov_b32 m0, s75
	s_nop 0
	global_load_lds_dwordx4 v[236:237], off
	s_mov_b32 m0, s1
	v_lshl_add_u64 v[236:237], s[46:47], 0, v[170:171]
	s_mov_b32 s1, m0
	s_mov_b32 m0, s63
	s_nop 0
	global_load_lds_dwordx4 v[236:237], off
	s_mov_b32 m0, s1
	v_lshl_add_u64 v[236:237], s[46:47], 0, v[174:175]
	s_mov_b32 s1, m0
	s_mov_b32 m0, s66
	s_nop 0
	global_load_lds_dwordx4 v[236:237], off
	s_mov_b32 m0, s1
	s_waitcnt vmcnt(8)
	s_waitcnt lgkmcnt(0)
	s_barrier
	s_waitcnt lgkmcnt(7)
	v_mfma_f32_16x16x32_bf16 v[54:57], v[134:137], v[166:169], v[54:57]
	v_mfma_f32_16x16x32_bf16 v[50:53], v[142:145], v[166:169], v[50:53]
	s_waitcnt lgkmcnt(5)
	v_mfma_f32_16x16x32_bf16 v[38:41], v[134:137], v[186:189], v[38:41]
	v_mfma_f32_16x16x32_bf16 v[34:37], v[142:145], v[186:189], v[34:37]
	s_waitcnt lgkmcnt(3)
	v_mfma_f32_16x16x32_bf16 v[22:25], v[134:137], v[210:213], v[22:25]
	v_mfma_f32_16x16x32_bf16 v[18:21], v[142:145], v[210:213], v[18:21]
	s_waitcnt lgkmcnt(1)
	v_mfma_f32_16x16x32_bf16 v[6:9], v[134:137], v[228:231], v[6:9]
	v_mfma_f32_16x16x32_bf16 v[2:5], v[142:145], v[228:231], v[2:5]
	v_mfma_f32_16x16x32_bf16 v[54:57], v[138:141], v[182:185], v[54:57]
	v_mfma_f32_16x16x32_bf16 v[50:53], v[146:149], v[182:185], v[50:53]
	v_mfma_f32_16x16x32_bf16 v[38:41], v[138:141], v[206:209], v[38:41]
	v_mfma_f32_16x16x32_bf16 v[34:37], v[146:149], v[206:209], v[34:37]
	v_mfma_f32_16x16x32_bf16 v[22:25], v[138:141], v[224:227], v[22:25]
	v_mfma_f32_16x16x32_bf16 v[18:21], v[146:149], v[224:227], v[18:21]
	s_waitcnt lgkmcnt(0)
	v_mfma_f32_16x16x32_bf16 v[6:9], v[138:141], v[232:235], v[6:9]
	v_mfma_f32_16x16x32_bf16 v[2:5], v[146:149], v[232:235], v[2:5]
	v_mfma_f32_16x16x32_bf16 v[62:65], v[150:153], v[166:169], v[62:65]
	v_mfma_f32_16x16x32_bf16 v[58:61], v[158:161], v[166:169], v[58:61]
	v_mfma_f32_16x16x32_bf16 v[46:49], v[150:153], v[186:189], v[46:49]
	v_mfma_f32_16x16x32_bf16 v[42:45], v[158:161], v[186:189], v[42:45]
	v_mfma_f32_16x16x32_bf16 v[30:33], v[150:153], v[210:213], v[30:33]
	v_mfma_f32_16x16x32_bf16 v[26:29], v[158:161], v[210:213], v[26:29]
	v_mfma_f32_16x16x32_bf16 v[14:17], v[150:153], v[228:231], v[14:17]
	v_mfma_f32_16x16x32_bf16 v[10:13], v[158:161], v[228:231], v[10:13]
	v_mfma_f32_16x16x32_bf16 v[62:65], v[154:157], v[182:185], v[62:65]
	v_mfma_f32_16x16x32_bf16 v[58:61], v[162:165], v[182:185], v[58:61]
	v_mfma_f32_16x16x32_bf16 v[46:49], v[154:157], v[206:209], v[46:49]
	v_mfma_f32_16x16x32_bf16 v[42:45], v[162:165], v[206:209], v[42:45]
	v_mfma_f32_16x16x32_bf16 v[30:33], v[154:157], v[224:227], v[30:33]
	v_mfma_f32_16x16x32_bf16 v[26:29], v[162:165], v[224:227], v[26:29]
	v_mfma_f32_16x16x32_bf16 v[14:17], v[154:157], v[232:235], v[14:17]
	v_mfma_f32_16x16x32_bf16 v[10:13], v[162:165], v[232:235], v[10:13]
	s_barrier
	s_add_i32 s84, s84, 2
	s_add_u32 s88, s88, 0x100
	s_addc_u32 s89, s89, 0
	s_add_u32 s64, s64, 0x100
	s_addc_u32 s65, s65, 0
	s_cmp_gt_u32 s84, 13
	s_cbranch_scc1 .LBB0_146

; #define PG8_WAIT_V(n) asm volatile("s_waitcnt vmcnt(" #n ")" ::: "memory")
; #define PG8_BAR __builtin_amdgcn_s_barrier()
; template <class Epi, class Sched, bool ALIGN_EPI = false, bool SP2 = false>
; __device__ __forceinline__ void gemm_phase(PG8_LAS unsigned char* lds, const Gemm g, const Sched& S, const Epi& E, int wave_u) {
;     ...
;     PG8_WAIT_V(0);
;     if constexpr (!ALIGN_EPI) { if (wr == 0) PG8_BAR; }
;     PG8_BAR;
.LBB0_187:
	v_readlane_b32 s78, v255, 13
	s_setprio 0
	s_waitcnt vmcnt(0)
	v_readlane_b32 s79, v255, 14
	s_mov_b32 s92, s78
	v_readlane_b32 s64, v255, 16
	v_readlane_b32 s76, v255, 18
	v_readlane_b32 s78, v255, 20
	v_readlane_b32 s80, v255, 22
	v_readlane_b32 s82, v255, 24
	v_readlane_b32 s86, v255, 26
	v_readlane_b32 s88, v255, 28
	v_readlane_b32 s52, v251, 39
	v_readlane_b32 s30, v255, 60
	v_readlane_b32 s75, v255, 15
	v_readlane_b32 s65, v255, 17
	v_readlane_b32 s77, v255, 19
	v_readlane_b32 s79, v255, 21
	v_readlane_b32 s81, v255, 23
	v_readlane_b32 s83, v255, 25
	v_readlane_b32 s87, v255, 27
	v_readlane_b32 s89, v255, 29
	v_readlane_b32 s53, v251, 40
	v_readlane_b32 s31, v255, 61
	s_barrier

; template <class Epi, class Sched, bool ALIGN_EPI = false, bool SP2 = false>
; __device__ __forceinline__ void gemm_phase(PG8_LAS unsigned char* lds, const Gemm g, const Sched& S, const Epi& E, int wave_u) {
;     ...
;     const int tid = tid_, wid = __builtin_amdgcn_readfirstlane(tid >> 6), lane = tid & 63, wr = wid >> 2, wc = wid & 3, fr = lane & 15, fq = lane >> 4;
;     const int K = g.K, nt = K / BK;
;     unsigned voffA[2], voffB[2];
; #pragma unroll
;     for (int i = 0; i < 2; ++i) { int R, C; stage_rc(tid * 16 + i * 8192, R, C); const int Rb = Epi::PERM ? ((R & ~31) + perm32(R & 31)) : R;
;         voffA[i] = (unsigned)(R * K + C) * 2u; voffB[i] = (unsigned)(Rb * K + C) * 2u; }
;     const size_t kstep = (size_t)(BK * 2);
;     const size_t hstep = (size_t)HALF * K * 2;
;     const size_t tstep = 2 * hstep;
;     const unsigned ldsw = (unsigned)wid * 1024u;
;     const unsigned ldsb = (unsigned)__builtin_amdgcn_readfirstlane((int)((unsigned)(size_t)lds + ldsw));
;     const int aoff = lds_byte(wr * 64 + fr, fq * 8), boff = lds_byte(wc * 32 + fr, fq * 8);
.LBB0_255:
	v_readlane_b32 s0, v255, 41
	v_readlane_b32 s1, v255, 42
	s_lshl_b32 s2, s0, 9
	s_mov_b32 s16, s0
	s_lshl_b64 s[0:1], s[2:3], 2
	v_readlane_b32 s2, v250, 25
	s_add_u32 s18, s2, s0
	v_readlane_b32 s0, v250, 26
	s_addc_u32 s19, s0, s1
	s_mul_i32 s1, s16, 0x780000
	v_readlane_b32 s2, v250, 17
	v_writelane_b32 v255, s18, 51
	s_mul_hi_u32 s0, s16, 0x780000
	s_add_u32 s16, s2, s1
	v_readlane_b32 s1, v250, 18
	v_writelane_b32 v255, s19, 52
	s_addc_u32 s17, s1, s0
	v_writelane_b32 v255, s16, 53
	s_andn2_b64 vcc, exec, s[10:11]
	s_nop 0
	v_writelane_b32 v255, s17, 54
	s_cbranch_vccnz .LBB0_338
	s_waitcnt vmcnt(0)
	v_bfe_i32 v3, v126, 27, 1
	v_lshlrev_b32_e32 v0, 4, v126
	v_lshrrev_b32_e32 v3, 22, v3
	v_add_u32_e32 v3, v0, v3
	v_and_b32_e32 v3, 0xfffffc00, v3
	v_sub_u32_e32 v3, v0, v3
	v_ashrrev_i32_e32 v127, 31, v126
	v_lshrrev_b32_e32 v4, 4, v3
	v_lshrrev_b32_e32 v2, 26, v127
	v_bitop3_b32 v3, v4, v3, 32 bitop3:0x6c
	v_add_u32_e32 v2, v126, v2
	v_ashrrev_i32_e32 v5, 31, v3
	v_ashrrev_i32_e32 v2, 6, v2
	v_lshrrev_b32_e32 v5, 26, v5
	v_lshlrev_b32_e32 v4, 3, v2
	v_add_u32_e32 v5, v3, v5
	v_and_b32_e32 v4, -16, v4
	v_ashrrev_i32_e32 v6, 6, v5
	v_and_b32_e32 v5, 0xc0, v5
	v_add_u32_e32 v4, v6, v4
	v_sub_u32_e32 v3, v3, v5
	v_mov_b32_e32 v8, 1
	v_lshlrev_b32_e32 v2, 5, v2
	v_ashrrev_i16_sdwa v3, v8, sext(v3) dst_sel:DWORD dst_unused:UNUSED_PAD src0_sel:DWORD src1_sel:BYTE_0
	v_lshlrev_b32_e32 v5, 1, v4
	v_lshrrev_b32_e32 v7, 2, v4
	v_and_b32_e32 v6, 3, v6
	s_mov_b32 s0, 0x1fffe0
	v_and_b32_e32 v2, 32, v2
	v_bfe_i32 v3, v3, 0, 16
	v_and_b32_e32 v5, 24, v5
	v_and_b32_e32 v7, 4, v7
	v_and_or_b32 v6, v4, s0, v6
	v_or3_b32 v5, v6, v7, v5
	v_add_lshl_u32 v2, v2, v3, 1
	v_add_u32_e32 v0, 0x2000, v0
	v_lshl_add_u32 v178, v4, 11, v2
	v_lshl_add_u32 v180, v5, 11, v2
	v_ashrrev_i32_e32 v2, 31, v0
	v_lshrrev_b32_e32 v2, 22, v2
	v_add_u32_e32 v2, v0, v2
	v_ashrrev_i32_e32 v2, 10, v2
	v_mul_i32_i24_e32 v3, 0x400, v2
	v_sub_u32_e32 v0, v0, v3
	v_lshrrev_b32_e32 v3, 4, v0
	v_bitop3_b32 v0, v3, v0, 32 bitop3:0x6c
	v_ashrrev_i32_e32 v4, 31, v0
	v_lshrrev_b32_e32 v4, 26, v4
	v_lshlrev_b32_e32 v3, 3, v2
	v_add_u32_e32 v4, v0, v4
	v_and_b32_e32 v3, -16, v3
	v_ashrrev_i32_e32 v5, 6, v4
	v_add_u32_e32 v3, v5, v3
	v_and_b32_e32 v5, 3, v5
	v_and_or_b32 v5, v3, s0, v5
	s_lshl_b32 s0, s14, 10
	s_add_i32 s2, s0, 0
	s_lshl_b32 s0, s14, 8
	s_add_i32 s11, s0, 0
	s_ashr_i32 s13, s12, 31
	s_ashr_i32 s29, s28, 31
	s_ashr_i32 s10, s7, 8
	v_and_b32_e32 v4, 0xc0, v4
	s_add_i32 s84, s11, 0x20400
	s_lshl_b64 s[0:1], s[12:13], 19
	s_lshl_b64 s[16:17], s[28:29], 19
	v_readlane_b32 s18, v255, 43
	v_sub_u32_e32 v0, v0, v4
	v_readlane_b32 s19, v255, 44
	s_add_u32 s64, s18, s16
	v_lshlrev_b32_e32 v2, 5, v2
	v_ashrrev_i16_sdwa v0, v8, sext(v0) dst_sel:DWORD dst_unused:UNUSED_PAD src0_sel:DWORD src1_sel:BYTE_0
	v_lshlrev_b32_e32 v4, 1, v3
	v_lshrrev_b32_e32 v6, 2, v3
	s_addc_u32 s65, s19, s17
	s_lshl_b64 s[16:17], s[12:13], 11
	v_and_b32_e32 v2, 32, v2
	v_bfe_i32 v0, v0, 0, 16
	v_and_b32_e32 v4, 24, v4
	v_and_b32_e32 v6, 4, v6
	s_add_u32 s16, s30, s16
	v_or3_b32 v4, v5, v6, v4
	v_add_lshl_u32 v0, v2, v0, 1
	s_addc_u32 s17, s31, s17
	v_lshlrev_b64 v[128:129], 2, v[126:127]
	v_lshl_add_u32 v182, v3, 11, v0
	v_lshl_add_u32 v184, v4, 11, v0
	s_waitcnt lgkmcnt(0)
; __device__ __forceinline__ f32x4 zero4_pk() { f32x2_z a, b; asm volatile("v_pk_mov_b32 %0, 0, 0" : "=v"(a)); asm volatile("v_pk_mov_b32 %0, 0, 0" : "=v"(b)); return (f32x4){a.x, a.y, b.x, b.y}; }
; #define PG8_STAGE(bufoff, gbase, voff) do { _Pragma("unroll") for (int _i = 0; _i < 2; ++_i) \
;         glds16_asm((const char*)(gbase) + (voff)[_i], ldsb + (unsigned)((bufoff) + _i * 8192)); } while (0)
; #define PG8_WAIT_V(n) asm volatile("s_waitcnt vmcnt(" #n ")" ::: "memory")
; #define PG8_BAR __builtin_amdgcn_s_barrier()
; template <class Epi, class Sched, bool ALIGN_EPI = false, bool SP2 = false>
; __device__ __forceinline__ void gemm_phase(PG8_LAS unsigned char* lds, const Gemm g, const Sched& S, const Epi& E, int wave_u) {
;     ...
;     f32x4 acc[2][2][4][2];
; #pragma unroll
;     for (int a = 0; a < 2; ++a)
; #pragma unroll
;         for (int b = 0; b < 2; ++b)
; #pragma unroll
;             for (int m = 0; m < 4; ++m)
; #pragma unroll
;                 for (int n = 0; n < 2; ++n) acc[a][b][m][n] = zero4_pk();
;     bf16x8 At[4][2], B0[2][2], B1[2][2];
;     const char* cA = (const char*)g.A + (size_t)cur.pm * tstep; const char* cB = (const char*)g.Bt + (size_t)cur.pn * tstep;
;     S.a_ready(cur);
;     epi_prefetch(E, cur.pm, cur.pn, evb, tid);
;     if constexpr (SP2) {
;         PG8_STAGE(PG8_SB(0, 0), cB, voffB); PG8_STAGE(PG8_SB(0, 1), cB + hstep, voffB); PG8_STAGE(PG8_SA(0, 0), cA, voffA); PG8_STAGE(PG8_SA(0, 1), cA + hstep, voffA);
;         if (wr == 1) PG8_BAR;
;         PG8_WAIT_V(2); PG8_BAR;
;         PG8_STAGE(PG8_SB(1, 0), cB + kstep, voffB); PG8_STAGE(PG8_SA(1, 0), cA + kstep, voffA); PG8_STAGE(PG8_SB(1, 1), cB + hstep + kstep, voffB);
;         PG8_WAIT_V(6); PG8_BAR;
;     } else {
;         PG8_STAGE(PG8_SB(0, 0), cB, voffB); PG8_STAGE(PG8_SA(0, 0), cA, voffA); PG8_STAGE(PG8_SB(0, 1), cB + hstep, voffB); PG8_STAGE(PG8_SA(0, 1), cA + hstep, voffA);
;         if (wr == 1) PG8_BAR;
;         PG8_WAIT_V(4); PG8_BAR;
;         PG8_STAGE(PG8_SB(1, 0), cB + kstep, voffB); PG8_STAGE(PG8_SA(1, 0), cA + kstep, voffA); PG8_STAGE(PG8_SB(1, 1), cB + hstep + kstep, voffB);
;         PG8_WAIT_V(6); PG8_BAR;
	v_pk_mov_b32 v[134:135], 0, 0
	v_pk_mov_b32 v[136:137], 0, 0
	v_pk_mov_b32 v[122:123], 0, 0
	v_pk_mov_b32 v[124:125], 0, 0
	v_pk_mov_b32 v[110:111], 0, 0
	v_pk_mov_b32 v[112:113], 0, 0
	v_pk_mov_b32 v[106:107], 0, 0
	v_pk_mov_b32 v[108:109], 0, 0
	v_pk_mov_b32 v[94:95], 0, 0
	v_pk_mov_b32 v[96:97], 0, 0
	v_pk_mov_b32 v[90:91], 0, 0
	v_pk_mov_b32 v[92:93], 0, 0
	v_pk_mov_b32 v[78:79], 0, 0
	v_pk_mov_b32 v[80:81], 0, 0
	v_pk_mov_b32 v[74:75], 0, 0
	v_pk_mov_b32 v[76:77], 0, 0
	v_pk_mov_b32 v[118:119], 0, 0
	v_pk_mov_b32 v[120:121], 0, 0
	v_pk_mov_b32 v[114:115], 0, 0
	v_pk_mov_b32 v[116:117], 0, 0
	v_pk_mov_b32 v[102:103], 0, 0
	v_pk_mov_b32 v[104:105], 0, 0
	v_pk_mov_b32 v[98:99], 0, 0
	v_pk_mov_b32 v[100:101], 0, 0
	v_pk_mov_b32 v[86:87], 0, 0
	v_pk_mov_b32 v[88:89], 0, 0
	v_pk_mov_b32 v[82:83], 0, 0
	v_pk_mov_b32 v[84:85], 0, 0
	v_pk_mov_b32 v[70:71], 0, 0
	v_pk_mov_b32 v[72:73], 0, 0
	v_pk_mov_b32 v[66:67], 0, 0
	v_pk_mov_b32 v[68:69], 0, 0
	v_pk_mov_b32 v[62:63], 0, 0
	v_pk_mov_b32 v[64:65], 0, 0
	v_pk_mov_b32 v[58:59], 0, 0
	v_pk_mov_b32 v[60:61], 0, 0
	v_pk_mov_b32 v[46:47], 0, 0
	v_pk_mov_b32 v[48:49], 0, 0
	v_pk_mov_b32 v[42:43], 0, 0
	v_pk_mov_b32 v[44:45], 0, 0
	v_pk_mov_b32 v[30:31], 0, 0
	v_pk_mov_b32 v[32:33], 0, 0
	v_pk_mov_b32 v[26:27], 0, 0
	v_pk_mov_b32 v[28:29], 0, 0
	v_pk_mov_b32 v[14:15], 0, 0
	v_pk_mov_b32 v[16:17], 0, 0
	v_pk_mov_b32 v[10:11], 0, 0
	v_pk_mov_b32 v[12:13], 0, 0
	v_pk_mov_b32 v[54:55], 0, 0
	v_pk_mov_b32 v[56:57], 0, 0
	v_pk_mov_b32 v[50:51], 0, 0
	v_pk_mov_b32 v[52:53], 0, 0
	v_pk_mov_b32 v[38:39], 0, 0
	v_pk_mov_b32 v[40:41], 0, 0
	v_pk_mov_b32 v[34:35], 0, 0
	v_pk_mov_b32 v[36:37], 0, 0
	v_pk_mov_b32 v[22:23], 0, 0
	v_pk_mov_b32 v[24:25], 0, 0
	v_pk_mov_b32 v[18:19], 0, 0
	v_pk_mov_b32 v[20:21], 0, 0
	v_pk_mov_b32 v[6:7], 0, 0
	v_pk_mov_b32 v[8:9], 0, 0
	v_pk_mov_b32 v[2:3], 0, 0
	v_pk_mov_b32 v[4:5], 0, 0
	v_lshl_add_u64 v[130:131], s[16:17], 0, v[128:129]
	s_mov_b32 s13, m0
	s_mov_b32 m0, s84
	s_nop 0
	global_load_lds_dword v[130:131], off
	s_mov_b32 m0, s13
	s_movk_i32 s13, 0x100
	v_cmp_gt_i32_e32 vcc, s13, v126
	v_readlane_b32 s16, v255, 45
	v_mov_b32_e32 v131, v1
	v_cndmask_b32_e64 v130, v219, 0, vcc
	v_readlane_b32 s17, v255, 46
	s_add_i32 s11, s11, 0x20c00
	s_add_i32 s63, s2, 0x10000
	v_lshl_add_u64 v[130:131], s[16:17], 0, v[130:131]
	s_lshl_b32 s16, s28, 8
	s_ashr_i32 s17, s16, 31
	v_lshl_add_u64 v[132:133], s[16:17], 2, v[130:131]
	v_lshl_add_u64 v[132:133], v[132:133], 0, v[128:129]
	s_mov_b32 s13, m0
	s_mov_b32 m0, s11
	s_nop 0
	global_load_lds_dword v[132:133], off
	s_mov_b32 m0, s13
	v_mov_b32_e32 v181, v1
	s_add_i32 s86, s2, 0x12000
	v_lshl_add_u64 v[132:133], s[64:65], 0, v[180:181]
	s_mov_b32 s11, m0
	s_mov_b32 m0, s63
	s_nop 0
	global_load_lds_dwordx4 v[132:133], off
	s_mov_b32 m0, s11
	v_mov_b32_e32 v185, v1
	s_add_u32 s16, s64, 0x40000
	v_lshl_add_u64 v[132:133], s[64:65], 0, v[184:185]
	s_mov_b32 s11, m0
	s_mov_b32 m0, s86
	s_nop 0
	global_load_lds_dwordx4 v[132:133], off
	s_mov_b32 m0, s11
	s_addc_u32 s17, s65, 0
	s_add_i32 s87, s2, 0x14000
	s_add_i32 s90, s2, 0x16000
	v_lshl_add_u64 v[132:133], s[16:17], 0, v[180:181]
	s_mov_b32 s11, m0
	s_mov_b32 m0, s87
	s_nop 0
	global_load_lds_dwordx4 v[132:133], off
	s_mov_b32 m0, s11
	s_add_u32 s88, s70, s0
	v_lshl_add_u64 v[132:133], s[16:17], 0, v[184:185]
	s_mov_b32 s11, m0
	s_mov_b32 m0, s90
	s_nop 0
	global_load_lds_dwordx4 v[132:133], off
	s_mov_b32 m0, s11
	s_addc_u32 s89, s71, s1
	v_mov_b32_e32 v179, v1
	v_lshl_add_u64 v[132:133], s[88:89], 0, v[178:179]
	s_mov_b32 s0, m0
	s_mov_b32 m0, s2
	s_nop 0
	global_load_lds_dwordx4 v[132:133], off
	s_mov_b32 m0, s0
	v_mov_b32_e32 v183, v1
	v_lshl_add_u64 v[132:133], s[88:89], 0, v[182:183]
	s_add_i32 s91, s2, 0x2000
	s_mov_b32 s0, m0
	s_mov_b32 m0, s91
	s_nop 0
	global_load_lds_dwordx4 v[132:133], off
	s_mov_b32 m0, s0
	s_add_u32 s0, s88, 0x40000
	s_addc_u32 s1, s89, 0
	s_add_i32 s20, s2, 0x4000
	v_lshl_add_u64 v[132:133], s[0:1], 0, v[178:179]
	s_mov_b32 s11, m0
	s_mov_b32 m0, s20
	s_nop 0
	global_load_lds_dwordx4 v[132:133], off
	s_mov_b32 m0, s11
	s_add_i32 s21, s2, 0x6000
	v_lshl_add_u64 v[132:133], s[0:1], 0, v[182:183]
	s_mov_b32 s0, m0
	s_mov_b32 m0, s21
	s_nop 0
	global_load_lds_dwordx4 v[132:133], off
	s_mov_b32 m0, s0
	s_cmp_eq_u32 s10, 1
	s_cselect_b64 s[0:1], -1, 0
	v_writelane_b32 v255, s0, 55
	v_mov_b32_e32 v215, 1
	s_cmp_lg_u32 s10, 1
	v_writelane_b32 v255, s1, 56
	s_cbranch_scc1 .LBB0_258
	s_setprio 1
	s_barrier

; #define PG8_STAGE(bufoff, gbase, voff) do { _Pragma("unroll") for (int _i = 0; _i < 2; ++_i) \
;         glds16_asm((const char*)(gbase) + (voff)[_i], ldsb + (unsigned)((bufoff) + _i * 8192)); } while (0)
; #define PG8_LDA(dst, b, h) do { _Pragma("unroll") for (int m = 0; m < 4; ++m) _Pragma("unroll") for (int k = 0; k < 2; ++k) dst[m][k] = *(const PG8_LAS bf16x8*)(lds + PG8_SA(b, h) + aoff + m * 2048 + k * 1024); } while (0)
; #define PG8_LDB(dst, b, h) do { _Pragma("unroll") for (int n = 0; n < 2; ++n) _Pragma("unroll") for (int k = 0; k < 2; ++k) dst[n][k] = *(const PG8_LAS bf16x8*)(lds + PG8_SB(b, h) + boff + n * 2048 + k * 1024); } while (0)
; #define PG8_MMA(ai, bj, At, Bt) do { __builtin_amdgcn_s_setprio(1); _Pragma("unroll") for (int m = 0; m < 4; ++m) _Pragma("unroll") for (int n = 0; n < 2; ++n) _Pragma("unroll") for (int k = 0; k < 2; ++k) \
;         acc[ai][bj][m][n] = __builtin_amdgcn_mfma_f32_16x16x32_bf16(Bt[n][k], At[m][k], acc[ai][bj][m][n], 0, 0, 0); __builtin_amdgcn_s_setprio(0); } while (0)
; #define PG8_WAIT_V(n) asm volatile("s_waitcnt vmcnt(" #n ")" ::: "memory")
; #define PG8_BAR __builtin_amdgcn_s_barrier()
; template <class Epi, class Sched, bool ALIGN_EPI = false, bool SP2 = false>
; __device__ __forceinline__ void gemm_phase(PG8_LAS unsigned char* lds, const Gemm g, const Sched& S, const Epi& E, int wave_u) {
;     ...
;             PG8_LDB(B0, 0, 0); PG8_LDB(B1, 0, 1); PG8_SCHED; PG8_LDA(At, 0, 0); PG8_STAGE(PG8_SA(1, 1), a1 + hstep, voffA);
;             PG8_WAIT_V(8); PG8_WAIT_L(0); PG8_BAR; PG8_MMA(0, 0, At, B0); PG8_MMA(0, 1, At, B1); PG8_BAR; PG8_SCHED;
;             PG8_LDA(At, 0, 1); PG8_STAGE(PG8_SB(0, 0), b2, voffB); PG8_STAGE(PG8_SB(0, 1), b2 + hstep, voffB); PG8_STAGE(PG8_SA(0, 0), a2, voffA);
;             PG8_WAIT_V(8); PG8_WAIT_L(0); PG8_BAR; PG8_MMA(1, 0, At, B0); PG8_MMA(1, 1, At, B1); PG8_BAR; PG8_SCHED;
;             PG8_LDB(B0, 1, 0); PG8_LDB(B1, 1, 1); PG8_SCHED; PG8_LDA(At, 1, 0); PG8_STAGE(PG8_SA(0, 1), a2 + hstep, voffA);
;             PG8_WAIT_V(8); PG8_WAIT_L(0); PG8_BAR; PG8_MMA(0, 0, At, B0); PG8_MMA(0, 1, At, B1); PG8_BAR; PG8_SCHED;
;             PG8_LDA(At, 1, 1); PG8_STAGE(PG8_SB(1, 0), b3, voffB); PG8_STAGE(PG8_SB(1, 1), b3 + hstep, voffB); PG8_STAGE(PG8_SA(1, 0), a3, voffA);
;             PG8_WAIT_V(8); PG8_WAIT_L(0); PG8_BAR; PG8_MMA(1, 0, At, B0); PG8_MMA(1, 1, At, B1); PG8_BAR; PG8_SCHED;
.LBB0_264:
	v_add_u32_e32 v0, 0x10000, v211
	s_waitcnt lgkmcnt(0)
	ds_read_b128 v[130:133], v0
	ds_read_b128 v[138:141], v0 offset:1024
	ds_read_b128 v[142:145], v0 offset:2048
	ds_read_b128 v[146:149], v0 offset:3072
	v_add_u32_e32 v0, 0x14000, v211
	s_add_u32 s1, s88, 0xfffc0080
	ds_read_b128 v[150:153], v0
	ds_read_b128 v[154:157], v0 offset:1024
	ds_read_b128 v[158:161], v0 offset:2048
	ds_read_b128 v[162:165], v0 offset:3072
	s_addc_u32 s46, s89, -1
	s_and_b64 s[44:45], s[44:45], exec
	s_cselect_b32 s56, s19, s1
	s_cselect_b32 s57, s13, s46
	s_cselect_b32 s45, s17, s41
	s_cselect_b32 s44, s29, s40
	s_add_u32 s46, s56, 0x80
	s_addc_u32 s47, s57, 0
	s_add_u32 s48, s44, 0x80
	s_addc_u32 s49, s45, 0
	ds_read_b128 v[166:169], v212
	ds_read_b128 v[170:173], v212 offset:1024
	ds_read_b128 v[174:177], v212 offset:2048
	ds_read_b128 v[198:201], v212 offset:3072
	ds_read_b128 v[224:227], v212 offset:4096
	ds_read_b128 v[228:231], v212 offset:5120
	ds_read_b128 v[232:235], v212 offset:6144
	ds_read_b128 v[236:239], v212 offset:7168
	v_lshl_add_u64 v[202:203], s[88:89], 0, v[178:179]
	s_mov_b32 s1, m0
	s_mov_b32 m0, s27
	s_nop 0
	global_load_lds_dwordx4 v[202:203], off
	s_mov_b32 m0, s1
	v_lshl_add_u64 v[202:203], s[88:89], 0, v[182:183]
	s_mov_b32 s1, m0
	s_mov_b32 m0, s60
	s_nop 0
	global_load_lds_dwordx4 v[202:203], off
	s_mov_b32 m0, s1
	s_waitcnt vmcnt(8)
	s_waitcnt lgkmcnt(0)
	s_barrier
	s_waitcnt lgkmcnt(7)
	v_mfma_f32_16x16x32_bf16 v[134:137], v[130:133], v[166:169], v[134:137]
	v_mfma_f32_16x16x32_bf16 v[122:125], v[142:145], v[166:169], v[122:125]
	s_waitcnt lgkmcnt(5)
	v_mfma_f32_16x16x32_bf16 v[110:113], v[130:133], v[174:177], v[110:113]
	v_mfma_f32_16x16x32_bf16 v[106:109], v[142:145], v[174:177], v[106:109]
	s_waitcnt lgkmcnt(3)
	v_mfma_f32_16x16x32_bf16 v[94:97], v[130:133], v[224:227], v[94:97]
	v_mfma_f32_16x16x32_bf16 v[90:93], v[142:145], v[224:227], v[90:93]
	s_waitcnt lgkmcnt(1)
	v_mfma_f32_16x16x32_bf16 v[78:81], v[130:133], v[232:235], v[78:81]
	v_mfma_f32_16x16x32_bf16 v[74:77], v[142:145], v[232:235], v[74:77]
	v_mfma_f32_16x16x32_bf16 v[134:137], v[138:141], v[170:173], v[134:137]
	v_mfma_f32_16x16x32_bf16 v[122:125], v[146:149], v[170:173], v[122:125]
	v_mfma_f32_16x16x32_bf16 v[110:113], v[138:141], v[198:201], v[110:113]
	v_mfma_f32_16x16x32_bf16 v[106:109], v[146:149], v[198:201], v[106:109]
	v_mfma_f32_16x16x32_bf16 v[94:97], v[138:141], v[228:231], v[94:97]
	v_mfma_f32_16x16x32_bf16 v[90:93], v[146:149], v[228:231], v[90:93]
	s_waitcnt lgkmcnt(0)
	v_mfma_f32_16x16x32_bf16 v[78:81], v[138:141], v[236:239], v[78:81]
	v_mfma_f32_16x16x32_bf16 v[74:77], v[146:149], v[236:239], v[74:77]
	v_mfma_f32_16x16x32_bf16 v[118:121], v[150:153], v[166:169], v[118:121]
	v_mfma_f32_16x16x32_bf16 v[114:117], v[158:161], v[166:169], v[114:117]
	v_mfma_f32_16x16x32_bf16 v[102:105], v[150:153], v[174:177], v[102:105]
	v_mfma_f32_16x16x32_bf16 v[98:101], v[158:161], v[174:177], v[98:101]
	v_mfma_f32_16x16x32_bf16 v[86:89], v[150:153], v[224:227], v[86:89]
	v_mfma_f32_16x16x32_bf16 v[82:85], v[158:161], v[224:227], v[82:85]
	v_mfma_f32_16x16x32_bf16 v[70:73], v[150:153], v[232:235], v[70:73]
	v_mfma_f32_16x16x32_bf16 v[66:69], v[158:161], v[232:235], v[66:69]
	v_mfma_f32_16x16x32_bf16 v[118:121], v[154:157], v[170:173], v[118:121]
	v_mfma_f32_16x16x32_bf16 v[114:117], v[162:165], v[170:173], v[114:117]
	v_mfma_f32_16x16x32_bf16 v[102:105], v[154:157], v[198:201], v[102:105]
	v_mfma_f32_16x16x32_bf16 v[98:101], v[162:165], v[198:201], v[98:101]
	v_mfma_f32_16x16x32_bf16 v[86:89], v[154:157], v[228:231], v[86:89]
	v_mfma_f32_16x16x32_bf16 v[82:85], v[162:165], v[228:231], v[82:85]
	v_mfma_f32_16x16x32_bf16 v[70:73], v[154:157], v[236:239], v[70:73]
	v_mfma_f32_16x16x32_bf16 v[66:69], v[162:165], v[236:239], v[66:69]
	s_barrier
	ds_read_b128 v[166:169], v212 offset:16384
	ds_read_b128 v[170:173], v212 offset:17408
	ds_read_b128 v[174:177], v212 offset:18432
	ds_read_b128 v[198:201], v212 offset:19456
	ds_read_b128 v[224:227], v212 offset:20480
	ds_read_b128 v[228:231], v212 offset:21504
	ds_read_b128 v[232:235], v212 offset:22528
	ds_read_b128 v[236:239], v212 offset:23552
	v_lshl_add_u64 v[202:203], s[44:45], 0, v[180:181]
	s_mov_b32 s1, m0
	s_mov_b32 m0, s63
	s_nop 0
	global_load_lds_dwordx4 v[202:203], off
	s_mov_b32 m0, s1
	s_add_u32 s58, s44, 0x40000
	v_lshl_add_u64 v[202:203], s[44:45], 0, v[184:185]
	s_mov_b32 s1, m0
	s_mov_b32 m0, s86
	s_nop 0
	global_load_lds_dwordx4 v[202:203], off
	s_mov_b32 m0, s1
	s_addc_u32 s59, s45, 0
	v_lshl_add_u64 v[202:203], s[58:59], 0, v[180:181]
	s_mov_b32 s1, m0
	s_mov_b32 m0, s87
	s_nop 0
	global_load_lds_dwordx4 v[202:203], off
	s_mov_b32 m0, s1
	v_lshl_add_u64 v[202:203], s[58:59], 0, v[184:185]
	s_mov_b32 s1, m0
	s_mov_b32 m0, s90
	s_nop 0
	global_load_lds_dwordx4 v[202:203], off
	s_mov_b32 m0, s1
	v_lshl_add_u64 v[202:203], s[56:57], 0, v[178:179]
	s_mov_b32 s1, m0
	s_mov_b32 m0, s2
	s_nop 0
	global_load_lds_dwordx4 v[202:203], off
	s_mov_b32 m0, s1
	v_lshl_add_u64 v[202:203], s[56:57], 0, v[182:183]
	s_mov_b32 s1, m0
	s_mov_b32 m0, s91
	s_nop 0
	global_load_lds_dwordx4 v[202:203], off
	s_mov_b32 m0, s1
	s_waitcnt vmcnt(8)
	s_waitcnt lgkmcnt(0)
	s_barrier
; #define PG8_STAGE(bufoff, gbase, voff) do { _Pragma("unroll") for (int _i = 0; _i < 2; ++_i) \
;         glds16_asm((const char*)(gbase) + (voff)[_i], ldsb + (unsigned)((bufoff) + _i * 8192)); } while (0)
; #define PG8_LDA(dst, b, h) do { _Pragma("unroll") for (int m = 0; m < 4; ++m) _Pragma("unroll") for (int k = 0; k < 2; ++k) dst[m][k] = *(const PG8_LAS bf16x8*)(lds + PG8_SA(b, h) + aoff + m * 2048 + k * 1024); } while (0)
; #define PG8_LDB(dst, b, h) do { _Pragma("unroll") for (int n = 0; n < 2; ++n) _Pragma("unroll") for (int k = 0; k < 2; ++k) dst[n][k] = *(const PG8_LAS bf16x8*)(lds + PG8_SB(b, h) + boff + n * 2048 + k * 1024); } while (0)
; #define PG8_MMA(ai, bj, At, Bt) do { __builtin_amdgcn_s_setprio(1); _Pragma("unroll") for (int m = 0; m < 4; ++m) _Pragma("unroll") for (int n = 0; n < 2; ++n) _Pragma("unroll") for (int k = 0; k < 2; ++k) \
;         acc[ai][bj][m][n] = __builtin_amdgcn_mfma_f32_16x16x32_bf16(Bt[n][k], At[m][k], acc[ai][bj][m][n], 0, 0, 0); __builtin_amdgcn_s_setprio(0); } while (0)
; #define PG8_WAIT_V(n) asm volatile("s_waitcnt vmcnt(" #n ")" ::: "memory")
; #define PG8_BAR __builtin_amdgcn_s_barrier()
; template <class Epi, class Sched, bool ALIGN_EPI = false, bool SP2 = false>
; __device__ __forceinline__ void gemm_phase(PG8_LAS unsigned char* lds, const Gemm g, const Sched& S, const Epi& E, int wave_u) {
;     ...
;             PG8_LDB(B0, 0, 0); PG8_LDB(B1, 0, 1); PG8_SCHED; PG8_LDA(At, 0, 0); PG8_STAGE(PG8_SA(1, 1), a1 + hstep, voffA);
;             PG8_WAIT_V(8); PG8_WAIT_L(0); PG8_BAR; PG8_MMA(0, 0, At, B0); PG8_MMA(0, 1, At, B1); PG8_BAR; PG8_SCHED;
;             PG8_LDA(At, 0, 1); PG8_STAGE(PG8_SB(0, 0), b2, voffB); PG8_STAGE(PG8_SB(0, 1), b2 + hstep, voffB); PG8_STAGE(PG8_SA(0, 0), a2, voffA);
;             PG8_WAIT_V(8); PG8_WAIT_L(0); PG8_BAR; PG8_MMA(1, 0, At, B0); PG8_MMA(1, 1, At, B1); PG8_BAR; PG8_SCHED;
;             PG8_LDB(B0, 1, 0); PG8_LDB(B1, 1, 1); PG8_SCHED; PG8_LDA(At, 1, 0); PG8_STAGE(PG8_SA(0, 1), a2 + hstep, voffA);
;             PG8_WAIT_V(8); PG8_WAIT_L(0); PG8_BAR; PG8_MMA(0, 0, At, B0); PG8_MMA(0, 1, At, B1); PG8_BAR; PG8_SCHED;
;             PG8_LDA(At, 1, 1); PG8_STAGE(PG8_SB(1, 0), b3, voffB); PG8_STAGE(PG8_SB(1, 1), b3 + hstep, voffB); PG8_STAGE(PG8_SA(1, 0), a3, voffA);
;             PG8_WAIT_V(8); PG8_WAIT_L(0); PG8_BAR; PG8_MMA(1, 0, At, B0); PG8_MMA(1, 1, At, B1); PG8_BAR; PG8_SCHED;
	s_waitcnt lgkmcnt(7)
	v_mfma_f32_16x16x32_bf16 v[62:65], v[130:133], v[166:169], v[62:65]
	v_mfma_f32_16x16x32_bf16 v[58:61], v[142:145], v[166:169], v[58:61]
	s_waitcnt lgkmcnt(5)
	v_mfma_f32_16x16x32_bf16 v[46:49], v[130:133], v[174:177], v[46:49]
	v_mfma_f32_16x16x32_bf16 v[42:45], v[142:145], v[174:177], v[42:45]
	s_waitcnt lgkmcnt(3)
	v_mfma_f32_16x16x32_bf16 v[30:33], v[130:133], v[224:227], v[30:33]
	v_mfma_f32_16x16x32_bf16 v[26:29], v[142:145], v[224:227], v[26:29]
	s_waitcnt lgkmcnt(1)
	v_mfma_f32_16x16x32_bf16 v[14:17], v[130:133], v[232:235], v[14:17]
	v_mfma_f32_16x16x32_bf16 v[10:13], v[142:145], v[232:235], v[10:13]
	v_mfma_f32_16x16x32_bf16 v[62:65], v[138:141], v[170:173], v[62:65]
	v_mfma_f32_16x16x32_bf16 v[58:61], v[146:149], v[170:173], v[58:61]
	v_mfma_f32_16x16x32_bf16 v[46:49], v[138:141], v[198:201], v[46:49]
	v_mfma_f32_16x16x32_bf16 v[42:45], v[146:149], v[198:201], v[42:45]
	v_mfma_f32_16x16x32_bf16 v[30:33], v[138:141], v[228:231], v[30:33]
	v_mfma_f32_16x16x32_bf16 v[26:29], v[146:149], v[228:231], v[26:29]
	s_waitcnt lgkmcnt(0)
	v_mfma_f32_16x16x32_bf16 v[14:17], v[138:141], v[236:239], v[14:17]
	v_mfma_f32_16x16x32_bf16 v[10:13], v[146:149], v[236:239], v[10:13]
	v_mfma_f32_16x16x32_bf16 v[54:57], v[150:153], v[166:169], v[54:57]
	v_mfma_f32_16x16x32_bf16 v[50:53], v[158:161], v[166:169], v[50:53]
	v_mfma_f32_16x16x32_bf16 v[38:41], v[150:153], v[174:177], v[38:41]
	v_mfma_f32_16x16x32_bf16 v[34:37], v[158:161], v[174:177], v[34:37]
	v_mfma_f32_16x16x32_bf16 v[22:25], v[150:153], v[224:227], v[22:25]
	v_mfma_f32_16x16x32_bf16 v[18:21], v[158:161], v[224:227], v[18:21]
	v_mfma_f32_16x16x32_bf16 v[6:9], v[150:153], v[232:235], v[6:9]
	v_mfma_f32_16x16x32_bf16 v[2:5], v[158:161], v[232:235], v[2:5]
	v_mfma_f32_16x16x32_bf16 v[54:57], v[154:157], v[170:173], v[54:57]
	v_mfma_f32_16x16x32_bf16 v[50:53], v[162:165], v[170:173], v[50:53]
	v_mfma_f32_16x16x32_bf16 v[38:41], v[154:157], v[198:201], v[38:41]
	v_mfma_f32_16x16x32_bf16 v[34:37], v[162:165], v[198:201], v[34:37]
	v_mfma_f32_16x16x32_bf16 v[22:25], v[154:157], v[228:231], v[22:25]
	v_mfma_f32_16x16x32_bf16 v[18:21], v[162:165], v[228:231], v[18:21]
	v_mfma_f32_16x16x32_bf16 v[6:9], v[154:157], v[236:239], v[6:9]
	v_mfma_f32_16x16x32_bf16 v[2:5], v[162:165], v[236:239], v[2:5]
	s_barrier
	v_add_u32_e32 v0, 0x18000, v211
	ds_read_b128 v[130:133], v0
	ds_read_b128 v[138:141], v0 offset:1024
	ds_read_b128 v[142:145], v0 offset:2048
	ds_read_b128 v[146:149], v0 offset:3072
	v_add_u32_e32 v0, 0x1c000, v211
	ds_read_b128 v[150:153], v0
	ds_read_b128 v[154:157], v0 offset:1024
	ds_read_b128 v[158:161], v0 offset:2048
	ds_read_b128 v[162:165], v0 offset:3072
	ds_read_b128 v[166:169], v212 offset:32768
	ds_read_b128 v[170:173], v212 offset:33792
	ds_read_b128 v[174:177], v212 offset:34816
	ds_read_b128 v[198:201], v212 offset:35840
	ds_read_b128 v[224:227], v212 offset:36864
	ds_read_b128 v[228:231], v212 offset:37888
	ds_read_b128 v[232:235], v212 offset:38912
	ds_read_b128 v[236:239], v212 offset:39936
	s_add_u32 s56, s56, 0x40000
	s_addc_u32 s57, s57, 0
	v_lshl_add_u64 v[202:203], s[56:57], 0, v[178:179]
	s_mov_b32 s1, m0
	s_mov_b32 m0, s20
	s_nop 0
	global_load_lds_dwordx4 v[202:203], off
	s_mov_b32 m0, s1
	v_lshl_add_u64 v[202:203], s[56:57], 0, v[182:183]
	s_mov_b32 s1, m0
	s_mov_b32 m0, s21
	s_nop 0
	global_load_lds_dwordx4 v[202:203], off
	s_mov_b32 m0, s1
	s_waitcnt vmcnt(8)
	s_waitcnt lgkmcnt(0)
	s_barrier
	s_waitcnt lgkmcnt(7)
	v_mfma_f32_16x16x32_bf16 v[134:137], v[130:133], v[166:169], v[134:137]
	v_mfma_f32_16x16x32_bf16 v[122:125], v[142:145], v[166:169], v[122:125]
	s_waitcnt lgkmcnt(5)
	v_mfma_f32_16x16x32_bf16 v[110:113], v[130:133], v[174:177], v[110:113]
	v_mfma_f32_16x16x32_bf16 v[106:109], v[142:145], v[174:177], v[106:109]
	s_waitcnt lgkmcnt(3)
	v_mfma_f32_16x16x32_bf16 v[94:97], v[130:133], v[224:227], v[94:97]
	v_mfma_f32_16x16x32_bf16 v[90:93], v[142:145], v[224:227], v[90:93]
	s_waitcnt lgkmcnt(1)
	v_mfma_f32_16x16x32_bf16 v[78:81], v[130:133], v[232:235], v[78:81]
	v_mfma_f32_16x16x32_bf16 v[74:77], v[142:145], v[232:235], v[74:77]
	v_mfma_f32_16x16x32_bf16 v[134:137], v[138:141], v[170:173], v[134:137]
	v_mfma_f32_16x16x32_bf16 v[122:125], v[146:149], v[170:173], v[122:125]
	v_mfma_f32_16x16x32_bf16 v[110:113], v[138:141], v[198:201], v[110:113]
	v_mfma_f32_16x16x32_bf16 v[106:109], v[146:149], v[198:201], v[106:109]
	v_mfma_f32_16x16x32_bf16 v[94:97], v[138:141], v[228:231], v[94:97]
	v_mfma_f32_16x16x32_bf16 v[90:93], v[146:149], v[228:231], v[90:93]
	s_waitcnt lgkmcnt(0)
	v_mfma_f32_16x16x32_bf16 v[78:81], v[138:141], v[236:239], v[78:81]
	v_mfma_f32_16x16x32_bf16 v[74:77], v[146:149], v[236:239], v[74:77]
	v_mfma_f32_16x16x32_bf16 v[118:121], v[150:153], v[166:169], v[118:121]
	v_mfma_f32_16x16x32_bf16 v[114:117], v[158:161], v[166:169], v[114:117]
	v_mfma_f32_16x16x32_bf16 v[102:105], v[150:153], v[174:177], v[102:105]
	v_mfma_f32_16x16x32_bf16 v[98:101], v[158:161], v[174:177], v[98:101]
	v_mfma_f32_16x16x32_bf16 v[86:89], v[150:153], v[224:227], v[86:89]
	v_mfma_f32_16x16x32_bf16 v[82:85], v[158:161], v[224:227], v[82:85]
	v_mfma_f32_16x16x32_bf16 v[70:73], v[150:153], v[232:235], v[70:73]
	v_mfma_f32_16x16x32_bf16 v[66:69], v[158:161], v[232:235], v[66:69]
	v_mfma_f32_16x16x32_bf16 v[118:121], v[154:157], v[170:173], v[118:121]
	v_mfma_f32_16x16x32_bf16 v[114:117], v[162:165], v[170:173], v[114:117]
	v_mfma_f32_16x16x32_bf16 v[102:105], v[154:157], v[198:201], v[102:105]
	v_mfma_f32_16x16x32_bf16 v[98:101], v[162:165], v[198:201], v[98:101]
	v_mfma_f32_16x16x32_bf16 v[86:89], v[154:157], v[228:231], v[86:89]
	v_mfma_f32_16x16x32_bf16 v[82:85], v[162:165], v[228:231], v[82:85]
	v_mfma_f32_16x16x32_bf16 v[70:73], v[154:157], v[236:239], v[70:73]
	v_mfma_f32_16x16x32_bf16 v[66:69], v[162:165], v[236:239], v[66:69]
	s_barrier
; #define PG8_STAGE(bufoff, gbase, voff) do { _Pragma("unroll") for (int _i = 0; _i < 2; ++_i) \
;         glds16_asm((const char*)(gbase) + (voff)[_i], ldsb + (unsigned)((bufoff) + _i * 8192)); } while (0)
; #define PG8_LDA(dst, b, h) do { _Pragma("unroll") for (int m = 0; m < 4; ++m) _Pragma("unroll") for (int k = 0; k < 2; ++k) dst[m][k] = *(const PG8_LAS bf16x8*)(lds + PG8_SA(b, h) + aoff + m * 2048 + k * 1024); } while (0)
; #define PG8_LDB(dst, b, h) do { _Pragma("unroll") for (int n = 0; n < 2; ++n) _Pragma("unroll") for (int k = 0; k < 2; ++k) dst[n][k] = *(const PG8_LAS bf16x8*)(lds + PG8_SB(b, h) + boff + n * 2048 + k * 1024); } while (0)
; #define PG8_MMA(ai, bj, At, Bt) do { __builtin_amdgcn_s_setprio(1); _Pragma("unroll") for (int m = 0; m < 4; ++m) _Pragma("unroll") for (int n = 0; n < 2; ++n) _Pragma("unroll") for (int k = 0; k < 2; ++k) \
;         acc[ai][bj][m][n] = __builtin_amdgcn_mfma_f32_16x16x32_bf16(Bt[n][k], At[m][k], acc[ai][bj][m][n], 0, 0, 0); __builtin_amdgcn_s_setprio(0); } while (0)
; #define PG8_WAIT_V(n) asm volatile("s_waitcnt vmcnt(" #n ")" ::: "memory")
; #define PG8_BAR __builtin_amdgcn_s_barrier()
; template <class Epi, class Sched, bool ALIGN_EPI = false, bool SP2 = false>
; __device__ __forceinline__ void gemm_phase(PG8_LAS unsigned char* lds, const Gemm g, const Sched& S, const Epi& E, int wave_u) {
;     ...
;             PG8_LDB(B0, 0, 0); PG8_LDB(B1, 0, 1); PG8_SCHED; PG8_LDA(At, 0, 0); PG8_STAGE(PG8_SA(1, 1), a1 + hstep, voffA);
;             PG8_WAIT_V(8); PG8_WAIT_L(0); PG8_BAR; PG8_MMA(0, 0, At, B0); PG8_MMA(0, 1, At, B1); PG8_BAR; PG8_SCHED;
;             PG8_LDA(At, 0, 1); PG8_STAGE(PG8_SB(0, 0), b2, voffB); PG8_STAGE(PG8_SB(0, 1), b2 + hstep, voffB); PG8_STAGE(PG8_SA(0, 0), a2, voffA);
;             PG8_WAIT_V(8); PG8_WAIT_L(0); PG8_BAR; PG8_MMA(1, 0, At, B0); PG8_MMA(1, 1, At, B1); PG8_BAR; PG8_SCHED;
;             PG8_LDB(B0, 1, 0); PG8_LDB(B1, 1, 1); PG8_SCHED; PG8_LDA(At, 1, 0); PG8_STAGE(PG8_SA(0, 1), a2 + hstep, voffA);
;             PG8_WAIT_V(8); PG8_WAIT_L(0); PG8_BAR; PG8_MMA(0, 0, At, B0); PG8_MMA(0, 1, At, B1); PG8_BAR; PG8_SCHED;
;             PG8_LDA(At, 1, 1); PG8_STAGE(PG8_SB(1, 0), b3, voffB); PG8_STAGE(PG8_SB(1, 1), b3 + hstep, voffB); PG8_STAGE(PG8_SA(1, 0), a3, voffA);
;             PG8_WAIT_V(8); PG8_WAIT_L(0); PG8_BAR; PG8_MMA(1, 0, At, B0); PG8_MMA(1, 1, At, B1); PG8_BAR; PG8_SCHED;
	ds_read_b128 v[166:169], v212 offset:49152
	ds_read_b128 v[170:173], v212 offset:50176
	ds_read_b128 v[174:177], v212 offset:51200
	ds_read_b128 v[198:201], v212 offset:52224
	ds_read_b128 v[224:227], v212 offset:53248
	ds_read_b128 v[228:231], v212 offset:54272
	ds_read_b128 v[232:235], v212 offset:55296
	ds_read_b128 v[236:239], v212 offset:56320
	v_lshl_add_u64 v[202:203], s[48:49], 0, v[180:181]
	s_mov_b32 s1, m0
	s_mov_b32 m0, s22
	s_nop 0
	global_load_lds_dwordx4 v[202:203], off
	s_mov_b32 m0, s1
	s_add_u32 s44, s44, 0x40080
	v_lshl_add_u64 v[202:203], s[48:49], 0, v[184:185]
	s_mov_b32 s1, m0
	s_mov_b32 m0, s23
	s_nop 0
	global_load_lds_dwordx4 v[202:203], off
	s_mov_b32 m0, s1
	s_addc_u32 s45, s45, 0
	v_lshl_add_u64 v[202:203], s[44:45], 0, v[180:181]
	s_mov_b32 s1, m0
	s_mov_b32 m0, s61
	s_nop 0
	global_load_lds_dwordx4 v[202:203], off
	s_mov_b32 m0, s1
	v_lshl_add_u64 v[202:203], s[44:45], 0, v[184:185]
	s_mov_b32 s1, m0
	s_mov_b32 m0, s26
	s_nop 0
	global_load_lds_dwordx4 v[202:203], off
	s_mov_b32 m0, s1
	v_lshl_add_u64 v[202:203], s[46:47], 0, v[178:179]
	s_mov_b32 s1, m0
	s_mov_b32 m0, s24
	s_nop 0
	global_load_lds_dwordx4 v[202:203], off
	s_mov_b32 m0, s1
	v_lshl_add_u64 v[202:203], s[46:47], 0, v[182:183]
	s_mov_b32 s1, m0
	s_mov_b32 m0, s25
	s_nop 0
	global_load_lds_dwordx4 v[202:203], off
	s_mov_b32 m0, s1
	s_waitcnt vmcnt(8)
	s_waitcnt lgkmcnt(0)
	s_barrier
	s_waitcnt lgkmcnt(7)
	v_mfma_f32_16x16x32_bf16 v[62:65], v[130:133], v[166:169], v[62:65]
	v_mfma_f32_16x16x32_bf16 v[58:61], v[142:145], v[166:169], v[58:61]
	s_waitcnt lgkmcnt(5)
	v_mfma_f32_16x16x32_bf16 v[46:49], v[130:133], v[174:177], v[46:49]
	v_mfma_f32_16x16x32_bf16 v[42:45], v[142:145], v[174:177], v[42:45]
	s_waitcnt lgkmcnt(3)
	v_mfma_f32_16x16x32_bf16 v[30:33], v[130:133], v[224:227], v[30:33]
	v_mfma_f32_16x16x32_bf16 v[26:29], v[142:145], v[224:227], v[26:29]
	s_waitcnt lgkmcnt(1)
	v_mfma_f32_16x16x32_bf16 v[14:17], v[130:133], v[232:235], v[14:17]
	v_mfma_f32_16x16x32_bf16 v[10:13], v[142:145], v[232:235], v[10:13]
	v_mfma_f32_16x16x32_bf16 v[62:65], v[138:141], v[170:173], v[62:65]
	v_mfma_f32_16x16x32_bf16 v[58:61], v[146:149], v[170:173], v[58:61]
	v_mfma_f32_16x16x32_bf16 v[46:49], v[138:141], v[198:201], v[46:49]
	v_mfma_f32_16x16x32_bf16 v[42:45], v[146:149], v[198:201], v[42:45]
	v_mfma_f32_16x16x32_bf16 v[30:33], v[138:141], v[228:231], v[30:33]
	v_mfma_f32_16x16x32_bf16 v[26:29], v[146:149], v[228:231], v[26:29]
	s_waitcnt lgkmcnt(0)
	v_mfma_f32_16x16x32_bf16 v[14:17], v[138:141], v[236:239], v[14:17]
	v_mfma_f32_16x16x32_bf16 v[10:13], v[146:149], v[236:239], v[10:13]
	v_mfma_f32_16x16x32_bf16 v[54:57], v[150:153], v[166:169], v[54:57]
	v_mfma_f32_16x16x32_bf16 v[50:53], v[158:161], v[166:169], v[50:53]
	v_mfma_f32_16x16x32_bf16 v[38:41], v[150:153], v[174:177], v[38:41]
	v_mfma_f32_16x16x32_bf16 v[34:37], v[158:161], v[174:177], v[34:37]
	v_mfma_f32_16x16x32_bf16 v[22:25], v[150:153], v[224:227], v[22:25]
	v_mfma_f32_16x16x32_bf16 v[18:21], v[158:161], v[224:227], v[18:21]
	v_mfma_f32_16x16x32_bf16 v[6:9], v[150:153], v[232:235], v[6:9]
	v_mfma_f32_16x16x32_bf16 v[2:5], v[158:161], v[232:235], v[2:5]
	v_mfma_f32_16x16x32_bf16 v[54:57], v[154:157], v[170:173], v[54:57]
	v_mfma_f32_16x16x32_bf16 v[50:53], v[162:165], v[170:173], v[50:53]
	v_mfma_f32_16x16x32_bf16 v[38:41], v[154:157], v[198:201], v[38:41]
	v_mfma_f32_16x16x32_bf16 v[34:37], v[162:165], v[198:201], v[34:37]
	v_mfma_f32_16x16x32_bf16 v[22:25], v[154:157], v[228:231], v[22:25]
	v_mfma_f32_16x16x32_bf16 v[18:21], v[162:165], v[228:231], v[18:21]
	v_mfma_f32_16x16x32_bf16 v[6:9], v[154:157], v[236:239], v[6:9]
	v_mfma_f32_16x16x32_bf16 v[2:5], v[162:165], v[236:239], v[2:5]
	s_barrier
	s_add_i32 s52, s52, 2
	s_add_u32 s88, s88, 0x100
	s_addc_u32 s89, s89, 0
	s_add_u32 s40, s40, 0x100
	s_addc_u32 s41, s41, 0
	s_cmp_gt_u32 s52, 13
	s_cbranch_scc1 .LBB0_267

; #define PG8_WAIT_V(n) asm volatile("s_waitcnt vmcnt(" #n ")" ::: "memory")
; #define PG8_BAR __builtin_amdgcn_s_barrier()
; template <class Epi, class Sched, bool ALIGN_EPI = false, bool SP2 = false>
; __device__ __forceinline__ void gemm_phase(PG8_LAS unsigned char* lds, const Gemm g, const Sched& S, const Epi& E, int wave_u) {
;     ...
;     PG8_WAIT_V(0);
;     if constexpr (!ALIGN_EPI) { if (wr == 0) PG8_BAR; }
;     PG8_BAR;
.LBB0_337:
	s_setprio 0
	s_waitcnt vmcnt(0)
	v_readlane_b32 s64, v255, 16
	v_readlane_b32 s76, v255, 18
	v_readlane_b32 s78, v255, 20
	v_readlane_b32 s80, v255, 22
	v_readlane_b32 s82, v255, 24
	v_readlane_b32 s86, v255, 26
	v_readlane_b32 s88, v255, 28
	v_readlane_b32 s84, v251, 41
	v_readlane_b32 s90, v251, 61
	v_readlane_b32 s30, v255, 60
	v_readlane_b32 s65, v255, 17
	v_readlane_b32 s77, v255, 19
	v_readlane_b32 s79, v255, 21
	v_readlane_b32 s81, v255, 23
	v_readlane_b32 s83, v255, 25
	v_readlane_b32 s87, v255, 27
	v_readlane_b32 s89, v255, 29
	v_readlane_b32 s85, v251, 42
	v_readlane_b32 s91, v251, 62
	v_readlane_b32 s31, v255, 61
	s_barrier

; template <class Epi, class Sched, bool ALIGN_EPI = false, bool SP2 = false>
; __device__ __forceinline__ void gemm_phase(PG8_LAS unsigned char* lds, const Gemm g, const Sched& S, const Epi& E, int wave_u) {
;     ...
;     const int tid = tid_, wid = __builtin_amdgcn_readfirstlane(tid >> 6), lane = tid & 63, wr = wid >> 2, wc = wid & 3, fr = lane & 15, fq = lane >> 4;
;     const int K = g.K, nt = K / BK;
;     unsigned voffA[2], voffB[2];
; #pragma unroll
;     for (int i = 0; i < 2; ++i) { int R, C; stage_rc(tid * 16 + i * 8192, R, C); const int Rb = Epi::PERM ? ((R & ~31) + perm32(R & 31)) : R;
;         voffA[i] = (unsigned)(R * K + C) * 2u; voffB[i] = (unsigned)(Rb * K + C) * 2u; }
;     const size_t kstep = (size_t)(BK * 2);
;     const size_t hstep = (size_t)HALF * K * 2;
;     const size_t tstep = 2 * hstep;
;     const unsigned ldsw = (unsigned)wid * 1024u;
;     const unsigned ldsb = (unsigned)__builtin_amdgcn_readfirstlane((int)((unsigned)(size_t)lds + ldsw));
;     const int aoff = lds_byte(wr * 64 + fr, fq * 8), boff = lds_byte(wc * 32 + fr, fq * 8);
.LBB0_967:
	v_readlane_b32 s0, v255, 62
	s_mul_i32 s0, s0, 0x41000
	v_readlane_b32 s18, v252, 54
	v_readlane_b32 s1, v255, 63
	v_readlane_b32 s19, v252, 55
	s_add_u32 s0, s18, s0
	s_addc_u32 s1, s19, 0
	v_writelane_b32 v255, s0, 57
	s_add_u32 s28, s0, 0x100000
	v_writelane_b32 v255, s1, 59
	s_addc_u32 s29, s1, 0
	v_readlane_b32 s0, v255, 43
	v_readlane_b32 s1, v255, 44
	s_add_u32 s30, s0, 0x600000
	s_addc_u32 s31, s1, 0
	s_andn2_b64 vcc, exec, s[16:17]
	s_cbranch_vccnz .LBB0_1005
	s_waitcnt vmcnt(0)
	v_bfe_i32 v3, v50, 27, 1
	v_lshlrev_b32_e32 v0, 4, v50
	v_lshrrev_b32_e32 v3, 22, v3
	v_add_u32_e32 v3, v0, v3
	v_and_b32_e32 v3, 0xfffffc00, v3
	v_sub_u32_e32 v3, v0, v3
	v_ashrrev_i32_e32 v51, 31, v50
	v_lshrrev_b32_e32 v4, 4, v3
	v_lshrrev_b32_e32 v2, 26, v51
	v_bitop3_b32 v3, v4, v3, 32 bitop3:0x6c
	v_add_u32_e32 v2, v50, v2
	v_ashrrev_i32_e32 v5, 31, v3
	v_ashrrev_i32_e32 v2, 6, v2
	v_lshrrev_b32_e32 v5, 26, v5
	v_lshlrev_b32_e32 v4, 3, v2
	v_add_u32_e32 v5, v3, v5
	v_and_b32_e32 v4, -16, v4
	v_ashrrev_i32_e32 v6, 6, v5
	v_and_b32_e32 v5, 0xc0, v5
	v_add_u32_e32 v4, v6, v4
	v_sub_u32_e32 v3, v3, v5
	v_mov_b32_e32 v8, 1
	v_lshlrev_b32_e32 v2, 5, v2
	v_ashrrev_i16_sdwa v3, v8, sext(v3) dst_sel:DWORD dst_unused:UNUSED_PAD src0_sel:DWORD src1_sel:BYTE_0
	v_lshlrev_b32_e32 v5, 1, v4
	v_lshrrev_b32_e32 v7, 2, v4
	v_and_b32_e32 v6, 3, v6
	s_mov_b32 s1, 0x1fffe0
	v_and_b32_e32 v2, 32, v2
	v_bfe_i32 v3, v3, 0, 16
	v_and_b32_e32 v5, 24, v5
	v_and_b32_e32 v7, 4, v7
	v_and_or_b32 v6, v4, s1, v6
	v_or3_b32 v5, v6, v7, v5
	v_add_lshl_u32 v2, v2, v3, 1
	v_add_u32_e32 v0, 0x2000, v0
	v_lshl_add_u32 v198, v4, 11, v2
	v_lshl_add_u32 v200, v5, 11, v2
	v_ashrrev_i32_e32 v2, 31, v0
	v_lshrrev_b32_e32 v2, 22, v2
	v_add_u32_e32 v2, v0, v2
	v_ashrrev_i32_e32 v2, 10, v2
	v_mul_i32_i24_e32 v3, 0x400, v2
	v_sub_u32_e32 v0, v0, v3
	v_lshrrev_b32_e32 v3, 4, v0
	v_bitop3_b32 v0, v3, v0, 32 bitop3:0x6c
	v_ashrrev_i32_e32 v4, 31, v0
	v_lshrrev_b32_e32 v4, 26, v4
	v_lshlrev_b32_e32 v3, 3, v2
	v_add_u32_e32 v4, v0, v4
	v_and_b32_e32 v3, -16, v3
	v_ashrrev_i32_e32 v5, 6, v4
	v_add_u32_e32 v3, v5, v3
	v_and_b32_e32 v5, 3, v5
	v_and_or_b32 v5, v3, s1, v5
	s_lshl_b32 s1, s7, 10
	s_add_i32 s2, s1, 0
	s_lshl_b32 s1, s7, 8
	s_add_i32 s1, s1, 0
	s_ashr_i32 s0, s20, 8
	s_add_i32 s59, s1, 0x20400
	v_readlane_b32 s16, v252, 54
	v_readlane_b32 s17, v252, 55
	s_add_u32 s12, s16, s12
	s_addc_u32 s13, s17, s13
	s_ashr_i32 s27, s26, 31
	s_ashr_i32 s35, s34, 31
	v_and_b32_e32 v4, 0xc0, v4
	s_lshl_b64 s[16:17], s[26:27], 19
	s_lshl_b64 s[18:19], s[34:35], 19
	v_sub_u32_e32 v0, v0, v4
	s_add_u32 s60, s30, s18
	v_lshlrev_b32_e32 v2, 5, v2
	v_ashrrev_i16_sdwa v0, v8, sext(v0) dst_sel:DWORD dst_unused:UNUSED_PAD src0_sel:DWORD src1_sel:BYTE_0
	v_lshlrev_b32_e32 v4, 1, v3
	v_lshrrev_b32_e32 v6, 2, v3
	s_addc_u32 s61, s31, s19
	s_lshl_b64 s[18:19], s[26:27], 11
	v_and_b32_e32 v2, 32, v2
	v_bfe_i32 v0, v0, 0, 16
	v_and_b32_e32 v4, 24, v4
	v_and_b32_e32 v6, 4, v6
	s_add_u32 s18, s12, s18
	v_or3_b32 v4, v5, v6, v4
	v_add_lshl_u32 v0, v2, v0, 1
	s_addc_u32 s19, s13, s19
	v_lshlrev_b64 v[52:53], 2, v[50:51]
	v_lshl_add_u32 v202, v3, 11, v0
	v_lshl_add_u32 v204, v4, 11, v0
	v_pk_mov_b32 v[170:171], 0, 0
	v_pk_mov_b32 v[172:173], 0, 0
	v_pk_mov_b32 v[166:167], 0, 0
	v_pk_mov_b32 v[168:169], 0, 0
	v_pk_mov_b32 v[142:143], 0, 0
	v_pk_mov_b32 v[144:145], 0, 0
	v_pk_mov_b32 v[134:135], 0, 0
	v_pk_mov_b32 v[136:137], 0, 0
	v_pk_mov_b32 v[118:119], 0, 0
	v_pk_mov_b32 v[120:121], 0, 0
	v_pk_mov_b32 v[110:111], 0, 0
	v_pk_mov_b32 v[112:113], 0, 0
	v_pk_mov_b32 v[94:95], 0, 0
	v_pk_mov_b32 v[96:97], 0, 0
	v_pk_mov_b32 v[86:87], 0, 0
	v_pk_mov_b32 v[88:89], 0, 0
	v_pk_mov_b32 v[154:155], 0, 0
	v_pk_mov_b32 v[156:157], 0, 0
	v_pk_mov_b32 v[150:151], 0, 0
	v_pk_mov_b32 v[152:153], 0, 0
	v_pk_mov_b32 v[130:131], 0, 0
; __device__ __forceinline__ f32x4 zero4_pk() { f32x2_z a, b; asm volatile("v_pk_mov_b32 %0, 0, 0" : "=v"(a)); asm volatile("v_pk_mov_b32 %0, 0, 0" : "=v"(b)); return (f32x4){a.x, a.y, b.x, b.y}; }
; #define PG8_STAGE(bufoff, gbase, voff) do { _Pragma("unroll") for (int _i = 0; _i < 2; ++_i) \
;         glds16_asm((const char*)(gbase) + (voff)[_i], ldsb + (unsigned)((bufoff) + _i * 8192)); } while (0)
; #define PG8_WAIT_V(n) asm volatile("s_waitcnt vmcnt(" #n ")" ::: "memory")
; #define PG8_BAR __builtin_amdgcn_s_barrier()
; template <class Epi, class Sched, bool ALIGN_EPI = false, bool SP2 = false>
; __device__ __forceinline__ void gemm_phase(PG8_LAS unsigned char* lds, const Gemm g, const Sched& S, const Epi& E, int wave_u) {
;     ...
;     f32x4 acc[2][2][4][2];
; #pragma unroll
;     for (int a = 0; a < 2; ++a)
; #pragma unroll
;         for (int b = 0; b < 2; ++b)
; #pragma unroll
;             for (int m = 0; m < 4; ++m)
; #pragma unroll
;                 for (int n = 0; n < 2; ++n) acc[a][b][m][n] = zero4_pk();
;     bf16x8 At[4][2], B0[2][2], B1[2][2];
;     const char* cA = (const char*)g.A + (size_t)cur.pm * tstep; const char* cB = (const char*)g.Bt + (size_t)cur.pn * tstep;
;     S.a_ready(cur);
;     epi_prefetch(E, cur.pm, cur.pn, evb, tid);
;     if constexpr (SP2) {
;         PG8_STAGE(PG8_SB(0, 0), cB, voffB); PG8_STAGE(PG8_SB(0, 1), cB + hstep, voffB); PG8_STAGE(PG8_SA(0, 0), cA, voffA); PG8_STAGE(PG8_SA(0, 1), cA + hstep, voffA);
;         if (wr == 1) PG8_BAR;
;         PG8_WAIT_V(2); PG8_BAR;
;         PG8_STAGE(PG8_SB(1, 0), cB + kstep, voffB); PG8_STAGE(PG8_SA(1, 0), cA + kstep, voffA); PG8_STAGE(PG8_SB(1, 1), cB + hstep + kstep, voffB);
;         PG8_WAIT_V(6); PG8_BAR;
;     } else {
;         PG8_STAGE(PG8_SB(0, 0), cB, voffB); PG8_STAGE(PG8_SA(0, 0), cA, voffA); PG8_STAGE(PG8_SB(0, 1), cB + hstep, voffB); PG8_STAGE(PG8_SA(0, 1), cA + hstep, voffA);
;         if (wr == 1) PG8_BAR;
;         PG8_WAIT_V(4); PG8_BAR;
;         PG8_STAGE(PG8_SB(1, 0), cB + kstep, voffB); PG8_STAGE(PG8_SA(1, 0), cA + kstep, voffA); PG8_STAGE(PG8_SB(1, 1), cB + hstep + kstep, voffB);
;         PG8_WAIT_V(6); PG8_BAR;
	v_pk_mov_b32 v[132:133], 0, 0
	v_pk_mov_b32 v[126:127], 0, 0
	v_pk_mov_b32 v[128:129], 0, 0
	v_pk_mov_b32 v[106:107], 0, 0
	v_pk_mov_b32 v[108:109], 0, 0
	v_pk_mov_b32 v[102:103], 0, 0
	v_pk_mov_b32 v[104:105], 0, 0
	v_pk_mov_b32 v[82:83], 0, 0
	v_pk_mov_b32 v[84:85], 0, 0
	v_pk_mov_b32 v[78:79], 0, 0
	v_pk_mov_b32 v[80:81], 0, 0
	v_pk_mov_b32 v[70:71], 0, 0
	v_pk_mov_b32 v[72:73], 0, 0
	v_pk_mov_b32 v[66:67], 0, 0
	v_pk_mov_b32 v[68:69], 0, 0
	v_pk_mov_b32 v[46:47], 0, 0
	v_pk_mov_b32 v[48:49], 0, 0
	v_pk_mov_b32 v[42:43], 0, 0
	v_pk_mov_b32 v[44:45], 0, 0
	v_pk_mov_b32 v[30:31], 0, 0
	v_pk_mov_b32 v[32:33], 0, 0
	v_pk_mov_b32 v[26:27], 0, 0
	v_pk_mov_b32 v[28:29], 0, 0
	v_pk_mov_b32 v[14:15], 0, 0
	v_pk_mov_b32 v[16:17], 0, 0
	v_pk_mov_b32 v[10:11], 0, 0
	v_pk_mov_b32 v[12:13], 0, 0
	v_pk_mov_b32 v[58:59], 0, 0
	v_pk_mov_b32 v[60:61], 0, 0
	v_pk_mov_b32 v[54:55], 0, 0
	v_pk_mov_b32 v[56:57], 0, 0
	v_pk_mov_b32 v[38:39], 0, 0
	v_pk_mov_b32 v[40:41], 0, 0
	v_pk_mov_b32 v[34:35], 0, 0
	v_pk_mov_b32 v[36:37], 0, 0
	v_pk_mov_b32 v[22:23], 0, 0
	v_pk_mov_b32 v[24:25], 0, 0
	v_pk_mov_b32 v[18:19], 0, 0
	v_pk_mov_b32 v[20:21], 0, 0
	v_pk_mov_b32 v[6:7], 0, 0
	v_pk_mov_b32 v[8:9], 0, 0
	v_pk_mov_b32 v[2:3], 0, 0
	v_pk_mov_b32 v[4:5], 0, 0
	v_lshl_add_u64 v[62:63], s[18:19], 0, v[52:53]
	s_mov_b32 s18, m0
	s_mov_b32 m0, s59
	s_nop 0
	global_load_lds_dword v[62:63], off
	s_mov_b32 m0, s18
	s_add_u32 s14, s14, 0xfffffc00
	s_movk_i32 s18, 0x100
	s_addc_u32 s15, s15, -1
	v_cmp_gt_i32_e32 vcc, s18, v50
	v_mov_b32_e32 v0, s15
	v_mov_b32_e32 v51, s11
	v_cndmask_b32_e32 v63, v0, v51, vcc
	v_mov_b32_e32 v0, s14
	v_mov_b32_e32 v51, s10
	s_lshl_b32 s10, s34, 8
	v_cndmask_b32_e32 v62, v0, v51, vcc
	s_ashr_i32 s11, s10, 31
	v_lshl_add_u64 v[64:65], s[10:11], 2, v[62:63]
	v_lshl_add_u64 v[64:65], v[64:65], 0, v[52:53]
	s_add_i32 s1, s1, 0x20c00
	s_mov_b32 s10, m0
	s_mov_b32 m0, s1
	s_nop 0
	global_load_lds_dword v[64:65], off
	s_mov_b32 m0, s10
	s_add_i32 s35, s2, 0x10000
	v_mov_b32_e32 v201, v1
	s_add_i32 s62, s2, 0x12000
	v_lshl_add_u64 v[64:65], s[60:61], 0, v[200:201]
	v_mov_b32_e32 v205, v1
	s_add_u32 s10, s60, 0x40000
	s_mov_b32 s1, m0
	s_mov_b32 m0, s35
	s_nop 0
	global_load_lds_dwordx4 v[64:65], off
	s_mov_b32 m0, s1
	v_lshl_add_u64 v[64:65], s[60:61], 0, v[204:205]
	s_addc_u32 s11, s61, 0
	s_mov_b32 s1, m0
	s_mov_b32 m0, s62
	s_nop 0
	global_load_lds_dwordx4 v[64:65], off
	s_mov_b32 m0, s1
	v_lshl_add_u64 v[64:65], s[10:11], 0, v[200:201]
	s_add_i32 s63, s2, 0x14000
	s_mov_b32 s1, m0
	s_mov_b32 m0, s63
	s_nop 0
	global_load_lds_dwordx4 v[64:65], off
	s_mov_b32 m0, s1
	v_lshl_add_u64 v[64:65], s[10:11], 0, v[204:205]
	s_add_i32 s86, s2, 0x16000
	v_readlane_b32 s10, v250, 11
	v_readlane_b32 s11, v250, 12
	s_add_u32 s64, s10, s16
	s_mov_b32 s1, m0
	s_mov_b32 m0, s86
	s_nop 0
	global_load_lds_dwordx4 v[64:65], off
	s_mov_b32 m0, s1
	s_addc_u32 s65, s11, s17
	v_mov_b32_e32 v199, v1
	s_add_i32 s87, s2, 0x2000
	v_lshl_add_u64 v[64:65], s[64:65], 0, v[198:199]
	s_mov_b32 s1, m0
	s_mov_b32 m0, s2
	s_nop 0
	global_load_lds_dwordx4 v[64:65], off
	s_mov_b32 m0, s1
	v_mov_b32_e32 v203, v1
	s_add_u32 s10, s64, 0x40000
	v_lshl_add_u64 v[64:65], s[64:65], 0, v[202:203]
	s_mov_b32 s1, m0
	s_mov_b32 m0, s87
	s_nop 0
	global_load_lds_dwordx4 v[64:65], off
	s_mov_b32 m0, s1
	s_addc_u32 s11, s65, 0
	s_add_i32 s88, s2, 0x4000
	v_lshl_add_u64 v[64:65], s[10:11], 0, v[198:199]
	s_mov_b32 s1, m0
	s_mov_b32 m0, s88
	s_nop 0
	global_load_lds_dwordx4 v[64:65], off
	s_mov_b32 m0, s1
	v_lshl_add_u64 v[64:65], s[10:11], 0, v[202:203]
	s_add_i32 s89, s2, 0x6000
	s_mov_b32 s1, m0
	s_mov_b32 m0, s89
	s_nop 0
	global_load_lds_dwordx4 v[64:65], off
	s_mov_b32 m0, s1
	s_cmp_eq_u32 s0, 1
	v_mov_b32_e32 v215, 1
	s_cselect_b64 s[14:15], -1, 0
	s_cmp_lg_u32 s0, 1
	s_cbranch_scc1 .LBB0_970
	s_setprio 1
	s_barrier

; #define PG8_STAGE(bufoff, gbase, voff) do { _Pragma("unroll") for (int _i = 0; _i < 2; ++_i) \
;         glds16_asm((const char*)(gbase) + (voff)[_i], ldsb + (unsigned)((bufoff) + _i * 8192)); } while (0)
; #define PG8_LDA(dst, b, h) do { _Pragma("unroll") for (int m = 0; m < 4; ++m) _Pragma("unroll") for (int k = 0; k < 2; ++k) dst[m][k] = *(const PG8_LAS bf16x8*)(lds + PG8_SA(b, h) + aoff + m * 2048 + k * 1024); } while (0)
; #define PG8_LDB(dst, b, h) do { _Pragma("unroll") for (int n = 0; n < 2; ++n) _Pragma("unroll") for (int k = 0; k < 2; ++k) dst[n][k] = *(const PG8_LAS bf16x8*)(lds + PG8_SB(b, h) + boff + n * 2048 + k * 1024); } while (0)
; #define PG8_MMA(ai, bj, At, Bt) do { __builtin_amdgcn_s_setprio(1); _Pragma("unroll") for (int m = 0; m < 4; ++m) _Pragma("unroll") for (int n = 0; n < 2; ++n) _Pragma("unroll") for (int k = 0; k < 2; ++k) \
;         acc[ai][bj][m][n] = __builtin_amdgcn_mfma_f32_16x16x32_bf16(Bt[n][k], At[m][k], acc[ai][bj][m][n], 0, 0, 0); __builtin_amdgcn_s_setprio(0); } while (0)
; #define PG8_WAIT_V(n) asm volatile("s_waitcnt vmcnt(" #n ")" ::: "memory")
; #define PG8_BAR __builtin_amdgcn_s_barrier()
; template <class Epi, class Sched, bool ALIGN_EPI = false, bool SP2 = false>
; __device__ __forceinline__ void gemm_phase(PG8_LAS unsigned char* lds, const Gemm g, const Sched& S, const Epi& E, int wave_u) {
;     ...
;             PG8_LDB(B0, 0, 0); PG8_LDB(B1, 0, 1); PG8_SCHED; PG8_LDA(At, 0, 0); PG8_STAGE(PG8_SA(1, 1), a1 + hstep, voffA);
;             PG8_WAIT_V(8); PG8_WAIT_L(0); PG8_BAR; PG8_MMA(0, 0, At, B0); PG8_MMA(0, 1, At, B1); PG8_BAR; PG8_SCHED;
;             PG8_LDA(At, 0, 1); PG8_STAGE(PG8_SB(0, 0), b2, voffB); PG8_STAGE(PG8_SB(0, 1), b2 + hstep, voffB); PG8_STAGE(PG8_SA(0, 0), a2, voffA);
;             PG8_WAIT_V(8); PG8_WAIT_L(0); PG8_BAR; PG8_MMA(1, 0, At, B0); PG8_MMA(1, 1, At, B1); PG8_BAR; PG8_SCHED;
;             PG8_LDB(B0, 1, 0); PG8_LDB(B1, 1, 1); PG8_SCHED; PG8_LDA(At, 1, 0); PG8_STAGE(PG8_SA(0, 1), a2 + hstep, voffA);
;             PG8_WAIT_V(8); PG8_WAIT_L(0); PG8_BAR; PG8_MMA(0, 0, At, B0); PG8_MMA(0, 1, At, B1); PG8_BAR; PG8_SCHED;
;             PG8_LDA(At, 1, 1); PG8_STAGE(PG8_SB(1, 0), b3, voffB); PG8_STAGE(PG8_SB(1, 1), b3 + hstep, voffB); PG8_STAGE(PG8_SA(1, 0), a3, voffA);
;             PG8_WAIT_V(8); PG8_WAIT_L(0); PG8_BAR; PG8_MMA(1, 0, At, B0); PG8_MMA(1, 1, At, B1); PG8_BAR; PG8_SCHED;
.LBB0_980:
	v_add_u32_e32 v0, 0x10000, v227
	ds_read_b128 v[62:65], v0
	ds_read_b128 v[74:77], v0 offset:1024
	ds_read_b128 v[90:93], v0 offset:2048
	ds_read_b128 v[98:101], v0 offset:3072
	v_add_u32_e32 v0, 0x14000, v227
	s_add_u32 s1, s64, 0xfffc0080
	ds_read_b128 v[114:117], v0
	ds_read_b128 v[122:125], v0 offset:1024
	ds_read_b128 v[138:141], v0 offset:2048
	ds_read_b128 v[146:149], v0 offset:3072
	s_addc_u32 s46, s65, -1
	s_and_b64 s[44:45], s[44:45], exec
	s_cselect_b32 s56, s53, s1
	s_cselect_b32 s57, s52, s46
	s_cselect_b32 s45, s19, s61
	s_cselect_b32 s44, s96, s60
	s_add_u32 s46, s56, 0x80
	s_addc_u32 s47, s57, 0
	s_add_u32 s48, s44, 0x80
	s_addc_u32 s49, s45, 0
	ds_read_b128 v[158:161], v228
	ds_read_b128 v[162:165], v228 offset:1024
	ds_read_b128 v[174:177], v228 offset:2048
	ds_read_b128 v[178:181], v228 offset:3072
	ds_read_b128 v[182:185], v228 offset:4096
	ds_read_b128 v[186:189], v228 offset:5120
	ds_read_b128 v[210:213], v228 offset:6144
	ds_read_b128 v[230:233], v228 offset:7168
	v_lshl_add_u64 v[234:235], s[64:65], 0, v[198:199]
	s_mov_b32 s1, m0
	s_mov_b32 m0, s7
	s_nop 0
	global_load_lds_dwordx4 v[234:235], off
	s_mov_b32 m0, s1
	v_lshl_add_u64 v[234:235], s[64:65], 0, v[202:203]
	s_mov_b32 s1, m0
	s_mov_b32 m0, s75
	s_nop 0
	global_load_lds_dwordx4 v[234:235], off
	s_mov_b32 m0, s1
	s_waitcnt vmcnt(8)
	s_waitcnt lgkmcnt(0)
	s_barrier
	s_waitcnt lgkmcnt(7)
	v_mfma_f32_16x16x32_bf16 v[170:173], v[62:65], v[158:161], v[170:173]
	v_mfma_f32_16x16x32_bf16 v[166:169], v[90:93], v[158:161], v[166:169]
	s_waitcnt lgkmcnt(5)
	v_mfma_f32_16x16x32_bf16 v[142:145], v[62:65], v[174:177], v[142:145]
	v_mfma_f32_16x16x32_bf16 v[134:137], v[90:93], v[174:177], v[134:137]
	s_waitcnt lgkmcnt(3)
	v_mfma_f32_16x16x32_bf16 v[118:121], v[62:65], v[182:185], v[118:121]
	v_mfma_f32_16x16x32_bf16 v[110:113], v[90:93], v[182:185], v[110:113]
	s_waitcnt lgkmcnt(1)
	v_mfma_f32_16x16x32_bf16 v[94:97], v[62:65], v[210:213], v[94:97]
	v_mfma_f32_16x16x32_bf16 v[86:89], v[90:93], v[210:213], v[86:89]
	v_mfma_f32_16x16x32_bf16 v[170:173], v[74:77], v[162:165], v[170:173]
	v_mfma_f32_16x16x32_bf16 v[166:169], v[98:101], v[162:165], v[166:169]
	v_mfma_f32_16x16x32_bf16 v[142:145], v[74:77], v[178:181], v[142:145]
	v_mfma_f32_16x16x32_bf16 v[134:137], v[98:101], v[178:181], v[134:137]
	v_mfma_f32_16x16x32_bf16 v[118:121], v[74:77], v[186:189], v[118:121]
	v_mfma_f32_16x16x32_bf16 v[110:113], v[98:101], v[186:189], v[110:113]
	s_waitcnt lgkmcnt(0)
	v_mfma_f32_16x16x32_bf16 v[94:97], v[74:77], v[230:233], v[94:97]
	v_mfma_f32_16x16x32_bf16 v[86:89], v[98:101], v[230:233], v[86:89]
	v_mfma_f32_16x16x32_bf16 v[154:157], v[114:117], v[158:161], v[154:157]
	v_mfma_f32_16x16x32_bf16 v[150:153], v[138:141], v[158:161], v[150:153]
	v_mfma_f32_16x16x32_bf16 v[130:133], v[114:117], v[174:177], v[130:133]
	v_mfma_f32_16x16x32_bf16 v[126:129], v[138:141], v[174:177], v[126:129]
	v_mfma_f32_16x16x32_bf16 v[106:109], v[114:117], v[182:185], v[106:109]
	v_mfma_f32_16x16x32_bf16 v[102:105], v[138:141], v[182:185], v[102:105]
	v_mfma_f32_16x16x32_bf16 v[82:85], v[114:117], v[210:213], v[82:85]
	v_mfma_f32_16x16x32_bf16 v[78:81], v[138:141], v[210:213], v[78:81]
	v_mfma_f32_16x16x32_bf16 v[154:157], v[122:125], v[162:165], v[154:157]
	v_mfma_f32_16x16x32_bf16 v[150:153], v[146:149], v[162:165], v[150:153]
	v_mfma_f32_16x16x32_bf16 v[130:133], v[122:125], v[178:181], v[130:133]
	v_mfma_f32_16x16x32_bf16 v[126:129], v[146:149], v[178:181], v[126:129]
	v_mfma_f32_16x16x32_bf16 v[106:109], v[122:125], v[186:189], v[106:109]
	v_mfma_f32_16x16x32_bf16 v[102:105], v[146:149], v[186:189], v[102:105]
	v_mfma_f32_16x16x32_bf16 v[82:85], v[122:125], v[230:233], v[82:85]
	v_mfma_f32_16x16x32_bf16 v[78:81], v[146:149], v[230:233], v[78:81]
	s_barrier
	ds_read_b128 v[158:161], v228 offset:16384
	ds_read_b128 v[162:165], v228 offset:17408
	ds_read_b128 v[174:177], v228 offset:18432
	ds_read_b128 v[178:181], v228 offset:19456
	ds_read_b128 v[182:185], v228 offset:20480
	ds_read_b128 v[186:189], v228 offset:21504
	ds_read_b128 v[210:213], v228 offset:22528
	ds_read_b128 v[230:233], v228 offset:23552
	v_lshl_add_u64 v[234:235], s[44:45], 0, v[200:201]
	s_mov_b32 s1, m0
	s_mov_b32 m0, s35
	s_nop 0
	global_load_lds_dwordx4 v[234:235], off
	s_mov_b32 m0, s1
	s_add_u32 vcc_lo, s44, 0x40000
	v_lshl_add_u64 v[234:235], s[44:45], 0, v[204:205]
	s_mov_b32 s1, m0
	s_mov_b32 m0, s62
	s_nop 0
	global_load_lds_dwordx4 v[234:235], off
	s_mov_b32 m0, s1
	s_addc_u32 vcc_hi, s45, 0
	v_lshl_add_u64 v[234:235], vcc, 0, v[200:201]
	s_mov_b32 s1, m0
	s_mov_b32 m0, s63
	s_nop 0
	global_load_lds_dwordx4 v[234:235], off
	s_mov_b32 m0, s1
	v_lshl_add_u64 v[234:235], vcc, 0, v[204:205]
	s_mov_b32 s1, m0
	s_mov_b32 m0, s86
	s_nop 0
	global_load_lds_dwordx4 v[234:235], off
	s_mov_b32 m0, s1
	v_lshl_add_u64 v[234:235], s[56:57], 0, v[198:199]
	s_mov_b32 s1, m0
	s_mov_b32 m0, s2
	s_nop 0
	global_load_lds_dwordx4 v[234:235], off
	s_mov_b32 m0, s1
	v_lshl_add_u64 v[234:235], s[56:57], 0, v[202:203]
	s_mov_b32 s1, m0
	s_mov_b32 m0, s87
	s_nop 0
	global_load_lds_dwordx4 v[234:235], off
	s_mov_b32 m0, s1
	s_waitcnt vmcnt(8)
	s_waitcnt lgkmcnt(0)
	s_barrier
; #define PG8_STAGE(bufoff, gbase, voff) do { _Pragma("unroll") for (int _i = 0; _i < 2; ++_i) \
;         glds16_asm((const char*)(gbase) + (voff)[_i], ldsb + (unsigned)((bufoff) + _i * 8192)); } while (0)
; #define PG8_LDA(dst, b, h) do { _Pragma("unroll") for (int m = 0; m < 4; ++m) _Pragma("unroll") for (int k = 0; k < 2; ++k) dst[m][k] = *(const PG8_LAS bf16x8*)(lds + PG8_SA(b, h) + aoff + m * 2048 + k * 1024); } while (0)
; #define PG8_LDB(dst, b, h) do { _Pragma("unroll") for (int n = 0; n < 2; ++n) _Pragma("unroll") for (int k = 0; k < 2; ++k) dst[n][k] = *(const PG8_LAS bf16x8*)(lds + PG8_SB(b, h) + boff + n * 2048 + k * 1024); } while (0)
; #define PG8_MMA(ai, bj, At, Bt) do { __builtin_amdgcn_s_setprio(1); _Pragma("unroll") for (int m = 0; m < 4; ++m) _Pragma("unroll") for (int n = 0; n < 2; ++n) _Pragma("unroll") for (int k = 0; k < 2; ++k) \
;         acc[ai][bj][m][n] = __builtin_amdgcn_mfma_f32_16x16x32_bf16(Bt[n][k], At[m][k], acc[ai][bj][m][n], 0, 0, 0); __builtin_amdgcn_s_setprio(0); } while (0)
; #define PG8_WAIT_V(n) asm volatile("s_waitcnt vmcnt(" #n ")" ::: "memory")
; #define PG8_BAR __builtin_amdgcn_s_barrier()
; template <class Epi, class Sched, bool ALIGN_EPI = false, bool SP2 = false>
; __device__ __forceinline__ void gemm_phase(PG8_LAS unsigned char* lds, const Gemm g, const Sched& S, const Epi& E, int wave_u) {
;     ...
;             PG8_LDB(B0, 0, 0); PG8_LDB(B1, 0, 1); PG8_SCHED; PG8_LDA(At, 0, 0); PG8_STAGE(PG8_SA(1, 1), a1 + hstep, voffA);
;             PG8_WAIT_V(8); PG8_WAIT_L(0); PG8_BAR; PG8_MMA(0, 0, At, B0); PG8_MMA(0, 1, At, B1); PG8_BAR; PG8_SCHED;
;             PG8_LDA(At, 0, 1); PG8_STAGE(PG8_SB(0, 0), b2, voffB); PG8_STAGE(PG8_SB(0, 1), b2 + hstep, voffB); PG8_STAGE(PG8_SA(0, 0), a2, voffA);
;             PG8_WAIT_V(8); PG8_WAIT_L(0); PG8_BAR; PG8_MMA(1, 0, At, B0); PG8_MMA(1, 1, At, B1); PG8_BAR; PG8_SCHED;
;             PG8_LDB(B0, 1, 0); PG8_LDB(B1, 1, 1); PG8_SCHED; PG8_LDA(At, 1, 0); PG8_STAGE(PG8_SA(0, 1), a2 + hstep, voffA);
;             PG8_WAIT_V(8); PG8_WAIT_L(0); PG8_BAR; PG8_MMA(0, 0, At, B0); PG8_MMA(0, 1, At, B1); PG8_BAR; PG8_SCHED;
;             PG8_LDA(At, 1, 1); PG8_STAGE(PG8_SB(1, 0), b3, voffB); PG8_STAGE(PG8_SB(1, 1), b3 + hstep, voffB); PG8_STAGE(PG8_SA(1, 0), a3, voffA);
;             PG8_WAIT_V(8); PG8_WAIT_L(0); PG8_BAR; PG8_MMA(1, 0, At, B0); PG8_MMA(1, 1, At, B1); PG8_BAR; PG8_SCHED;
	s_waitcnt lgkmcnt(7)
	v_mfma_f32_16x16x32_bf16 v[70:73], v[62:65], v[158:161], v[70:73]
	v_mfma_f32_16x16x32_bf16 v[66:69], v[90:93], v[158:161], v[66:69]
	s_waitcnt lgkmcnt(5)
	v_mfma_f32_16x16x32_bf16 v[46:49], v[62:65], v[174:177], v[46:49]
	v_mfma_f32_16x16x32_bf16 v[42:45], v[90:93], v[174:177], v[42:45]
	s_waitcnt lgkmcnt(3)
	v_mfma_f32_16x16x32_bf16 v[30:33], v[62:65], v[182:185], v[30:33]
	v_mfma_f32_16x16x32_bf16 v[26:29], v[90:93], v[182:185], v[26:29]
	s_waitcnt lgkmcnt(1)
	v_mfma_f32_16x16x32_bf16 v[14:17], v[62:65], v[210:213], v[14:17]
	v_mfma_f32_16x16x32_bf16 v[10:13], v[90:93], v[210:213], v[10:13]
	v_mfma_f32_16x16x32_bf16 v[70:73], v[74:77], v[162:165], v[70:73]
	v_mfma_f32_16x16x32_bf16 v[66:69], v[98:101], v[162:165], v[66:69]
	v_mfma_f32_16x16x32_bf16 v[46:49], v[74:77], v[178:181], v[46:49]
	v_mfma_f32_16x16x32_bf16 v[42:45], v[98:101], v[178:181], v[42:45]
	v_mfma_f32_16x16x32_bf16 v[30:33], v[74:77], v[186:189], v[30:33]
	v_mfma_f32_16x16x32_bf16 v[26:29], v[98:101], v[186:189], v[26:29]
	s_waitcnt lgkmcnt(0)
	v_mfma_f32_16x16x32_bf16 v[14:17], v[74:77], v[230:233], v[14:17]
	v_mfma_f32_16x16x32_bf16 v[10:13], v[98:101], v[230:233], v[10:13]
	v_mfma_f32_16x16x32_bf16 v[58:61], v[114:117], v[158:161], v[58:61]
	v_mfma_f32_16x16x32_bf16 v[54:57], v[138:141], v[158:161], v[54:57]
	v_mfma_f32_16x16x32_bf16 v[38:41], v[114:117], v[174:177], v[38:41]
	v_mfma_f32_16x16x32_bf16 v[34:37], v[138:141], v[174:177], v[34:37]
	v_mfma_f32_16x16x32_bf16 v[22:25], v[114:117], v[182:185], v[22:25]
	v_mfma_f32_16x16x32_bf16 v[18:21], v[138:141], v[182:185], v[18:21]
	v_mfma_f32_16x16x32_bf16 v[6:9], v[114:117], v[210:213], v[6:9]
	v_mfma_f32_16x16x32_bf16 v[2:5], v[138:141], v[210:213], v[2:5]
	v_mfma_f32_16x16x32_bf16 v[58:61], v[122:125], v[162:165], v[58:61]
	v_mfma_f32_16x16x32_bf16 v[54:57], v[146:149], v[162:165], v[54:57]
	v_mfma_f32_16x16x32_bf16 v[38:41], v[122:125], v[178:181], v[38:41]
	v_mfma_f32_16x16x32_bf16 v[34:37], v[146:149], v[178:181], v[34:37]
	v_mfma_f32_16x16x32_bf16 v[22:25], v[122:125], v[186:189], v[22:25]
	v_mfma_f32_16x16x32_bf16 v[18:21], v[146:149], v[186:189], v[18:21]
	v_mfma_f32_16x16x32_bf16 v[6:9], v[122:125], v[230:233], v[6:9]
	v_mfma_f32_16x16x32_bf16 v[2:5], v[146:149], v[230:233], v[2:5]
	s_barrier
	v_add_u32_e32 v0, 0x18000, v227
	ds_read_b128 v[62:65], v0
	ds_read_b128 v[74:77], v0 offset:1024
	ds_read_b128 v[90:93], v0 offset:2048
	ds_read_b128 v[98:101], v0 offset:3072
	v_add_u32_e32 v0, 0x1c000, v227
	ds_read_b128 v[114:117], v0
	ds_read_b128 v[122:125], v0 offset:1024
	ds_read_b128 v[138:141], v0 offset:2048
	ds_read_b128 v[146:149], v0 offset:3072
	ds_read_b128 v[158:161], v228 offset:32768
	ds_read_b128 v[162:165], v228 offset:33792
	ds_read_b128 v[174:177], v228 offset:34816
	ds_read_b128 v[178:181], v228 offset:35840
	ds_read_b128 v[182:185], v228 offset:36864
	ds_read_b128 v[186:189], v228 offset:37888
	ds_read_b128 v[210:213], v228 offset:38912
	ds_read_b128 v[230:233], v228 offset:39936
	s_add_u32 s56, s56, 0x40000
	s_addc_u32 s57, s57, 0
	v_lshl_add_u64 v[234:235], s[56:57], 0, v[198:199]
	s_mov_b32 s1, m0
	s_mov_b32 m0, s88
	s_nop 0
	global_load_lds_dwordx4 v[234:235], off
	s_mov_b32 m0, s1
	v_lshl_add_u64 v[234:235], s[56:57], 0, v[202:203]
	s_mov_b32 s1, m0
	s_mov_b32 m0, s89
	s_nop 0
	global_load_lds_dwordx4 v[234:235], off
	s_mov_b32 m0, s1
	s_waitcnt vmcnt(8)
	s_waitcnt lgkmcnt(0)
	s_barrier
	s_waitcnt lgkmcnt(7)
	v_mfma_f32_16x16x32_bf16 v[170:173], v[62:65], v[158:161], v[170:173]
	v_mfma_f32_16x16x32_bf16 v[166:169], v[90:93], v[158:161], v[166:169]
	s_waitcnt lgkmcnt(5)
	v_mfma_f32_16x16x32_bf16 v[142:145], v[62:65], v[174:177], v[142:145]
	v_mfma_f32_16x16x32_bf16 v[134:137], v[90:93], v[174:177], v[134:137]
	s_waitcnt lgkmcnt(3)
	v_mfma_f32_16x16x32_bf16 v[118:121], v[62:65], v[182:185], v[118:121]
	v_mfma_f32_16x16x32_bf16 v[110:113], v[90:93], v[182:185], v[110:113]
	s_waitcnt lgkmcnt(1)
	v_mfma_f32_16x16x32_bf16 v[94:97], v[62:65], v[210:213], v[94:97]
	v_mfma_f32_16x16x32_bf16 v[86:89], v[90:93], v[210:213], v[86:89]
	v_mfma_f32_16x16x32_bf16 v[170:173], v[74:77], v[162:165], v[170:173]
	v_mfma_f32_16x16x32_bf16 v[166:169], v[98:101], v[162:165], v[166:169]
	v_mfma_f32_16x16x32_bf16 v[142:145], v[74:77], v[178:181], v[142:145]
	v_mfma_f32_16x16x32_bf16 v[134:137], v[98:101], v[178:181], v[134:137]
	v_mfma_f32_16x16x32_bf16 v[118:121], v[74:77], v[186:189], v[118:121]
	v_mfma_f32_16x16x32_bf16 v[110:113], v[98:101], v[186:189], v[110:113]
	s_waitcnt lgkmcnt(0)
	v_mfma_f32_16x16x32_bf16 v[94:97], v[74:77], v[230:233], v[94:97]
	v_mfma_f32_16x16x32_bf16 v[86:89], v[98:101], v[230:233], v[86:89]
	v_mfma_f32_16x16x32_bf16 v[154:157], v[114:117], v[158:161], v[154:157]
	v_mfma_f32_16x16x32_bf16 v[150:153], v[138:141], v[158:161], v[150:153]
	v_mfma_f32_16x16x32_bf16 v[130:133], v[114:117], v[174:177], v[130:133]
	v_mfma_f32_16x16x32_bf16 v[126:129], v[138:141], v[174:177], v[126:129]
	v_mfma_f32_16x16x32_bf16 v[106:109], v[114:117], v[182:185], v[106:109]
	v_mfma_f32_16x16x32_bf16 v[102:105], v[138:141], v[182:185], v[102:105]
	v_mfma_f32_16x16x32_bf16 v[82:85], v[114:117], v[210:213], v[82:85]
	v_mfma_f32_16x16x32_bf16 v[78:81], v[138:141], v[210:213], v[78:81]
	v_mfma_f32_16x16x32_bf16 v[154:157], v[122:125], v[162:165], v[154:157]
	v_mfma_f32_16x16x32_bf16 v[150:153], v[146:149], v[162:165], v[150:153]
	v_mfma_f32_16x16x32_bf16 v[130:133], v[122:125], v[178:181], v[130:133]
	v_mfma_f32_16x16x32_bf16 v[126:129], v[146:149], v[178:181], v[126:129]
	v_mfma_f32_16x16x32_bf16 v[106:109], v[122:125], v[186:189], v[106:109]
	v_mfma_f32_16x16x32_bf16 v[102:105], v[146:149], v[186:189], v[102:105]
	v_mfma_f32_16x16x32_bf16 v[82:85], v[122:125], v[230:233], v[82:85]
	v_mfma_f32_16x16x32_bf16 v[78:81], v[146:149], v[230:233], v[78:81]
	s_barrier
; #define PG8_STAGE(bufoff, gbase, voff) do { _Pragma("unroll") for (int _i = 0; _i < 2; ++_i) \
;         glds16_asm((const char*)(gbase) + (voff)[_i], ldsb + (unsigned)((bufoff) + _i * 8192)); } while (0)
; #define PG8_LDA(dst, b, h) do { _Pragma("unroll") for (int m = 0; m < 4; ++m) _Pragma("unroll") for (int k = 0; k < 2; ++k) dst[m][k] = *(const PG8_LAS bf16x8*)(lds + PG8_SA(b, h) + aoff + m * 2048 + k * 1024); } while (0)
; #define PG8_LDB(dst, b, h) do { _Pragma("unroll") for (int n = 0; n < 2; ++n) _Pragma("unroll") for (int k = 0; k < 2; ++k) dst[n][k] = *(const PG8_LAS bf16x8*)(lds + PG8_SB(b, h) + boff + n * 2048 + k * 1024); } while (0)
; #define PG8_MMA(ai, bj, At, Bt) do { __builtin_amdgcn_s_setprio(1); _Pragma("unroll") for (int m = 0; m < 4; ++m) _Pragma("unroll") for (int n = 0; n < 2; ++n) _Pragma("unroll") for (int k = 0; k < 2; ++k) \
;         acc[ai][bj][m][n] = __builtin_amdgcn_mfma_f32_16x16x32_bf16(Bt[n][k], At[m][k], acc[ai][bj][m][n], 0, 0, 0); __builtin_amdgcn_s_setprio(0); } while (0)
; #define PG8_WAIT_V(n) asm volatile("s_waitcnt vmcnt(" #n ")" ::: "memory")
; #define PG8_BAR __builtin_amdgcn_s_barrier()
; template <class Epi, class Sched, bool ALIGN_EPI = false, bool SP2 = false>
; __device__ __forceinline__ void gemm_phase(PG8_LAS unsigned char* lds, const Gemm g, const Sched& S, const Epi& E, int wave_u) {
;     ...
;             PG8_LDB(B0, 0, 0); PG8_LDB(B1, 0, 1); PG8_SCHED; PG8_LDA(At, 0, 0); PG8_STAGE(PG8_SA(1, 1), a1 + hstep, voffA);
;             PG8_WAIT_V(8); PG8_WAIT_L(0); PG8_BAR; PG8_MMA(0, 0, At, B0); PG8_MMA(0, 1, At, B1); PG8_BAR; PG8_SCHED;
;             PG8_LDA(At, 0, 1); PG8_STAGE(PG8_SB(0, 0), b2, voffB); PG8_STAGE(PG8_SB(0, 1), b2 + hstep, voffB); PG8_STAGE(PG8_SA(0, 0), a2, voffA);
;             PG8_WAIT_V(8); PG8_WAIT_L(0); PG8_BAR; PG8_MMA(1, 0, At, B0); PG8_MMA(1, 1, At, B1); PG8_BAR; PG8_SCHED;
;             PG8_LDB(B0, 1, 0); PG8_LDB(B1, 1, 1); PG8_SCHED; PG8_LDA(At, 1, 0); PG8_STAGE(PG8_SA(0, 1), a2 + hstep, voffA);
;             PG8_WAIT_V(8); PG8_WAIT_L(0); PG8_BAR; PG8_MMA(0, 0, At, B0); PG8_MMA(0, 1, At, B1); PG8_BAR; PG8_SCHED;
;             PG8_LDA(At, 1, 1); PG8_STAGE(PG8_SB(1, 0), b3, voffB); PG8_STAGE(PG8_SB(1, 1), b3 + hstep, voffB); PG8_STAGE(PG8_SA(1, 0), a3, voffA);
;             PG8_WAIT_V(8); PG8_WAIT_L(0); PG8_BAR; PG8_MMA(1, 0, At, B0); PG8_MMA(1, 1, At, B1); PG8_BAR; PG8_SCHED;
	ds_read_b128 v[158:161], v228 offset:49152
	ds_read_b128 v[162:165], v228 offset:50176
	ds_read_b128 v[174:177], v228 offset:51200
	ds_read_b128 v[178:181], v228 offset:52224
	ds_read_b128 v[182:185], v228 offset:53248
	ds_read_b128 v[186:189], v228 offset:54272
	ds_read_b128 v[210:213], v228 offset:55296
	ds_read_b128 v[230:233], v228 offset:56320
	v_lshl_add_u64 v[234:235], s[48:49], 0, v[200:201]
	s_mov_b32 s1, m0
	s_mov_b32 m0, s90
	s_nop 0
	global_load_lds_dwordx4 v[234:235], off
	s_mov_b32 m0, s1
	s_add_u32 s44, s44, 0x40080
	v_lshl_add_u64 v[234:235], s[48:49], 0, v[204:205]
	s_mov_b32 s1, m0
	s_mov_b32 m0, s91
	s_nop 0
	global_load_lds_dwordx4 v[234:235], off
	s_mov_b32 m0, s1
	s_addc_u32 s45, s45, 0
	v_lshl_add_u64 v[234:235], s[44:45], 0, v[200:201]
	s_mov_b32 s1, m0
	s_mov_b32 m0, s66
	s_nop 0
	global_load_lds_dwordx4 v[234:235], off
	s_mov_b32 m0, s1
	v_lshl_add_u64 v[234:235], s[44:45], 0, v[204:205]
	s_mov_b32 s1, m0
	s_mov_b32 m0, s67
	s_nop 0
	global_load_lds_dwordx4 v[234:235], off
	s_mov_b32 m0, s1
	v_lshl_add_u64 v[234:235], s[46:47], 0, v[198:199]
	s_mov_b32 s1, m0
	s_mov_b32 m0, s40
	s_nop 0
	global_load_lds_dwordx4 v[234:235], off
	s_mov_b32 m0, s1
	v_lshl_add_u64 v[234:235], s[46:47], 0, v[202:203]
	s_mov_b32 s1, m0
	s_mov_b32 m0, s41
	s_nop 0
	global_load_lds_dwordx4 v[234:235], off
	s_mov_b32 m0, s1
	s_waitcnt vmcnt(8)
	s_waitcnt lgkmcnt(0)
	s_barrier
	s_waitcnt lgkmcnt(7)
	v_mfma_f32_16x16x32_bf16 v[70:73], v[62:65], v[158:161], v[70:73]
	v_mfma_f32_16x16x32_bf16 v[66:69], v[90:93], v[158:161], v[66:69]
	s_waitcnt lgkmcnt(5)
	v_mfma_f32_16x16x32_bf16 v[46:49], v[62:65], v[174:177], v[46:49]
	v_mfma_f32_16x16x32_bf16 v[42:45], v[90:93], v[174:177], v[42:45]
	s_waitcnt lgkmcnt(3)
	v_mfma_f32_16x16x32_bf16 v[30:33], v[62:65], v[182:185], v[30:33]
	v_mfma_f32_16x16x32_bf16 v[26:29], v[90:93], v[182:185], v[26:29]
	s_waitcnt lgkmcnt(1)
	v_mfma_f32_16x16x32_bf16 v[14:17], v[62:65], v[210:213], v[14:17]
	v_mfma_f32_16x16x32_bf16 v[10:13], v[90:93], v[210:213], v[10:13]
	v_mfma_f32_16x16x32_bf16 v[70:73], v[74:77], v[162:165], v[70:73]
	v_mfma_f32_16x16x32_bf16 v[66:69], v[98:101], v[162:165], v[66:69]
	v_mfma_f32_16x16x32_bf16 v[46:49], v[74:77], v[178:181], v[46:49]
	v_mfma_f32_16x16x32_bf16 v[42:45], v[98:101], v[178:181], v[42:45]
	v_mfma_f32_16x16x32_bf16 v[30:33], v[74:77], v[186:189], v[30:33]
	v_mfma_f32_16x16x32_bf16 v[26:29], v[98:101], v[186:189], v[26:29]
	s_waitcnt lgkmcnt(0)
	v_mfma_f32_16x16x32_bf16 v[14:17], v[74:77], v[230:233], v[14:17]
	v_mfma_f32_16x16x32_bf16 v[10:13], v[98:101], v[230:233], v[10:13]
	v_mfma_f32_16x16x32_bf16 v[58:61], v[114:117], v[158:161], v[58:61]
	v_mfma_f32_16x16x32_bf16 v[54:57], v[138:141], v[158:161], v[54:57]
	v_mfma_f32_16x16x32_bf16 v[38:41], v[114:117], v[174:177], v[38:41]
	v_mfma_f32_16x16x32_bf16 v[34:37], v[138:141], v[174:177], v[34:37]
	v_mfma_f32_16x16x32_bf16 v[22:25], v[114:117], v[182:185], v[22:25]
	v_mfma_f32_16x16x32_bf16 v[18:21], v[138:141], v[182:185], v[18:21]
	v_mfma_f32_16x16x32_bf16 v[6:9], v[114:117], v[210:213], v[6:9]
	v_mfma_f32_16x16x32_bf16 v[2:5], v[138:141], v[210:213], v[2:5]
	v_mfma_f32_16x16x32_bf16 v[58:61], v[122:125], v[162:165], v[58:61]
	v_mfma_f32_16x16x32_bf16 v[54:57], v[146:149], v[162:165], v[54:57]
	v_mfma_f32_16x16x32_bf16 v[38:41], v[122:125], v[178:181], v[38:41]
	v_mfma_f32_16x16x32_bf16 v[34:37], v[146:149], v[178:181], v[34:37]
	v_mfma_f32_16x16x32_bf16 v[22:25], v[122:125], v[186:189], v[22:25]
	v_mfma_f32_16x16x32_bf16 v[18:21], v[146:149], v[186:189], v[18:21]
	v_mfma_f32_16x16x32_bf16 v[6:9], v[122:125], v[230:233], v[6:9]
	v_mfma_f32_16x16x32_bf16 v[2:5], v[146:149], v[230:233], v[2:5]
	s_barrier
	s_add_i32 s84, s84, 2
	s_add_u32 s64, s64, 0x100
	s_addc_u32 s65, s65, 0
	s_add_u32 s60, s60, 0x100
	s_addc_u32 s61, s61, 0
	s_cmp_gt_u32 s84, 13
	s_cbranch_scc1 .LBB0_983

; #define PG8_WAIT_V(n) asm volatile("s_waitcnt vmcnt(" #n ")" ::: "memory")
; #define PG8_BAR __builtin_amdgcn_s_barrier()
; template <class Epi, class Sched, bool ALIGN_EPI = false, bool SP2 = false>
; __device__ __forceinline__ void gemm_phase(PG8_LAS unsigned char* lds, const Gemm g, const Sched& S, const Epi& E, int wave_u) {
;     ...
;     PG8_WAIT_V(0);
;     if constexpr (!ALIGN_EPI) { if (wr == 0) PG8_BAR; }
;     PG8_BAR;
.LBB0_1004:
	v_readlane_b32 s78, v255, 13
	s_setprio 0
	s_waitcnt vmcnt(0)
	v_readlane_b32 s79, v255, 14
	s_mov_b32 s92, s78
	v_readlane_b32 s64, v255, 16
	v_readlane_b32 s76, v255, 18
	v_readlane_b32 s78, v255, 20
	v_readlane_b32 s80, v255, 22
	v_readlane_b32 s82, v255, 24
	v_readlane_b32 s86, v255, 26
	v_readlane_b32 s88, v255, 28
	v_readlane_b32 s75, v255, 15
	v_readlane_b32 s65, v255, 17
	v_readlane_b32 s77, v255, 19
	v_readlane_b32 s79, v255, 21
	v_readlane_b32 s81, v255, 23
	v_readlane_b32 s83, v255, 25
	v_readlane_b32 s87, v255, 27
	v_readlane_b32 s89, v255, 29
	s_barrier

;     __host__ __device__ bool next(int i, Unit& u) const {
;         const long L = (long)i * G + c; if (L >= nwg) return false;
;         int wgid = (int)L; { const int q = nwg / NXCD, r = nwg % NXCD, xcd = wgid % NXCD, off = wgid / NXCD; wgid = (xcd < r ? xcd * (q + 1) : r * (q + 1) + (xcd - r) * q) + off; }
;         const int nig = WGM * nN, gid = wgid / nig, fm = gid * WGM, gsz = (nM - fm) < WGM ? (nM - fm) : WGM;
;         u.pm = fm + ((wgid % nig) % gsz); u.pn = (wgid % nig) / gsz; return true;
; template <class Epi, class Sched, bool ALIGN_EPI = false, bool SP2 = false>
; __device__ __forceinline__ void gemm_phase(PG8_LAS unsigned char* lds, const Gemm g, const Sched& S, const Epi& E, int wave_u) {
;     ...
;     const int tid = tid_, wid = __builtin_amdgcn_readfirstlane(tid >> 6), lane = tid & 63, wr = wid >> 2, wc = wid & 3, fr = lane & 15, fq = lane >> 4;
;     const int K = g.K, nt = K / BK;
;     unsigned voffA[2], voffB[2];
; #pragma unroll
;     for (int i = 0; i < 2; ++i) { int R, C; stage_rc(tid * 16 + i * 8192, R, C); const int Rb = Epi::PERM ? ((R & ~31) + perm32(R & 31)) : R;
;         voffA[i] = (unsigned)(R * K + C) * 2u; voffB[i] = (unsigned)(Rb * K + C) * 2u; }
;     const size_t kstep = (size_t)(BK * 2);
;     const size_t hstep = (size_t)HALF * K * 2;
;     const size_t tstep = 2 * hstep;
;     const unsigned ldsw = (unsigned)wid * 1024u;
;     const unsigned ldsb = (unsigned)__builtin_amdgcn_readfirstlane((int)((unsigned)(size_t)lds + ldsw));
;     const int aoff = lds_byte(wr * 64 + fr, fq * 8), boff = lds_byte(wc * 32 + fr, fq * 8);
.LBB0_1166:
	v_readlane_b32 s0, v255, 43
	v_readlane_b32 s1, v255, 44
	s_add_u32 s12, s0, 0x800000
	s_addc_u32 s13, s1, 0
	v_readlane_b32 s0, v254, 27
	v_readlane_b32 s1, v254, 28
	s_mov_b32 s2, s0
	v_readlane_b32 s0, v255, 45
	v_mbcnt_lo_u32_b32 v0, -1, 0
	v_mbcnt_hi_u32_b32 v0, -1, v0
	v_readlane_b32 s1, v255, 46
	v_add_u32_e32 v130, s75, v0
	s_add_u32 s56, s0, 0x6000
	s_addc_u32 s57, s1, 0
	v_readfirstlane_b32 s10, v130
	s_ashr_i32 s0, s10, 6
	s_cmpk_gt_i32 s2, 0x57f
	s_cbranch_scc1 .LBB0_1184
	v_lshlrev_b32_e32 v0, 4, v130
	s_waitcnt vmcnt(0) lgkmcnt(1)
	v_add_u32_e32 v2, 0x2000, v0
	v_ashrrev_i32_e32 v3, 31, v2
	v_lshrrev_b32_e32 v3, 22, v3
	v_add_u32_e32 v3, v2, v3
	v_ashrrev_i32_e32 v3, 10, v3
	s_waitcnt lgkmcnt(0)
	v_mul_i32_i24_e32 v4, 0x400, v3
	v_sub_u32_e32 v2, v2, v4
	v_lshrrev_b32_e32 v4, 4, v2
	v_bitop3_b32 v2, v4, v2, 32 bitop3:0x6c
	v_ashrrev_i32_e32 v4, 31, v2
	v_lshrrev_b32_e32 v4, 26, v4
	v_add_u32_e32 v4, v2, v4
	v_lshlrev_b32_e32 v6, 3, v3
	v_ashrrev_i32_e32 v5, 6, v4
	v_and_b32_e32 v6, -16, v6
	v_add_u32_e32 v6, v5, v6
	v_and_b32_e32 v5, 3, v5
	s_mov_b32 s16, 0x1fffe0
	v_lshrrev_b32_e32 v7, 2, v6
	v_lshlrev_b32_e32 v8, 1, v6
	v_and_or_b32 v5, v6, s16, v5
	v_and_b32_e32 v7, 4, v7
	v_and_b32_e32 v8, 24, v8
	v_and_b32_e32 v4, 0xc0, v4
	v_or3_b32 v5, v5, v7, v8
	v_sub_u32_e32 v2, v2, v4
	v_mov_b32_e32 v8, 1
	v_lshlrev_b32_e32 v3, 5, v3
	v_ashrrev_i16_sdwa v2, v8, sext(v2) dst_sel:DWORD dst_unused:UNUSED_PAD src0_sel:DWORD src1_sel:BYTE_0
	v_and_b32_e32 v3, 32, v3
	v_bfe_i32 v2, v2, 0, 16
	v_add_lshl_u32 v2, v3, v2, 1
	v_lshl_add_u32 v162, v5, 11, v2
	v_lshl_add_u32 v164, v6, 11, v2
	v_bfe_i32 v2, v130, 27, 1
	v_lshrrev_b32_e32 v2, 22, v2
	v_add_u32_e32 v2, v0, v2
	v_and_b32_e32 v2, 0xfffffc00, v2
	v_sub_u32_e32 v0, v0, v2
	v_lshrrev_b32_e32 v2, 4, v0
	v_ashrrev_i32_e32 v131, 31, v130
	v_bitop3_b32 v0, v2, v0, 32 bitop3:0x6c
	v_lshrrev_b32_e32 v4, 26, v131
	v_ashrrev_i32_e32 v2, 31, v0
	v_add_u32_e32 v4, v130, v4
	v_lshrrev_b32_e32 v2, 26, v2
	v_ashrrev_i32_e32 v4, 6, v4
	v_add_u32_e32 v2, v0, v2
	v_lshlrev_b32_e32 v5, 3, v4
	v_ashrrev_i32_e32 v3, 6, v2
	v_and_b32_e32 v5, -16, v5
	v_add_u32_e32 v5, v3, v5
	v_and_b32_e32 v3, 3, v3
	s_ashr_i32 s41, s2, 31
	s_lshl_b32 s1, s0, 10
	v_and_or_b32 v3, v5, s16, v3
	s_lshr_b32 s16, s41, 29
	s_add_i32 s7, s1, 0
	s_lshl_b32 s1, s0, 8
	s_add_i32 s16, s2, s16
	s_add_i32 s1, s1, 0
	s_ashr_i32 s17, s16, 3
	s_and_b32 s16, s16, -8
	s_ashr_i32 s11, s10, 8
	s_add_i32 s40, s1, 0x20400
	s_sub_i32 s16, s2, s16
	s_cmp_lt_i32 s16, 0
	s_movk_i32 s76, 0xb1
	s_cselect_b32 s18, s76, 0xb0
	s_mul_i32 s16, s16, s18
	s_add_i32 s16, s16, s17
	s_mul_hi_i32 s17, s16, 0x2e8ba2e9
	s_lshr_b32 s18, s17, 31
	s_ashr_i32 s17, s17, 5
	s_add_i32 s17, s17, s18
	s_lshl_b32 s18, s17, 3
	s_mulk_i32 s17, 0xb0
	s_sub_i32 s17, s16, s17
	s_bfe_u32 s16, s17, 0x3001c
	s_add_i32 s19, s17, s16
	s_sext_i32_i16 s20, s19
	s_and_b32 s19, s19, 0xfff8
	s_sub_i32 s17, s17, s19
	s_sext_i32_i16 s17, s17
	s_lshr_b32 s16, s20, 3
	s_add_i32 s30, s18, s17
	s_ashr_i32 s31, s30, 31
	s_bfe_i64 s[16:17], s[16:17], 0x100000
	v_and_b32_e32 v2, 0xc0, v2
	s_ashr_i32 s53, s20, 3
	s_lshl_b64 s[18:19], s[30:31], 19
	s_lshl_b64 s[16:17], s[16:17], 19
	v_sub_u32_e32 v0, v0, v2
	s_add_u32 s34, s12, s16
	v_lshrrev_b32_e32 v6, 2, v5
	v_lshlrev_b32_e32 v7, 1, v5
	v_lshlrev_b32_e32 v4, 5, v4
	v_ashrrev_i16_sdwa v0, v8, sext(v0) dst_sel:DWORD dst_unused:UNUSED_PAD src0_sel:DWORD src1_sel:BYTE_0
	s_addc_u32 s35, s13, s17
	s_lshl_b64 s[16:17], s[30:31], 11
	v_and_b32_e32 v6, 4, v6
	v_and_b32_e32 v7, 24, v7
	v_and_b32_e32 v4, 32, v4
	v_bfe_i32 v0, v0, 0, 16
	s_add_u32 s16, s28, s16
	v_or3_b32 v3, v3, v6, v7
	v_add_lshl_u32 v0, v4, v0, 1
	s_addc_u32 s17, s29, s17
	v_lshlrev_b64 v[132:133], 2, v[130:131]
	v_lshl_add_u32 v166, v3, 11, v0
	v_lshl_add_u32 v168, v5, 11, v0
	v_pk_mov_b32 v[122:123], 0, 0
	v_pk_mov_b32 v[124:125], 0, 0
	v_pk_mov_b32 v[114:115], 0, 0
	v_pk_mov_b32 v[116:117], 0, 0
	v_pk_mov_b32 v[106:107], 0, 0
	v_pk_mov_b32 v[108:109], 0, 0
	v_pk_mov_b32 v[98:99], 0, 0
	v_pk_mov_b32 v[100:101], 0, 0
	v_pk_mov_b32 v[90:91], 0, 0
	v_pk_mov_b32 v[92:93], 0, 0
	v_pk_mov_b32 v[82:83], 0, 0
	v_pk_mov_b32 v[84:85], 0, 0
; __device__ __forceinline__ f32x4 zero4_pk() { f32x2_z a, b; asm volatile("v_pk_mov_b32 %0, 0, 0" : "=v"(a)); asm volatile("v_pk_mov_b32 %0, 0, 0" : "=v"(b)); return (f32x4){a.x, a.y, b.x, b.y}; }
; #define PG8_STAGE(bufoff, gbase, voff) do { _Pragma("unroll") for (int _i = 0; _i < 2; ++_i) \
;         glds16_asm((const char*)(gbase) + (voff)[_i], ldsb + (unsigned)((bufoff) + _i * 8192)); } while (0)
; #define PG8_WAIT_V(n) asm volatile("s_waitcnt vmcnt(" #n ")" ::: "memory")
; #define PG8_BAR __builtin_amdgcn_s_barrier()
; template <class Epi, class Sched, bool ALIGN_EPI = false, bool SP2 = false>
; __device__ __forceinline__ void gemm_phase(PG8_LAS unsigned char* lds, const Gemm g, const Sched& S, const Epi& E, int wave_u) {
;     ...
;     f32x4 acc[2][2][4][2];
; #pragma unroll
;     for (int a = 0; a < 2; ++a)
; #pragma unroll
;         for (int b = 0; b < 2; ++b)
; #pragma unroll
;             for (int m = 0; m < 4; ++m)
; #pragma unroll
;                 for (int n = 0; n < 2; ++n) acc[a][b][m][n] = zero4_pk();
;     bf16x8 At[4][2], B0[2][2], B1[2][2];
;     const char* cA = (const char*)g.A + (size_t)cur.pm * tstep; const char* cB = (const char*)g.Bt + (size_t)cur.pn * tstep;
;     S.a_ready(cur);
;     epi_prefetch(E, cur.pm, cur.pn, evb, tid);
;     if constexpr (SP2) {
;         PG8_STAGE(PG8_SB(0, 0), cB, voffB); PG8_STAGE(PG8_SB(0, 1), cB + hstep, voffB); PG8_STAGE(PG8_SA(0, 0), cA, voffA); PG8_STAGE(PG8_SA(0, 1), cA + hstep, voffA);
;         if (wr == 1) PG8_BAR;
;         PG8_WAIT_V(2); PG8_BAR;
;         PG8_STAGE(PG8_SB(1, 0), cB + kstep, voffB); PG8_STAGE(PG8_SA(1, 0), cA + kstep, voffA); PG8_STAGE(PG8_SB(1, 1), cB + hstep + kstep, voffB);
;         PG8_WAIT_V(6); PG8_BAR;
;     } else {
;         PG8_STAGE(PG8_SB(0, 0), cB, voffB); PG8_STAGE(PG8_SA(0, 0), cA, voffA); PG8_STAGE(PG8_SB(0, 1), cB + hstep, voffB); PG8_STAGE(PG8_SA(0, 1), cA + hstep, voffA);
;         if (wr == 1) PG8_BAR;
;         PG8_WAIT_V(4); PG8_BAR;
;         PG8_STAGE(PG8_SB(1, 0), cB + kstep, voffB); PG8_STAGE(PG8_SA(1, 0), cA + kstep, voffA); PG8_STAGE(PG8_SB(1, 1), cB + hstep + kstep, voffB);
;         PG8_WAIT_V(6); PG8_BAR;
	v_pk_mov_b32 v[74:75], 0, 0
	v_pk_mov_b32 v[76:77], 0, 0
	v_pk_mov_b32 v[66:67], 0, 0
	v_pk_mov_b32 v[68:69], 0, 0
	v_pk_mov_b32 v[126:127], 0, 0
	v_pk_mov_b32 v[128:129], 0, 0
	v_pk_mov_b32 v[118:119], 0, 0
	v_pk_mov_b32 v[120:121], 0, 0
	v_pk_mov_b32 v[110:111], 0, 0
	v_pk_mov_b32 v[112:113], 0, 0
	v_pk_mov_b32 v[102:103], 0, 0
	v_pk_mov_b32 v[104:105], 0, 0
	v_pk_mov_b32 v[94:95], 0, 0
	v_pk_mov_b32 v[96:97], 0, 0
	v_pk_mov_b32 v[86:87], 0, 0
	v_pk_mov_b32 v[88:89], 0, 0
	v_pk_mov_b32 v[78:79], 0, 0
	v_pk_mov_b32 v[80:81], 0, 0
	v_pk_mov_b32 v[70:71], 0, 0
	v_pk_mov_b32 v[72:73], 0, 0
	v_pk_mov_b32 v[58:59], 0, 0
	v_pk_mov_b32 v[60:61], 0, 0
	v_pk_mov_b32 v[50:51], 0, 0
	v_pk_mov_b32 v[52:53], 0, 0
	v_pk_mov_b32 v[42:43], 0, 0
	v_pk_mov_b32 v[44:45], 0, 0
	v_pk_mov_b32 v[34:35], 0, 0
	v_pk_mov_b32 v[36:37], 0, 0
	v_pk_mov_b32 v[26:27], 0, 0
	v_pk_mov_b32 v[28:29], 0, 0
	v_pk_mov_b32 v[18:19], 0, 0
	v_pk_mov_b32 v[20:21], 0, 0
	v_pk_mov_b32 v[10:11], 0, 0
	v_pk_mov_b32 v[12:13], 0, 0
	v_pk_mov_b32 v[2:3], 0, 0
	v_pk_mov_b32 v[4:5], 0, 0
	v_pk_mov_b32 v[62:63], 0, 0
	v_pk_mov_b32 v[64:65], 0, 0
	v_pk_mov_b32 v[54:55], 0, 0
	v_pk_mov_b32 v[56:57], 0, 0
	v_pk_mov_b32 v[46:47], 0, 0
	v_pk_mov_b32 v[48:49], 0, 0
	v_pk_mov_b32 v[38:39], 0, 0
	v_pk_mov_b32 v[40:41], 0, 0
	v_pk_mov_b32 v[30:31], 0, 0
	v_pk_mov_b32 v[32:33], 0, 0
	v_pk_mov_b32 v[22:23], 0, 0
	v_pk_mov_b32 v[24:25], 0, 0
	v_pk_mov_b32 v[14:15], 0, 0
	v_pk_mov_b32 v[16:17], 0, 0
	v_pk_mov_b32 v[6:7], 0, 0
	v_pk_mov_b32 v[8:9], 0, 0
	v_lshl_add_u64 v[134:135], s[16:17], 0, v[132:133]
	s_mov_b32 s16, m0
	s_mov_b32 m0, s40
	s_nop 0
	global_load_lds_dword v[134:135], off
	s_mov_b32 m0, s16
	s_movk_i32 s16, 0x100
	v_cmp_gt_i32_e32 vcc, s16, v130
	v_readlane_b32 s16, v255, 45
	v_readlane_b32 s17, v255, 46
	s_add_u32 s16, s16, 0xb400
	s_addc_u32 s17, s17, 0
	v_mov_b32_e32 v0, s17
	v_mov_b32_e32 v131, s57
	v_cndmask_b32_e32 v135, v0, v131, vcc
	v_mov_b32_e32 v0, s16
	v_mov_b32_e32 v131, s56
	s_lshl_b32 s16, s53, 8
	v_cndmask_b32_e32 v134, v0, v131, vcc
	s_ashr_i32 s17, s16, 31
	v_lshl_add_u64 v[136:137], s[16:17], 2, v[134:135]
	v_lshl_add_u64 v[136:137], v[136:137], 0, v[132:133]
	s_add_i32 s1, s1, 0x20c00
	s_mov_b32 s16, m0
	s_mov_b32 m0, s1
	s_nop 0
	global_load_lds_dword v[136:137], off
	s_mov_b32 m0, s16
	s_add_i32 s52, s7, 0x10000
	v_mov_b32_e32 v167, v1
	s_add_i32 s58, s7, 0x12000
	v_lshl_add_u64 v[136:137], s[34:35], 0, v[166:167]
	s_mov_b32 s1, m0
	s_mov_b32 m0, s52
	s_nop 0
	global_load_lds_dwordx4 v[136:137], off
	s_mov_b32 m0, s1
	v_mov_b32_e32 v163, v1
	s_add_u32 s16, s34, 0x40000
	v_lshl_add_u64 v[136:137], s[34:35], 0, v[162:163]
	s_mov_b32 s1, m0
	s_mov_b32 m0, s58
	s_nop 0
	global_load_lds_dwordx4 v[136:137], off
	s_mov_b32 m0, s1
	s_addc_u32 s17, s35, 0
	s_add_i32 s59, s7, 0x14000
	s_add_i32 s62, s7, 0x16000
	v_lshl_add_u64 v[136:137], s[16:17], 0, v[166:167]
	s_mov_b32 s1, m0
	s_mov_b32 m0, s59
	s_nop 0
	global_load_lds_dwordx4 v[136:137], off
	s_mov_b32 m0, s1
	s_add_u32 s60, s72, s18
	v_lshl_add_u64 v[136:137], s[16:17], 0, v[162:163]
	s_mov_b32 s1, m0
	s_mov_b32 m0, s62
	s_nop 0
	global_load_lds_dwordx4 v[136:137], off
	s_mov_b32 m0, s1
	s_addc_u32 s61, s73, s19
	v_mov_b32_e32 v169, v1
	s_add_i32 s63, s7, 0x2000
	v_lshl_add_u64 v[136:137], s[60:61], 0, v[168:169]
	s_mov_b32 s1, m0
	s_mov_b32 m0, s7
	s_nop 0
	global_load_lds_dwordx4 v[136:137], off
	s_mov_b32 m0, s1
	v_mov_b32_e32 v165, v1
	s_add_u32 s16, s60, 0x40000
	v_lshl_add_u64 v[136:137], s[60:61], 0, v[164:165]
	s_mov_b32 s1, m0
	s_mov_b32 m0, s63
	s_nop 0
	global_load_lds_dwordx4 v[136:137], off
	s_mov_b32 m0, s1
	s_addc_u32 s17, s61, 0
	s_add_i32 s64, s7, 0x4000
	v_lshl_add_u64 v[136:137], s[16:17], 0, v[168:169]
	s_mov_b32 s1, m0
	s_mov_b32 m0, s64
	s_nop 0
	global_load_lds_dwordx4 v[136:137], off
	s_mov_b32 m0, s1
	v_lshl_add_u64 v[136:137], s[16:17], 0, v[164:165]
	s_add_i32 s65, s7, 0x6000
	s_mov_b32 s1, m0
	s_mov_b32 m0, s65
	s_nop 0
	global_load_lds_dwordx4 v[136:137], off
	s_mov_b32 m0, s1
	s_cmp_eq_u32 s11, 1
	v_mov_b32_e32 v215, 1
	s_cselect_b64 s[16:17], -1, 0
	s_cmp_lg_u32 s11, 1
	s_cbranch_scc1 .LBB0_1169
	s_setprio 1
	s_barrier

; #define PG8_STAGE(bufoff, gbase, voff) do { _Pragma("unroll") for (int _i = 0; _i < 2; ++_i) \
;         glds16_asm((const char*)(gbase) + (voff)[_i], ldsb + (unsigned)((bufoff) + _i * 8192)); } while (0)
; #define PG8_LDA(dst, b, h) do { _Pragma("unroll") for (int m = 0; m < 4; ++m) _Pragma("unroll") for (int k = 0; k < 2; ++k) dst[m][k] = *(const PG8_LAS bf16x8*)(lds + PG8_SA(b, h) + aoff + m * 2048 + k * 1024); } while (0)
; #define PG8_LDB(dst, b, h) do { _Pragma("unroll") for (int n = 0; n < 2; ++n) _Pragma("unroll") for (int k = 0; k < 2; ++k) dst[n][k] = *(const PG8_LAS bf16x8*)(lds + PG8_SB(b, h) + boff + n * 2048 + k * 1024); } while (0)
; #define PG8_MMA(ai, bj, At, Bt) do { __builtin_amdgcn_s_setprio(1); _Pragma("unroll") for (int m = 0; m < 4; ++m) _Pragma("unroll") for (int n = 0; n < 2; ++n) _Pragma("unroll") for (int k = 0; k < 2; ++k) \
;         acc[ai][bj][m][n] = __builtin_amdgcn_mfma_f32_16x16x32_bf16(Bt[n][k], At[m][k], acc[ai][bj][m][n], 0, 0, 0); __builtin_amdgcn_s_setprio(0); } while (0)
; #define PG8_WAIT_V(n) asm volatile("s_waitcnt vmcnt(" #n ")" ::: "memory")
; #define PG8_BAR __builtin_amdgcn_s_barrier()
; template <class Epi, class Sched, bool ALIGN_EPI = false, bool SP2 = false>
; __device__ __forceinline__ void gemm_phase(PG8_LAS unsigned char* lds, const Gemm g, const Sched& S, const Epi& E, int wave_u) {
;     ...
;             PG8_LDB(B0, 0, 0); PG8_LDB(B1, 0, 1); PG8_SCHED; PG8_LDA(At, 0, 0); PG8_STAGE(PG8_SA(1, 1), a1 + hstep, voffA);
;             PG8_WAIT_V(8); PG8_WAIT_L(0); PG8_BAR; PG8_MMA(0, 0, At, B0); PG8_MMA(0, 1, At, B1); PG8_BAR; PG8_SCHED;
;             PG8_LDA(At, 0, 1); PG8_STAGE(PG8_SB(0, 0), b2, voffB); PG8_STAGE(PG8_SB(0, 1), b2 + hstep, voffB); PG8_STAGE(PG8_SA(0, 0), a2, voffA);
;             PG8_WAIT_V(8); PG8_WAIT_L(0); PG8_BAR; PG8_MMA(1, 0, At, B0); PG8_MMA(1, 1, At, B1); PG8_BAR; PG8_SCHED;
;             PG8_LDB(B0, 1, 0); PG8_LDB(B1, 1, 1); PG8_SCHED; PG8_LDA(At, 1, 0); PG8_STAGE(PG8_SA(0, 1), a2 + hstep, voffA);
;             PG8_WAIT_V(8); PG8_WAIT_L(0); PG8_BAR; PG8_MMA(0, 0, At, B0); PG8_MMA(0, 1, At, B1); PG8_BAR; PG8_SCHED;
;             PG8_LDA(At, 1, 1); PG8_STAGE(PG8_SB(1, 0), b3, voffB); PG8_STAGE(PG8_SB(1, 1), b3 + hstep, voffB); PG8_STAGE(PG8_SA(1, 0), a3, voffA);
;             PG8_WAIT_V(8); PG8_WAIT_L(0); PG8_BAR; PG8_MMA(1, 0, At, B0); PG8_MMA(1, 1, At, B1); PG8_BAR; PG8_SCHED;
.LBB0_1175:
	v_add_u32_e32 v146, 0x10000, v177
	v_add_u32_e32 v179, 0x14000, v177
	s_add_u32 s44, s60, 0xfffc0080
	ds_read_b128 v[134:137], v146
	ds_read_b128 v[138:141], v146 offset:1024
	ds_read_b128 v[142:145], v146 offset:2048
	ds_read_b128 v[146:149], v146 offset:3072
	ds_read_b128 v[150:153], v179
	ds_read_b128 v[154:157], v179 offset:1024
	ds_read_b128 v[158:161], v179 offset:2048
	ds_read_b128 v[180:183], v179 offset:3072
	s_addc_u32 s45, s61, -1
	s_and_b64 s[34:35], s[34:35], exec
	s_cselect_b32 s48, s91, s44
	s_cselect_b32 s49, s90, s45
	s_cselect_b32 s35, s21, s85
	s_cselect_b32 s34, s96, s84
	s_add_u32 s44, s48, 0x80
	s_addc_u32 s45, s49, 0
	s_add_u32 s46, s34, 0x80
	s_addc_u32 s47, s35, 0
	ds_read_b128 v[184:187], v178
	ds_read_b128 v[198:201], v178 offset:1024
	ds_read_b128 v[202:205], v178 offset:2048
	ds_read_b128 v[206:209], v178 offset:3072
	ds_read_b128 v[210:213], v178 offset:4096
	ds_read_b128 v[224:227], v178 offset:5120
	ds_read_b128 v[228:231], v178 offset:6144
	ds_read_b128 v[232:235], v178 offset:7168
	v_lshl_add_u64 v[188:189], s[60:61], 0, v[168:169]
	s_mov_b32 vcc_lo, m0
	s_mov_b32 m0, s87
	s_nop 0
	global_load_lds_dwordx4 v[188:189], off
	s_mov_b32 m0, vcc_lo
	v_lshl_add_u64 v[188:189], s[60:61], 0, v[164:165]
	s_mov_b32 vcc_lo, m0
	s_mov_b32 m0, s88
	s_nop 0
	global_load_lds_dwordx4 v[188:189], off
	s_mov_b32 m0, vcc_lo
	s_waitcnt vmcnt(8)
	s_waitcnt lgkmcnt(0)
	s_barrier
	s_waitcnt lgkmcnt(7)
	v_mfma_f32_16x16x32_bf16 v[122:125], v[134:137], v[184:187], v[122:125]
	v_mfma_f32_16x16x32_bf16 v[114:117], v[142:145], v[184:187], v[114:117]
	s_waitcnt lgkmcnt(5)
	v_mfma_f32_16x16x32_bf16 v[106:109], v[134:137], v[202:205], v[106:109]
	v_mfma_f32_16x16x32_bf16 v[98:101], v[142:145], v[202:205], v[98:101]
	s_waitcnt lgkmcnt(3)
	v_mfma_f32_16x16x32_bf16 v[90:93], v[134:137], v[210:213], v[90:93]
	v_mfma_f32_16x16x32_bf16 v[82:85], v[142:145], v[210:213], v[82:85]
	s_waitcnt lgkmcnt(1)
	v_mfma_f32_16x16x32_bf16 v[74:77], v[134:137], v[228:231], v[74:77]
	v_mfma_f32_16x16x32_bf16 v[66:69], v[142:145], v[228:231], v[66:69]
	v_mfma_f32_16x16x32_bf16 v[122:125], v[138:141], v[198:201], v[122:125]
	v_mfma_f32_16x16x32_bf16 v[114:117], v[146:149], v[198:201], v[114:117]
	v_mfma_f32_16x16x32_bf16 v[106:109], v[138:141], v[206:209], v[106:109]
	v_mfma_f32_16x16x32_bf16 v[98:101], v[146:149], v[206:209], v[98:101]
	v_mfma_f32_16x16x32_bf16 v[90:93], v[138:141], v[224:227], v[90:93]
	v_mfma_f32_16x16x32_bf16 v[82:85], v[146:149], v[224:227], v[82:85]
	s_waitcnt lgkmcnt(0)
	v_mfma_f32_16x16x32_bf16 v[74:77], v[138:141], v[232:235], v[74:77]
	v_mfma_f32_16x16x32_bf16 v[66:69], v[146:149], v[232:235], v[66:69]
	v_mfma_f32_16x16x32_bf16 v[126:129], v[150:153], v[184:187], v[126:129]
	v_mfma_f32_16x16x32_bf16 v[118:121], v[158:161], v[184:187], v[118:121]
	v_mfma_f32_16x16x32_bf16 v[110:113], v[150:153], v[202:205], v[110:113]
	v_mfma_f32_16x16x32_bf16 v[102:105], v[158:161], v[202:205], v[102:105]
	v_mfma_f32_16x16x32_bf16 v[94:97], v[150:153], v[210:213], v[94:97]
	v_mfma_f32_16x16x32_bf16 v[86:89], v[158:161], v[210:213], v[86:89]
	v_mfma_f32_16x16x32_bf16 v[78:81], v[150:153], v[228:231], v[78:81]
	v_mfma_f32_16x16x32_bf16 v[70:73], v[158:161], v[228:231], v[70:73]
	v_mfma_f32_16x16x32_bf16 v[126:129], v[154:157], v[198:201], v[126:129]
	v_mfma_f32_16x16x32_bf16 v[118:121], v[180:183], v[198:201], v[118:121]
	v_mfma_f32_16x16x32_bf16 v[110:113], v[154:157], v[206:209], v[110:113]
	v_mfma_f32_16x16x32_bf16 v[102:105], v[180:183], v[206:209], v[102:105]
	v_mfma_f32_16x16x32_bf16 v[94:97], v[154:157], v[224:227], v[94:97]
	v_mfma_f32_16x16x32_bf16 v[86:89], v[180:183], v[224:227], v[86:89]
	v_mfma_f32_16x16x32_bf16 v[78:81], v[154:157], v[232:235], v[78:81]
	v_mfma_f32_16x16x32_bf16 v[70:73], v[180:183], v[232:235], v[70:73]
	s_barrier
	ds_read_b128 v[184:187], v178 offset:16384
	ds_read_b128 v[198:201], v178 offset:17408
	ds_read_b128 v[202:205], v178 offset:18432
	ds_read_b128 v[206:209], v178 offset:19456
	ds_read_b128 v[210:213], v178 offset:20480
	ds_read_b128 v[224:227], v178 offset:21504
	ds_read_b128 v[228:231], v178 offset:22528
	ds_read_b128 v[232:235], v178 offset:23552
	v_lshl_add_u64 v[188:189], s[34:35], 0, v[166:167]
	s_mov_b32 vcc_lo, m0
	s_mov_b32 m0, s52
	s_nop 0
	global_load_lds_dwordx4 v[188:189], off
	s_mov_b32 m0, vcc_lo
	v_lshl_add_u64 v[188:189], s[34:35], 0, v[162:163]
	s_mov_b32 vcc_lo, m0
	s_mov_b32 m0, s58
	s_nop 0
	global_load_lds_dwordx4 v[188:189], off
	s_mov_b32 m0, vcc_lo
	s_add_u32 vcc_lo, s34, 0x40000
	s_addc_u32 vcc_hi, s35, 0
	v_lshl_add_u64 v[188:189], vcc, 0, v[166:167]
	s_mov_b32 s92, m0
	s_mov_b32 m0, s59
	s_nop 0
	global_load_lds_dwordx4 v[188:189], off
	s_mov_b32 m0, s92
	v_lshl_add_u64 v[188:189], vcc, 0, v[162:163]
	s_mov_b32 s92, m0
	s_mov_b32 m0, s62
	s_nop 0
	global_load_lds_dwordx4 v[188:189], off
	s_mov_b32 m0, s92
	v_lshl_add_u64 v[188:189], s[48:49], 0, v[168:169]
	s_mov_b32 s92, m0
	s_mov_b32 m0, s7
	s_nop 0
	global_load_lds_dwordx4 v[188:189], off
	s_mov_b32 m0, s92
	v_lshl_add_u64 v[188:189], s[48:49], 0, v[164:165]
	s_mov_b32 s92, m0
	s_mov_b32 m0, s63
	s_nop 0
	global_load_lds_dwordx4 v[188:189], off
	s_mov_b32 m0, s92
	s_waitcnt vmcnt(8)
	s_waitcnt lgkmcnt(0)
	s_barrier
; #define PG8_STAGE(bufoff, gbase, voff) do { _Pragma("unroll") for (int _i = 0; _i < 2; ++_i) \
;         glds16_asm((const char*)(gbase) + (voff)[_i], ldsb + (unsigned)((bufoff) + _i * 8192)); } while (0)
; #define PG8_LDA(dst, b, h) do { _Pragma("unroll") for (int m = 0; m < 4; ++m) _Pragma("unroll") for (int k = 0; k < 2; ++k) dst[m][k] = *(const PG8_LAS bf16x8*)(lds + PG8_SA(b, h) + aoff + m * 2048 + k * 1024); } while (0)
; #define PG8_LDB(dst, b, h) do { _Pragma("unroll") for (int n = 0; n < 2; ++n) _Pragma("unroll") for (int k = 0; k < 2; ++k) dst[n][k] = *(const PG8_LAS bf16x8*)(lds + PG8_SB(b, h) + boff + n * 2048 + k * 1024); } while (0)
; #define PG8_MMA(ai, bj, At, Bt) do { __builtin_amdgcn_s_setprio(1); _Pragma("unroll") for (int m = 0; m < 4; ++m) _Pragma("unroll") for (int n = 0; n < 2; ++n) _Pragma("unroll") for (int k = 0; k < 2; ++k) \
;         acc[ai][bj][m][n] = __builtin_amdgcn_mfma_f32_16x16x32_bf16(Bt[n][k], At[m][k], acc[ai][bj][m][n], 0, 0, 0); __builtin_amdgcn_s_setprio(0); } while (0)
; #define PG8_WAIT_V(n) asm volatile("s_waitcnt vmcnt(" #n ")" ::: "memory")
; #define PG8_BAR __builtin_amdgcn_s_barrier()
; template <class Epi, class Sched, bool ALIGN_EPI = false, bool SP2 = false>
; __device__ __forceinline__ void gemm_phase(PG8_LAS unsigned char* lds, const Gemm g, const Sched& S, const Epi& E, int wave_u) {
;     ...
;             PG8_LDB(B0, 0, 0); PG8_LDB(B1, 0, 1); PG8_SCHED; PG8_LDA(At, 0, 0); PG8_STAGE(PG8_SA(1, 1), a1 + hstep, voffA);
;             PG8_WAIT_V(8); PG8_WAIT_L(0); PG8_BAR; PG8_MMA(0, 0, At, B0); PG8_MMA(0, 1, At, B1); PG8_BAR; PG8_SCHED;
;             PG8_LDA(At, 0, 1); PG8_STAGE(PG8_SB(0, 0), b2, voffB); PG8_STAGE(PG8_SB(0, 1), b2 + hstep, voffB); PG8_STAGE(PG8_SA(0, 0), a2, voffA);
;             PG8_WAIT_V(8); PG8_WAIT_L(0); PG8_BAR; PG8_MMA(1, 0, At, B0); PG8_MMA(1, 1, At, B1); PG8_BAR; PG8_SCHED;
;             PG8_LDB(B0, 1, 0); PG8_LDB(B1, 1, 1); PG8_SCHED; PG8_LDA(At, 1, 0); PG8_STAGE(PG8_SA(0, 1), a2 + hstep, voffA);
;             PG8_WAIT_V(8); PG8_WAIT_L(0); PG8_BAR; PG8_MMA(0, 0, At, B0); PG8_MMA(0, 1, At, B1); PG8_BAR; PG8_SCHED;
;             PG8_LDA(At, 1, 1); PG8_STAGE(PG8_SB(1, 0), b3, voffB); PG8_STAGE(PG8_SB(1, 1), b3 + hstep, voffB); PG8_STAGE(PG8_SA(1, 0), a3, voffA);
;             PG8_WAIT_V(8); PG8_WAIT_L(0); PG8_BAR; PG8_MMA(1, 0, At, B0); PG8_MMA(1, 1, At, B1); PG8_BAR; PG8_SCHED;
	s_waitcnt lgkmcnt(7)
	v_mfma_f32_16x16x32_bf16 v[58:61], v[134:137], v[184:187], v[58:61]
	v_mfma_f32_16x16x32_bf16 v[50:53], v[142:145], v[184:187], v[50:53]
	s_waitcnt lgkmcnt(5)
	v_mfma_f32_16x16x32_bf16 v[42:45], v[134:137], v[202:205], v[42:45]
	v_mfma_f32_16x16x32_bf16 v[34:37], v[142:145], v[202:205], v[34:37]
	s_waitcnt lgkmcnt(3)
	v_mfma_f32_16x16x32_bf16 v[26:29], v[134:137], v[210:213], v[26:29]
	v_mfma_f32_16x16x32_bf16 v[18:21], v[142:145], v[210:213], v[18:21]
	s_waitcnt lgkmcnt(1)
	v_mfma_f32_16x16x32_bf16 v[10:13], v[134:137], v[228:231], v[10:13]
	v_mfma_f32_16x16x32_bf16 v[2:5], v[142:145], v[228:231], v[2:5]
	v_mfma_f32_16x16x32_bf16 v[58:61], v[138:141], v[198:201], v[58:61]
	v_mfma_f32_16x16x32_bf16 v[50:53], v[146:149], v[198:201], v[50:53]
	v_mfma_f32_16x16x32_bf16 v[42:45], v[138:141], v[206:209], v[42:45]
	v_mfma_f32_16x16x32_bf16 v[34:37], v[146:149], v[206:209], v[34:37]
	v_mfma_f32_16x16x32_bf16 v[26:29], v[138:141], v[224:227], v[26:29]
	v_mfma_f32_16x16x32_bf16 v[18:21], v[146:149], v[224:227], v[18:21]
	s_waitcnt lgkmcnt(0)
	v_mfma_f32_16x16x32_bf16 v[10:13], v[138:141], v[232:235], v[10:13]
	v_mfma_f32_16x16x32_bf16 v[2:5], v[146:149], v[232:235], v[2:5]
	v_mfma_f32_16x16x32_bf16 v[62:65], v[150:153], v[184:187], v[62:65]
	v_mfma_f32_16x16x32_bf16 v[54:57], v[158:161], v[184:187], v[54:57]
	v_mfma_f32_16x16x32_bf16 v[46:49], v[150:153], v[202:205], v[46:49]
	v_mfma_f32_16x16x32_bf16 v[38:41], v[158:161], v[202:205], v[38:41]
	v_mfma_f32_16x16x32_bf16 v[30:33], v[150:153], v[210:213], v[30:33]
	v_mfma_f32_16x16x32_bf16 v[22:25], v[158:161], v[210:213], v[22:25]
	v_mfma_f32_16x16x32_bf16 v[14:17], v[150:153], v[228:231], v[14:17]
	v_mfma_f32_16x16x32_bf16 v[6:9], v[158:161], v[228:231], v[6:9]
	v_mfma_f32_16x16x32_bf16 v[62:65], v[154:157], v[198:201], v[62:65]
	v_mfma_f32_16x16x32_bf16 v[54:57], v[180:183], v[198:201], v[54:57]
	v_mfma_f32_16x16x32_bf16 v[46:49], v[154:157], v[206:209], v[46:49]
	v_mfma_f32_16x16x32_bf16 v[38:41], v[180:183], v[206:209], v[38:41]
	v_mfma_f32_16x16x32_bf16 v[30:33], v[154:157], v[224:227], v[30:33]
	v_mfma_f32_16x16x32_bf16 v[22:25], v[180:183], v[224:227], v[22:25]
	v_mfma_f32_16x16x32_bf16 v[14:17], v[154:157], v[232:235], v[14:17]
	v_mfma_f32_16x16x32_bf16 v[6:9], v[180:183], v[232:235], v[6:9]
	s_barrier
	v_add_u32_e32 v146, 0x18000, v177
	v_add_u32_e32 v179, 0x1c000, v177
	ds_read_b128 v[134:137], v146
	ds_read_b128 v[138:141], v146 offset:1024
	ds_read_b128 v[142:145], v146 offset:2048
	ds_read_b128 v[146:149], v146 offset:3072
	ds_read_b128 v[150:153], v179
	ds_read_b128 v[154:157], v179 offset:1024
	ds_read_b128 v[158:161], v179 offset:2048
	ds_read_b128 v[180:183], v179 offset:3072
	ds_read_b128 v[184:187], v178 offset:32768
	ds_read_b128 v[198:201], v178 offset:33792
	ds_read_b128 v[202:205], v178 offset:34816
	ds_read_b128 v[206:209], v178 offset:35840
	ds_read_b128 v[210:213], v178 offset:36864
	ds_read_b128 v[224:227], v178 offset:37888
	ds_read_b128 v[228:231], v178 offset:38912
	ds_read_b128 v[232:235], v178 offset:39936
	s_add_u32 s48, s48, 0x40000
	s_addc_u32 s49, s49, 0
	v_lshl_add_u64 v[188:189], s[48:49], 0, v[168:169]
	s_mov_b32 s92, m0
	s_mov_b32 m0, s64
	s_nop 0
	global_load_lds_dwordx4 v[188:189], off
	s_mov_b32 m0, s92
	v_lshl_add_u64 v[188:189], s[48:49], 0, v[164:165]
	s_mov_b32 s48, m0
	s_mov_b32 m0, s65
	s_nop 0
	global_load_lds_dwordx4 v[188:189], off
	s_mov_b32 m0, s48
	s_waitcnt vmcnt(8)
	s_waitcnt lgkmcnt(0)
	s_barrier
	s_waitcnt lgkmcnt(7)
	v_mfma_f32_16x16x32_bf16 v[122:125], v[134:137], v[184:187], v[122:125]
	v_mfma_f32_16x16x32_bf16 v[114:117], v[142:145], v[184:187], v[114:117]
	s_waitcnt lgkmcnt(5)
	v_mfma_f32_16x16x32_bf16 v[106:109], v[134:137], v[202:205], v[106:109]
	v_mfma_f32_16x16x32_bf16 v[98:101], v[142:145], v[202:205], v[98:101]
	s_waitcnt lgkmcnt(3)
	v_mfma_f32_16x16x32_bf16 v[90:93], v[134:137], v[210:213], v[90:93]
	v_mfma_f32_16x16x32_bf16 v[82:85], v[142:145], v[210:213], v[82:85]
	s_waitcnt lgkmcnt(1)
	v_mfma_f32_16x16x32_bf16 v[74:77], v[134:137], v[228:231], v[74:77]
	v_mfma_f32_16x16x32_bf16 v[66:69], v[142:145], v[228:231], v[66:69]
	v_mfma_f32_16x16x32_bf16 v[122:125], v[138:141], v[198:201], v[122:125]
	v_mfma_f32_16x16x32_bf16 v[114:117], v[146:149], v[198:201], v[114:117]
	v_mfma_f32_16x16x32_bf16 v[106:109], v[138:141], v[206:209], v[106:109]
	v_mfma_f32_16x16x32_bf16 v[98:101], v[146:149], v[206:209], v[98:101]
	v_mfma_f32_16x16x32_bf16 v[90:93], v[138:141], v[224:227], v[90:93]
	v_mfma_f32_16x16x32_bf16 v[82:85], v[146:149], v[224:227], v[82:85]
	s_waitcnt lgkmcnt(0)
	v_mfma_f32_16x16x32_bf16 v[74:77], v[138:141], v[232:235], v[74:77]
	v_mfma_f32_16x16x32_bf16 v[66:69], v[146:149], v[232:235], v[66:69]
	v_mfma_f32_16x16x32_bf16 v[126:129], v[150:153], v[184:187], v[126:129]
	v_mfma_f32_16x16x32_bf16 v[118:121], v[158:161], v[184:187], v[118:121]
	v_mfma_f32_16x16x32_bf16 v[110:113], v[150:153], v[202:205], v[110:113]
	v_mfma_f32_16x16x32_bf16 v[102:105], v[158:161], v[202:205], v[102:105]
	v_mfma_f32_16x16x32_bf16 v[94:97], v[150:153], v[210:213], v[94:97]
	v_mfma_f32_16x16x32_bf16 v[86:89], v[158:161], v[210:213], v[86:89]
	v_mfma_f32_16x16x32_bf16 v[78:81], v[150:153], v[228:231], v[78:81]
	v_mfma_f32_16x16x32_bf16 v[70:73], v[158:161], v[228:231], v[70:73]
	v_mfma_f32_16x16x32_bf16 v[126:129], v[154:157], v[198:201], v[126:129]
	v_mfma_f32_16x16x32_bf16 v[118:121], v[180:183], v[198:201], v[118:121]
	v_mfma_f32_16x16x32_bf16 v[110:113], v[154:157], v[206:209], v[110:113]
	v_mfma_f32_16x16x32_bf16 v[102:105], v[180:183], v[206:209], v[102:105]
	v_mfma_f32_16x16x32_bf16 v[94:97], v[154:157], v[224:227], v[94:97]
	v_mfma_f32_16x16x32_bf16 v[86:89], v[180:183], v[224:227], v[86:89]
	v_mfma_f32_16x16x32_bf16 v[78:81], v[154:157], v[232:235], v[78:81]
	v_mfma_f32_16x16x32_bf16 v[70:73], v[180:183], v[232:235], v[70:73]
	s_barrier
; #define PG8_STAGE(bufoff, gbase, voff) do { _Pragma("unroll") for (int _i = 0; _i < 2; ++_i) \
;         glds16_asm((const char*)(gbase) + (voff)[_i], ldsb + (unsigned)((bufoff) + _i * 8192)); } while (0)
; #define PG8_LDA(dst, b, h) do { _Pragma("unroll") for (int m = 0; m < 4; ++m) _Pragma("unroll") for (int k = 0; k < 2; ++k) dst[m][k] = *(const PG8_LAS bf16x8*)(lds + PG8_SA(b, h) + aoff + m * 2048 + k * 1024); } while (0)
; #define PG8_LDB(dst, b, h) do { _Pragma("unroll") for (int n = 0; n < 2; ++n) _Pragma("unroll") for (int k = 0; k < 2; ++k) dst[n][k] = *(const PG8_LAS bf16x8*)(lds + PG8_SB(b, h) + boff + n * 2048 + k * 1024); } while (0)
; #define PG8_MMA(ai, bj, At, Bt) do { __builtin_amdgcn_s_setprio(1); _Pragma("unroll") for (int m = 0; m < 4; ++m) _Pragma("unroll") for (int n = 0; n < 2; ++n) _Pragma("unroll") for (int k = 0; k < 2; ++k) \
;         acc[ai][bj][m][n] = __builtin_amdgcn_mfma_f32_16x16x32_bf16(Bt[n][k], At[m][k], acc[ai][bj][m][n], 0, 0, 0); __builtin_amdgcn_s_setprio(0); } while (0)
; #define PG8_WAIT_V(n) asm volatile("s_waitcnt vmcnt(" #n ")" ::: "memory")
; #define PG8_BAR __builtin_amdgcn_s_barrier()
; template <class Epi, class Sched, bool ALIGN_EPI = false, bool SP2 = false>
; __device__ __forceinline__ void gemm_phase(PG8_LAS unsigned char* lds, const Gemm g, const Sched& S, const Epi& E, int wave_u) {
;     ...
;             PG8_LDB(B0, 0, 0); PG8_LDB(B1, 0, 1); PG8_SCHED; PG8_LDA(At, 0, 0); PG8_STAGE(PG8_SA(1, 1), a1 + hstep, voffA);
;             PG8_WAIT_V(8); PG8_WAIT_L(0); PG8_BAR; PG8_MMA(0, 0, At, B0); PG8_MMA(0, 1, At, B1); PG8_BAR; PG8_SCHED;
;             PG8_LDA(At, 0, 1); PG8_STAGE(PG8_SB(0, 0), b2, voffB); PG8_STAGE(PG8_SB(0, 1), b2 + hstep, voffB); PG8_STAGE(PG8_SA(0, 0), a2, voffA);
;             PG8_WAIT_V(8); PG8_WAIT_L(0); PG8_BAR; PG8_MMA(1, 0, At, B0); PG8_MMA(1, 1, At, B1); PG8_BAR; PG8_SCHED;
;             PG8_LDB(B0, 1, 0); PG8_LDB(B1, 1, 1); PG8_SCHED; PG8_LDA(At, 1, 0); PG8_STAGE(PG8_SA(0, 1), a2 + hstep, voffA);
;             PG8_WAIT_V(8); PG8_WAIT_L(0); PG8_BAR; PG8_MMA(0, 0, At, B0); PG8_MMA(0, 1, At, B1); PG8_BAR; PG8_SCHED;
;             PG8_LDA(At, 1, 1); PG8_STAGE(PG8_SB(1, 0), b3, voffB); PG8_STAGE(PG8_SB(1, 1), b3 + hstep, voffB); PG8_STAGE(PG8_SA(1, 0), a3, voffA);
;             PG8_WAIT_V(8); PG8_WAIT_L(0); PG8_BAR; PG8_MMA(1, 0, At, B0); PG8_MMA(1, 1, At, B1); PG8_BAR; PG8_SCHED;
	ds_read_b128 v[184:187], v178 offset:49152
	ds_read_b128 v[198:201], v178 offset:50176
	ds_read_b128 v[202:205], v178 offset:51200
	ds_read_b128 v[206:209], v178 offset:52224
	ds_read_b128 v[210:213], v178 offset:53248
	ds_read_b128 v[224:227], v178 offset:54272
	ds_read_b128 v[228:231], v178 offset:55296
	ds_read_b128 v[232:235], v178 offset:56320
	v_lshl_add_u64 v[188:189], s[46:47], 0, v[166:167]
	s_mov_b32 s48, m0
	s_mov_b32 m0, s66
	s_nop 0
	global_load_lds_dwordx4 v[188:189], off
	s_mov_b32 m0, s48
	s_add_u32 s34, s34, 0x40080
	v_lshl_add_u64 v[188:189], s[46:47], 0, v[162:163]
	s_mov_b32 s46, m0
	s_mov_b32 m0, s67
	s_nop 0
	global_load_lds_dwordx4 v[188:189], off
	s_mov_b32 m0, s46
	s_addc_u32 s35, s35, 0
	v_lshl_add_u64 v[188:189], s[34:35], 0, v[166:167]
	s_mov_b32 s46, m0
	s_mov_b32 m0, s79
	s_nop 0
	global_load_lds_dwordx4 v[188:189], off
	s_mov_b32 m0, s46
	v_lshl_add_u64 v[188:189], s[34:35], 0, v[162:163]
	s_mov_b32 s34, m0
	s_mov_b32 m0, s86
	s_nop 0
	global_load_lds_dwordx4 v[188:189], off
	s_mov_b32 m0, s34
	v_lshl_add_u64 v[188:189], s[44:45], 0, v[168:169]
	s_mov_b32 s34, m0
	s_mov_b32 m0, s75
	s_nop 0
	global_load_lds_dwordx4 v[188:189], off
	s_mov_b32 m0, s34
	v_lshl_add_u64 v[188:189], s[44:45], 0, v[164:165]
	s_mov_b32 s34, m0
	s_mov_b32 m0, s78
	s_nop 0
	global_load_lds_dwordx4 v[188:189], off
	s_mov_b32 m0, s34
	s_waitcnt vmcnt(8)
	s_waitcnt lgkmcnt(0)
	s_barrier
	s_waitcnt lgkmcnt(7)
	v_mfma_f32_16x16x32_bf16 v[58:61], v[134:137], v[184:187], v[58:61]
	v_mfma_f32_16x16x32_bf16 v[50:53], v[142:145], v[184:187], v[50:53]
	s_waitcnt lgkmcnt(5)
	v_mfma_f32_16x16x32_bf16 v[42:45], v[134:137], v[202:205], v[42:45]
	v_mfma_f32_16x16x32_bf16 v[34:37], v[142:145], v[202:205], v[34:37]
	s_waitcnt lgkmcnt(3)
	v_mfma_f32_16x16x32_bf16 v[26:29], v[134:137], v[210:213], v[26:29]
	v_mfma_f32_16x16x32_bf16 v[18:21], v[142:145], v[210:213], v[18:21]
	s_waitcnt lgkmcnt(1)
	v_mfma_f32_16x16x32_bf16 v[10:13], v[134:137], v[228:231], v[10:13]
	v_mfma_f32_16x16x32_bf16 v[2:5], v[142:145], v[228:231], v[2:5]
	v_mfma_f32_16x16x32_bf16 v[58:61], v[138:141], v[198:201], v[58:61]
	v_mfma_f32_16x16x32_bf16 v[50:53], v[146:149], v[198:201], v[50:53]
	v_mfma_f32_16x16x32_bf16 v[42:45], v[138:141], v[206:209], v[42:45]
	v_mfma_f32_16x16x32_bf16 v[34:37], v[146:149], v[206:209], v[34:37]
	v_mfma_f32_16x16x32_bf16 v[26:29], v[138:141], v[224:227], v[26:29]
	v_mfma_f32_16x16x32_bf16 v[18:21], v[146:149], v[224:227], v[18:21]
	s_waitcnt lgkmcnt(0)
	v_mfma_f32_16x16x32_bf16 v[10:13], v[138:141], v[232:235], v[10:13]
	v_mfma_f32_16x16x32_bf16 v[2:5], v[146:149], v[232:235], v[2:5]
	v_mfma_f32_16x16x32_bf16 v[62:65], v[150:153], v[184:187], v[62:65]
	v_mfma_f32_16x16x32_bf16 v[54:57], v[158:161], v[184:187], v[54:57]
	v_mfma_f32_16x16x32_bf16 v[46:49], v[150:153], v[202:205], v[46:49]
	v_mfma_f32_16x16x32_bf16 v[38:41], v[158:161], v[202:205], v[38:41]
	v_mfma_f32_16x16x32_bf16 v[30:33], v[150:153], v[210:213], v[30:33]
	v_mfma_f32_16x16x32_bf16 v[22:25], v[158:161], v[210:213], v[22:25]
	v_mfma_f32_16x16x32_bf16 v[14:17], v[150:153], v[228:231], v[14:17]
	v_mfma_f32_16x16x32_bf16 v[6:9], v[158:161], v[228:231], v[6:9]
	v_mfma_f32_16x16x32_bf16 v[62:65], v[154:157], v[198:201], v[62:65]
	v_mfma_f32_16x16x32_bf16 v[54:57], v[180:183], v[198:201], v[54:57]
	v_mfma_f32_16x16x32_bf16 v[46:49], v[154:157], v[206:209], v[46:49]
	v_mfma_f32_16x16x32_bf16 v[38:41], v[180:183], v[206:209], v[38:41]
	v_mfma_f32_16x16x32_bf16 v[30:33], v[154:157], v[224:227], v[30:33]
	v_mfma_f32_16x16x32_bf16 v[22:25], v[180:183], v[224:227], v[22:25]
	v_mfma_f32_16x16x32_bf16 v[14:17], v[154:157], v[232:235], v[14:17]
	v_mfma_f32_16x16x32_bf16 v[6:9], v[180:183], v[232:235], v[6:9]
	s_barrier
	s_add_i32 s1, s1, 2
	s_add_u32 s60, s60, 0x100
	s_addc_u32 s61, s61, 0
	s_add_u32 s84, s84, 0x100
	s_addc_u32 s85, s85, 0
	s_cmp_gt_u32 s1, 13
	s_cbranch_scc1 .LBB0_1178

; template <class Epi, class Sched, bool ALIGN_EPI = false, bool SP2 = false>
; __device__ __forceinline__ void gemm_phase(PG8_LAS unsigned char* lds, const Gemm g, const Sched& S, const Epi& E, int wave_u) {
;     ...
;     const int tid = tid_, wid = __builtin_amdgcn_readfirstlane(tid >> 6), lane = tid & 63, wr = wid >> 2, wc = wid & 3, fr = lane & 15, fq = lane >> 4;
;     const int K = g.K, nt = K / BK;
;     unsigned voffA[2], voffB[2];
; #pragma unroll
;     for (int i = 0; i < 2; ++i) { int R, C; stage_rc(tid * 16 + i * 8192, R, C); const int Rb = Epi::PERM ? ((R & ~31) + perm32(R & 31)) : R;
;         voffA[i] = (unsigned)(R * K + C) * 2u; voffB[i] = (unsigned)(Rb * K + C) * 2u; }
;     const size_t kstep = (size_t)(BK * 2);
;     const size_t hstep = (size_t)HALF * K * 2;
;     const size_t tstep = 2 * hstep;
;     const unsigned ldsw = (unsigned)wid * 1024u;
;     const unsigned ldsb = (unsigned)__builtin_amdgcn_readfirstlane((int)((unsigned)(size_t)lds + ldsw));
;     const int aoff = lds_byte(wr * 64 + fr, fq * 8), boff = lds_byte(wc * 32 + fr, fq * 8);
.LBB0_1411:
	v_readlane_b32 s0, v255, 43
	v_readlane_b32 s1, v255, 44
	s_add_u32 s30, s0, 0x1300000
	s_addc_u32 s31, s1, 0
	v_readlane_b32 s0, v255, 62
	v_readlane_b32 s1, v255, 63
	s_lshl_b64 s[0:1], s[0:1], 12
	s_waitcnt lgkmcnt(0)
	s_add_u32 s58, s12, s0
	s_addc_u32 s59, s13, s1
	s_add_u32 s14, s14, s0
	s_addc_u32 s15, s15, s1
	v_readlane_b32 s0, v255, 57
	s_add_u32 s34, s0, 0x120800
	v_readlane_b32 s0, v255, 59
	s_addc_u32 s35, s0, 0
	s_andn2_b64 vcc, exec, s[10:11]
	s_cbranch_vccnz .LBB0_1453
	s_waitcnt vmcnt(0)
	v_bfe_i32 v3, v50, 27, 1
	v_lshlrev_b32_e32 v0, 4, v50
	v_lshrrev_b32_e32 v3, 22, v3
	v_add_u32_e32 v3, v0, v3
	v_and_b32_e32 v3, 0xfffffc00, v3
	v_sub_u32_e32 v3, v0, v3
	v_lshrrev_b32_e32 v4, 4, v3
	v_ashrrev_i32_e32 v51, 31, v50
	v_bitop3_b32 v3, v4, v3, 32 bitop3:0x6c
	v_lshrrev_b32_e32 v2, 26, v51
	v_ashrrev_i32_e32 v5, 31, v3
	v_add_u32_e32 v2, v50, v2
	v_lshrrev_b32_e32 v5, 26, v5
	v_ashrrev_i32_e32 v2, 6, v2
	v_add_u32_e32 v5, v3, v5
	v_lshlrev_b32_e32 v4, 3, v2
	v_ashrrev_i32_e32 v6, 6, v5
	v_and_b32_e32 v5, 0xc0, v5
	v_and_b32_e32 v4, -16, v4
	v_lshlrev_b32_e32 v2, 5, v2
	v_sub_u32_e32 v3, v3, v5
	v_mov_b32_e32 v7, 1
	v_add_u32_e32 v4, v6, v4
	v_and_b32_e32 v2, 32, v2
	v_ashrrev_i16_sdwa v3, v7, sext(v3) dst_sel:DWORD dst_unused:UNUSED_PAD src0_sel:DWORD src1_sel:BYTE_0
	v_add_u32_sdwa v2, v2, sext(v3) dst_sel:DWORD dst_unused:UNUSED_PAD src0_sel:DWORD src1_sel:WORD_0
	v_lshlrev_b32_e32 v3, 1, v4
	v_lshrrev_b32_e32 v5, 2, v4
	v_and_b32_e32 v6, 3, v6
	s_mov_b32 s1, 0xffffe0
	v_and_b32_e32 v3, 24, v3
	v_and_b32_e32 v5, 4, v5
	v_and_or_b32 v6, v4, s1, v6
	v_or3_b32 v3, v6, v5, v3
	s_movk_i32 s10, 0xb00
	v_mul_lo_u32 v4, v4, s10
	v_mul_u32_u24_e32 v3, 0xb00, v3
	v_add_u32_e32 v0, 0x2000, v0
	v_add_lshl_u32 v198, v2, v4, 1
	v_add_lshl_u32 v200, v3, v2, 1
	v_ashrrev_i32_e32 v2, 31, v0
	v_lshrrev_b32_e32 v2, 22, v2
	v_add_u32_e32 v2, v0, v2
	v_ashrrev_i32_e32 v2, 10, v2
	v_mul_i32_i24_e32 v3, 0x400, v2
	v_sub_u32_e32 v0, v0, v3
	v_lshrrev_b32_e32 v3, 4, v0
	v_bitop3_b32 v0, v3, v0, 32 bitop3:0x6c
	v_ashrrev_i32_e32 v4, 31, v0
	v_lshrrev_b32_e32 v4, 26, v4
	v_lshlrev_b32_e32 v3, 3, v2
	v_add_u32_e32 v4, v0, v4
	v_and_b32_e32 v3, -16, v3
	v_ashrrev_i32_e32 v5, 6, v4
	v_add_u32_e32 v3, v5, v3
	v_and_b32_e32 v5, 3, v5
	v_and_or_b32 v5, v3, s1, v5
	s_lshl_b32 s1, s7, 10
	v_and_b32_e32 v4, 0xc0, v4
	s_add_i32 s84, s1, 0
	s_lshl_b32 s1, s7, 8
	v_lshlrev_b32_e32 v2, 5, v2
	v_sub_u32_e32 v0, v0, v4
	s_add_i32 s1, s1, 0
	s_ashr_i32 s0, s18, 8
	v_and_b32_e32 v2, 32, v2
	v_ashrrev_i16_sdwa v0, v7, sext(v0) dst_sel:DWORD dst_unused:UNUSED_PAD src0_sel:DWORD src1_sel:BYTE_0
	s_add_i32 s85, s1, 0x20400
	s_ashr_i32 s27, s26, 31
	s_mul_i32 s11, s52, 0x160000
	v_add_u32_sdwa v0, v2, sext(v0) dst_sel:DWORD dst_unused:UNUSED_PAD src0_sel:DWORD src1_sel:WORD_0
	v_lshlrev_b32_e32 v2, 1, v3
	v_lshrrev_b32_e32 v4, 2, v3
	v_mul_lo_u32 v3, v3, s10
	s_mul_hi_i32 s10, s52, 0x160000
	s_add_u32 s60, s30, s11
	v_and_b32_e32 v2, 24, v2
	v_and_b32_e32 v4, 4, v4
	s_addc_u32 s61, s31, s10
	s_lshl_b64 s[10:11], s[26:27], 11
	v_or3_b32 v2, v5, v4, v2
	s_add_u32 s10, s28, s10
	v_mul_u32_u24_e32 v2, 0xb00, v2
	s_addc_u32 s11, s29, s11
	v_lshlrev_b64 v[52:53], 2, v[50:51]
	v_add_lshl_u32 v202, v0, v3, 1
	v_add_lshl_u32 v204, v2, v0, 1
	v_pk_mov_b32 v[170:171], 0, 0
	v_pk_mov_b32 v[172:173], 0, 0
	v_pk_mov_b32 v[166:167], 0, 0
	v_pk_mov_b32 v[168:169], 0, 0
	v_pk_mov_b32 v[142:143], 0, 0
	v_pk_mov_b32 v[144:145], 0, 0
	v_pk_mov_b32 v[134:135], 0, 0
	v_pk_mov_b32 v[136:137], 0, 0
	v_pk_mov_b32 v[118:119], 0, 0
	v_pk_mov_b32 v[120:121], 0, 0
	v_pk_mov_b32 v[110:111], 0, 0
	v_pk_mov_b32 v[112:113], 0, 0
	v_pk_mov_b32 v[94:95], 0, 0
	v_pk_mov_b32 v[96:97], 0, 0
	v_pk_mov_b32 v[86:87], 0, 0
	v_pk_mov_b32 v[88:89], 0, 0
	v_pk_mov_b32 v[154:155], 0, 0
	v_pk_mov_b32 v[156:157], 0, 0
	v_pk_mov_b32 v[150:151], 0, 0
	v_pk_mov_b32 v[152:153], 0, 0
	v_pk_mov_b32 v[130:131], 0, 0
; __device__ __forceinline__ f32x4 zero4_pk() { f32x2_z a, b; asm volatile("v_pk_mov_b32 %0, 0, 0" : "=v"(a)); asm volatile("v_pk_mov_b32 %0, 0, 0" : "=v"(b)); return (f32x4){a.x, a.y, b.x, b.y}; }
; #define PG8_STAGE(bufoff, gbase, voff) do { _Pragma("unroll") for (int _i = 0; _i < 2; ++_i) \
;         glds16_asm((const char*)(gbase) + (voff)[_i], ldsb + (unsigned)((bufoff) + _i * 8192)); } while (0)
; #define PG8_WAIT_V(n) asm volatile("s_waitcnt vmcnt(" #n ")" ::: "memory")
; #define PG8_BAR __builtin_amdgcn_s_barrier()
; template <class Epi, class Sched, bool ALIGN_EPI = false, bool SP2 = false>
; __device__ __forceinline__ void gemm_phase(PG8_LAS unsigned char* lds, const Gemm g, const Sched& S, const Epi& E, int wave_u) {
;     ...
;     f32x4 acc[2][2][4][2];
; #pragma unroll
;     for (int a = 0; a < 2; ++a)
; #pragma unroll
;         for (int b = 0; b < 2; ++b)
; #pragma unroll
;             for (int m = 0; m < 4; ++m)
; #pragma unroll
;                 for (int n = 0; n < 2; ++n) acc[a][b][m][n] = zero4_pk();
;     bf16x8 At[4][2], B0[2][2], B1[2][2];
;     const char* cA = (const char*)g.A + (size_t)cur.pm * tstep; const char* cB = (const char*)g.Bt + (size_t)cur.pn * tstep;
;     S.a_ready(cur);
;     epi_prefetch(E, cur.pm, cur.pn, evb, tid);
;     if constexpr (SP2) {
;         PG8_STAGE(PG8_SB(0, 0), cB, voffB); PG8_STAGE(PG8_SB(0, 1), cB + hstep, voffB); PG8_STAGE(PG8_SA(0, 0), cA, voffA); PG8_STAGE(PG8_SA(0, 1), cA + hstep, voffA);
;         if (wr == 1) PG8_BAR;
;         PG8_WAIT_V(2); PG8_BAR;
;         PG8_STAGE(PG8_SB(1, 0), cB + kstep, voffB); PG8_STAGE(PG8_SA(1, 0), cA + kstep, voffA); PG8_STAGE(PG8_SB(1, 1), cB + hstep + kstep, voffB);
;         PG8_WAIT_V(6); PG8_BAR;
;     } else {
;         PG8_STAGE(PG8_SB(0, 0), cB, voffB); PG8_STAGE(PG8_SA(0, 0), cA, voffA); PG8_STAGE(PG8_SB(0, 1), cB + hstep, voffB); PG8_STAGE(PG8_SA(0, 1), cA + hstep, voffA);
;         if (wr == 1) PG8_BAR;
;         PG8_WAIT_V(4); PG8_BAR;
;         PG8_STAGE(PG8_SB(1, 0), cB + kstep, voffB); PG8_STAGE(PG8_SA(1, 0), cA + kstep, voffA); PG8_STAGE(PG8_SB(1, 1), cB + hstep + kstep, voffB);
;         PG8_WAIT_V(6); PG8_BAR;
	v_pk_mov_b32 v[132:133], 0, 0
	v_pk_mov_b32 v[126:127], 0, 0
	v_pk_mov_b32 v[128:129], 0, 0
	v_pk_mov_b32 v[106:107], 0, 0
	v_pk_mov_b32 v[108:109], 0, 0
	v_pk_mov_b32 v[102:103], 0, 0
	v_pk_mov_b32 v[104:105], 0, 0
	v_pk_mov_b32 v[82:83], 0, 0
	v_pk_mov_b32 v[84:85], 0, 0
	v_pk_mov_b32 v[78:79], 0, 0
	v_pk_mov_b32 v[80:81], 0, 0
	v_pk_mov_b32 v[70:71], 0, 0
	v_pk_mov_b32 v[72:73], 0, 0
	v_pk_mov_b32 v[66:67], 0, 0
	v_pk_mov_b32 v[68:69], 0, 0
	v_pk_mov_b32 v[46:47], 0, 0
	v_pk_mov_b32 v[48:49], 0, 0
	v_pk_mov_b32 v[42:43], 0, 0
	v_pk_mov_b32 v[44:45], 0, 0
	v_pk_mov_b32 v[30:31], 0, 0
	v_pk_mov_b32 v[32:33], 0, 0
	v_pk_mov_b32 v[26:27], 0, 0
	v_pk_mov_b32 v[28:29], 0, 0
	v_pk_mov_b32 v[14:15], 0, 0
	v_pk_mov_b32 v[16:17], 0, 0
	v_pk_mov_b32 v[10:11], 0, 0
	v_pk_mov_b32 v[12:13], 0, 0
	v_pk_mov_b32 v[58:59], 0, 0
	v_pk_mov_b32 v[60:61], 0, 0
	v_pk_mov_b32 v[54:55], 0, 0
	v_pk_mov_b32 v[56:57], 0, 0
	v_pk_mov_b32 v[38:39], 0, 0
	v_pk_mov_b32 v[40:41], 0, 0
	v_pk_mov_b32 v[34:35], 0, 0
	v_pk_mov_b32 v[36:37], 0, 0
	v_pk_mov_b32 v[22:23], 0, 0
	v_pk_mov_b32 v[24:25], 0, 0
	v_pk_mov_b32 v[18:19], 0, 0
	v_pk_mov_b32 v[20:21], 0, 0
	v_pk_mov_b32 v[6:7], 0, 0
	v_pk_mov_b32 v[8:9], 0, 0
	v_pk_mov_b32 v[2:3], 0, 0
	v_pk_mov_b32 v[4:5], 0, 0
	v_lshl_add_u64 v[62:63], s[10:11], 0, v[52:53]
	s_mov_b32 s10, m0
	s_mov_b32 m0, s85
	s_nop 0
	global_load_lds_dword v[62:63], off
	s_mov_b32 m0, s10
	s_movk_i32 s10, 0x100
	v_cmp_gt_i32_e32 vcc, s10, v50
	s_add_u32 s10, s14, 0xfffffc00
	s_addc_u32 s11, s15, -1
	v_mov_b32_e32 v0, s11
	v_mov_b32_e32 v51, s59
	v_cndmask_b32_e32 v63, v0, v51, vcc
	v_mov_b32_e32 v0, s10
	v_mov_b32_e32 v51, s58
	s_lshl_b32 s10, s52, 8
	v_cndmask_b32_e32 v62, v0, v51, vcc
	s_ashr_i32 s11, s10, 31
	v_lshl_add_u64 v[64:65], s[10:11], 2, v[62:63]
	v_lshl_add_u64 v[64:65], v[64:65], 0, v[52:53]
	s_add_i32 s1, s1, 0x20c00
	s_mov_b32 s10, m0
	s_mov_b32 m0, s1
	s_nop 0
	global_load_lds_dword v[64:65], off
	s_mov_b32 m0, s10
	s_add_i32 s27, s84, 0x10000
	v_mov_b32_e32 v201, v1
	s_add_i32 s86, s84, 0x12000
	v_lshl_add_u64 v[64:65], s[60:61], 0, v[200:201]
	s_mov_b32 s1, m0
	s_mov_b32 m0, s27
	s_nop 0
	global_load_lds_dwordx4 v[64:65], off
	s_mov_b32 m0, s1
	v_mov_b32_e32 v205, v1
	s_add_u32 s10, s60, 0xb0000
	s_mul_i32 s13, s26, 0x160000
	v_lshl_add_u64 v[64:65], s[60:61], 0, v[204:205]
	s_mov_b32 s1, m0
	s_mov_b32 m0, s86
	s_nop 0
	global_load_lds_dwordx4 v[64:65], off
	s_mov_b32 m0, s1
	s_addc_u32 s11, s61, 0
	s_add_i32 s87, s84, 0x14000
	s_add_i32 s88, s84, 0x16000
	s_mul_hi_i32 s12, s26, 0x160000
	v_lshl_add_u64 v[64:65], s[10:11], 0, v[200:201]
	s_mov_b32 s1, m0
	s_mov_b32 m0, s87
	s_nop 0
	global_load_lds_dwordx4 v[64:65], off
	s_mov_b32 m0, s1
	s_add_u32 s64, s64, s13
	v_lshl_add_u64 v[64:65], s[10:11], 0, v[204:205]
	s_mov_b32 s1, m0
	s_mov_b32 m0, s88
	s_nop 0
	global_load_lds_dwordx4 v[64:65], off
	s_mov_b32 m0, s1
	s_addc_u32 s65, s65, s12
	v_mov_b32_e32 v199, v1
	s_add_i32 s89, s84, 0x2000
	v_lshl_add_u64 v[64:65], s[64:65], 0, v[198:199]
	s_mov_b32 s1, m0
	s_mov_b32 m0, s84
	s_nop 0
	global_load_lds_dwordx4 v[64:65], off
	s_mov_b32 m0, s1
	v_mov_b32_e32 v203, v1
	s_add_u32 s10, s64, 0xb0000
	v_lshl_add_u64 v[64:65], s[64:65], 0, v[202:203]
	s_mov_b32 s1, m0
	s_mov_b32 m0, s89
	s_nop 0
	global_load_lds_dwordx4 v[64:65], off
	s_mov_b32 m0, s1
	s_addc_u32 s11, s65, 0
	s_add_i32 s90, s84, 0x4000
	v_lshl_add_u64 v[64:65], s[10:11], 0, v[198:199]
	s_mov_b32 s1, m0
	s_mov_b32 m0, s90
	s_nop 0
	global_load_lds_dwordx4 v[64:65], off
	s_mov_b32 m0, s1
	v_lshl_add_u64 v[64:65], s[10:11], 0, v[202:203]
	s_add_i32 s91, s84, 0x6000
	s_mov_b32 s1, m0
	s_mov_b32 m0, s91
	s_nop 0
	global_load_lds_dwordx4 v[64:65], off
	s_mov_b32 m0, s1
	v_writelane_b32 v255, s14, 43
	s_cmp_eq_u32 s0, 1
	v_mov_b32_e32 v215, 1
	v_writelane_b32 v255, s15, 45
	s_cselect_b64 s[16:17], -1, 0
	s_cmp_lg_u32 s0, 1
	s_cbranch_scc1 .LBB0_1414
	s_setprio 1
	s_barrier

; #define PG8_STAGE(bufoff, gbase, voff) do { _Pragma("unroll") for (int _i = 0; _i < 2; ++_i) \
;         glds16_asm((const char*)(gbase) + (voff)[_i], ldsb + (unsigned)((bufoff) + _i * 8192)); } while (0)
; #define PG8_LDA(dst, b, h) do { _Pragma("unroll") for (int m = 0; m < 4; ++m) _Pragma("unroll") for (int k = 0; k < 2; ++k) dst[m][k] = *(const PG8_LAS bf16x8*)(lds + PG8_SA(b, h) + aoff + m * 2048 + k * 1024); } while (0)
; #define PG8_LDB(dst, b, h) do { _Pragma("unroll") for (int n = 0; n < 2; ++n) _Pragma("unroll") for (int k = 0; k < 2; ++k) dst[n][k] = *(const PG8_LAS bf16x8*)(lds + PG8_SB(b, h) + boff + n * 2048 + k * 1024); } while (0)
; #define PG8_MMA(ai, bj, At, Bt) do { __builtin_amdgcn_s_setprio(1); _Pragma("unroll") for (int m = 0; m < 4; ++m) _Pragma("unroll") for (int n = 0; n < 2; ++n) _Pragma("unroll") for (int k = 0; k < 2; ++k) \
;         acc[ai][bj][m][n] = __builtin_amdgcn_mfma_f32_16x16x32_bf16(Bt[n][k], At[m][k], acc[ai][bj][m][n], 0, 0, 0); __builtin_amdgcn_s_setprio(0); } while (0)
; #define PG8_WAIT_V(n) asm volatile("s_waitcnt vmcnt(" #n ")" ::: "memory")
; #define PG8_BAR __builtin_amdgcn_s_barrier()
; template <class Epi, class Sched, bool ALIGN_EPI = false, bool SP2 = false>
; __device__ __forceinline__ void gemm_phase(PG8_LAS unsigned char* lds, const Gemm g, const Sched& S, const Epi& E, int wave_u) {
;     ...
;             PG8_LDB(B0, 0, 0); PG8_LDB(B1, 0, 1); PG8_SCHED; PG8_LDA(At, 0, 0); PG8_STAGE(PG8_SA(1, 1), a1 + hstep, voffA);
;             PG8_WAIT_V(8); PG8_WAIT_L(0); PG8_BAR; PG8_MMA(0, 0, At, B0); PG8_MMA(0, 1, At, B1); PG8_BAR; PG8_SCHED;
;             PG8_LDA(At, 0, 1); PG8_STAGE(PG8_SB(0, 0), b2, voffB); PG8_STAGE(PG8_SB(0, 1), b2 + hstep, voffB); PG8_STAGE(PG8_SA(0, 0), a2, voffA);
;             PG8_WAIT_V(8); PG8_WAIT_L(0); PG8_BAR; PG8_MMA(1, 0, At, B0); PG8_MMA(1, 1, At, B1); PG8_BAR; PG8_SCHED;
;             PG8_LDB(B0, 1, 0); PG8_LDB(B1, 1, 1); PG8_SCHED; PG8_LDA(At, 1, 0); PG8_STAGE(PG8_SA(0, 1), a2 + hstep, voffA);
;             PG8_WAIT_V(8); PG8_WAIT_L(0); PG8_BAR; PG8_MMA(0, 0, At, B0); PG8_MMA(0, 1, At, B1); PG8_BAR; PG8_SCHED;
;             PG8_LDA(At, 1, 1); PG8_STAGE(PG8_SB(1, 0), b3, voffB); PG8_STAGE(PG8_SB(1, 1), b3 + hstep, voffB); PG8_STAGE(PG8_SA(1, 0), a3, voffA);
;             PG8_WAIT_V(8); PG8_WAIT_L(0); PG8_BAR; PG8_MMA(1, 0, At, B0); PG8_MMA(1, 1, At, B1); PG8_BAR; PG8_SCHED;
.LBB0_1428:
	v_add_u32_e32 v0, 0x10000, v227
	ds_read_b128 v[62:65], v0
	ds_read_b128 v[74:77], v0 offset:1024
	ds_read_b128 v[90:93], v0 offset:2048
	ds_read_b128 v[98:101], v0 offset:3072
	v_add_u32_e32 v0, 0x14000, v227
	s_add_u32 s46, s28, 0xfff50080
	ds_read_b128 v[114:117], v0
	ds_read_b128 v[122:125], v0 offset:1024
	ds_read_b128 v[138:141], v0 offset:2048
	ds_read_b128 v[146:149], v0 offset:3072
	s_addc_u32 s47, s29, -1
	s_and_b64 s[44:45], s[44:45], exec
	s_cselect_b32 s56, s22, s46
	s_cselect_b32 s57, s23, s47
	s_cselect_b32 s45, s25, s61
	s_cselect_b32 s44, s24, s60
	s_add_u32 s46, s56, 0x80
	s_addc_u32 s47, s57, 0
	s_add_u32 s48, s44, 0x80
	s_addc_u32 s49, s45, 0
	ds_read_b128 v[158:161], v228
	ds_read_b128 v[162:165], v228 offset:1024
	ds_read_b128 v[174:177], v228 offset:2048
	ds_read_b128 v[178:181], v228 offset:3072
	ds_read_b128 v[182:185], v228 offset:4096
	ds_read_b128 v[186:189], v228 offset:5120
	ds_read_b128 v[210:213], v228 offset:6144
	ds_read_b128 v[230:233], v228 offset:7168
	v_lshl_add_u64 v[190:191], s[28:29], 0, v[198:199]
	s_mov_b32 s64, m0
	s_mov_b32 m0, s7
	s_nop 0
	global_load_lds_dwordx4 v[190:191], off
	s_mov_b32 m0, s64
	v_lshl_add_u64 v[190:191], s[28:29], 0, v[202:203]
	s_mov_b32 s64, m0
	s_mov_b32 m0, s75
	s_nop 0
	global_load_lds_dwordx4 v[190:191], off
	s_mov_b32 m0, s64
	s_waitcnt vmcnt(8)
	s_waitcnt lgkmcnt(0)
	s_barrier
	s_waitcnt lgkmcnt(7)
	v_mfma_f32_16x16x32_bf16 v[170:173], v[62:65], v[158:161], v[170:173]
	v_mfma_f32_16x16x32_bf16 v[166:169], v[90:93], v[158:161], v[166:169]
	s_waitcnt lgkmcnt(5)
	v_mfma_f32_16x16x32_bf16 v[142:145], v[62:65], v[174:177], v[142:145]
	v_mfma_f32_16x16x32_bf16 v[134:137], v[90:93], v[174:177], v[134:137]
	s_waitcnt lgkmcnt(3)
	v_mfma_f32_16x16x32_bf16 v[118:121], v[62:65], v[182:185], v[118:121]
	v_mfma_f32_16x16x32_bf16 v[110:113], v[90:93], v[182:185], v[110:113]
	s_waitcnt lgkmcnt(1)
	v_mfma_f32_16x16x32_bf16 v[94:97], v[62:65], v[210:213], v[94:97]
	v_mfma_f32_16x16x32_bf16 v[86:89], v[90:93], v[210:213], v[86:89]
	v_mfma_f32_16x16x32_bf16 v[170:173], v[74:77], v[162:165], v[170:173]
	v_mfma_f32_16x16x32_bf16 v[166:169], v[98:101], v[162:165], v[166:169]
	v_mfma_f32_16x16x32_bf16 v[142:145], v[74:77], v[178:181], v[142:145]
	v_mfma_f32_16x16x32_bf16 v[134:137], v[98:101], v[178:181], v[134:137]
	v_mfma_f32_16x16x32_bf16 v[118:121], v[74:77], v[186:189], v[118:121]
	v_mfma_f32_16x16x32_bf16 v[110:113], v[98:101], v[186:189], v[110:113]
	s_waitcnt lgkmcnt(0)
	v_mfma_f32_16x16x32_bf16 v[94:97], v[74:77], v[230:233], v[94:97]
	v_mfma_f32_16x16x32_bf16 v[86:89], v[98:101], v[230:233], v[86:89]
	v_mfma_f32_16x16x32_bf16 v[154:157], v[114:117], v[158:161], v[154:157]
	v_mfma_f32_16x16x32_bf16 v[150:153], v[138:141], v[158:161], v[150:153]
	v_mfma_f32_16x16x32_bf16 v[130:133], v[114:117], v[174:177], v[130:133]
	v_mfma_f32_16x16x32_bf16 v[126:129], v[138:141], v[174:177], v[126:129]
	v_mfma_f32_16x16x32_bf16 v[106:109], v[114:117], v[182:185], v[106:109]
	v_mfma_f32_16x16x32_bf16 v[102:105], v[138:141], v[182:185], v[102:105]
	v_mfma_f32_16x16x32_bf16 v[82:85], v[114:117], v[210:213], v[82:85]
	v_mfma_f32_16x16x32_bf16 v[78:81], v[138:141], v[210:213], v[78:81]
	v_mfma_f32_16x16x32_bf16 v[154:157], v[122:125], v[162:165], v[154:157]
	v_mfma_f32_16x16x32_bf16 v[150:153], v[146:149], v[162:165], v[150:153]
	v_mfma_f32_16x16x32_bf16 v[130:133], v[122:125], v[178:181], v[130:133]
	v_mfma_f32_16x16x32_bf16 v[126:129], v[146:149], v[178:181], v[126:129]
	v_mfma_f32_16x16x32_bf16 v[106:109], v[122:125], v[186:189], v[106:109]
	v_mfma_f32_16x16x32_bf16 v[102:105], v[146:149], v[186:189], v[102:105]
	v_mfma_f32_16x16x32_bf16 v[82:85], v[122:125], v[230:233], v[82:85]
	v_mfma_f32_16x16x32_bf16 v[78:81], v[146:149], v[230:233], v[78:81]
	s_barrier
	ds_read_b128 v[158:161], v228 offset:16384
	ds_read_b128 v[162:165], v228 offset:17408
	ds_read_b128 v[174:177], v228 offset:18432
	ds_read_b128 v[178:181], v228 offset:19456
	ds_read_b128 v[182:185], v228 offset:20480
	ds_read_b128 v[186:189], v228 offset:21504
	ds_read_b128 v[210:213], v228 offset:22528
	ds_read_b128 v[230:233], v228 offset:23552
	v_lshl_add_u64 v[190:191], s[44:45], 0, v[200:201]
	s_mov_b32 s64, m0
	s_mov_b32 m0, s27
	s_nop 0
	global_load_lds_dwordx4 v[190:191], off
	s_mov_b32 m0, s64
	v_lshl_add_u64 v[190:191], s[44:45], 0, v[204:205]
	s_mov_b32 s64, m0
	s_mov_b32 m0, s86
	s_nop 0
	global_load_lds_dwordx4 v[190:191], off
	s_mov_b32 m0, s64
	s_add_u32 s64, s44, 0xb0000
	s_addc_u32 s65, s45, 0
	v_lshl_add_u64 v[190:191], s[64:65], 0, v[200:201]
	s_mov_b32 s92, m0
	s_mov_b32 m0, s87
	s_nop 0
	global_load_lds_dwordx4 v[190:191], off
	s_mov_b32 m0, s92
	v_lshl_add_u64 v[190:191], s[64:65], 0, v[204:205]
	s_mov_b32 s64, m0
	s_mov_b32 m0, s88
	s_nop 0
	global_load_lds_dwordx4 v[190:191], off
	s_mov_b32 m0, s64
	v_lshl_add_u64 v[190:191], s[56:57], 0, v[198:199]
	s_mov_b32 s64, m0
	s_mov_b32 m0, s84
	s_nop 0
	global_load_lds_dwordx4 v[190:191], off
	s_mov_b32 m0, s64
	v_lshl_add_u64 v[190:191], s[56:57], 0, v[202:203]
	s_mov_b32 s64, m0
	s_mov_b32 m0, s89
	s_nop 0
	global_load_lds_dwordx4 v[190:191], off
	s_mov_b32 m0, s64
	s_waitcnt vmcnt(8)
	s_waitcnt lgkmcnt(0)
	s_barrier
; #define PG8_STAGE(bufoff, gbase, voff) do { _Pragma("unroll") for (int _i = 0; _i < 2; ++_i) \
;         glds16_asm((const char*)(gbase) + (voff)[_i], ldsb + (unsigned)((bufoff) + _i * 8192)); } while (0)
; #define PG8_LDA(dst, b, h) do { _Pragma("unroll") for (int m = 0; m < 4; ++m) _Pragma("unroll") for (int k = 0; k < 2; ++k) dst[m][k] = *(const PG8_LAS bf16x8*)(lds + PG8_SA(b, h) + aoff + m * 2048 + k * 1024); } while (0)
; #define PG8_LDB(dst, b, h) do { _Pragma("unroll") for (int n = 0; n < 2; ++n) _Pragma("unroll") for (int k = 0; k < 2; ++k) dst[n][k] = *(const PG8_LAS bf16x8*)(lds + PG8_SB(b, h) + boff + n * 2048 + k * 1024); } while (0)
; #define PG8_MMA(ai, bj, At, Bt) do { __builtin_amdgcn_s_setprio(1); _Pragma("unroll") for (int m = 0; m < 4; ++m) _Pragma("unroll") for (int n = 0; n < 2; ++n) _Pragma("unroll") for (int k = 0; k < 2; ++k) \
;         acc[ai][bj][m][n] = __builtin_amdgcn_mfma_f32_16x16x32_bf16(Bt[n][k], At[m][k], acc[ai][bj][m][n], 0, 0, 0); __builtin_amdgcn_s_setprio(0); } while (0)
; #define PG8_WAIT_V(n) asm volatile("s_waitcnt vmcnt(" #n ")" ::: "memory")
; #define PG8_BAR __builtin_amdgcn_s_barrier()
; template <class Epi, class Sched, bool ALIGN_EPI = false, bool SP2 = false>
; __device__ __forceinline__ void gemm_phase(PG8_LAS unsigned char* lds, const Gemm g, const Sched& S, const Epi& E, int wave_u) {
;     ...
;             PG8_LDB(B0, 0, 0); PG8_LDB(B1, 0, 1); PG8_SCHED; PG8_LDA(At, 0, 0); PG8_STAGE(PG8_SA(1, 1), a1 + hstep, voffA);
;             PG8_WAIT_V(8); PG8_WAIT_L(0); PG8_BAR; PG8_MMA(0, 0, At, B0); PG8_MMA(0, 1, At, B1); PG8_BAR; PG8_SCHED;
;             PG8_LDA(At, 0, 1); PG8_STAGE(PG8_SB(0, 0), b2, voffB); PG8_STAGE(PG8_SB(0, 1), b2 + hstep, voffB); PG8_STAGE(PG8_SA(0, 0), a2, voffA);
;             PG8_WAIT_V(8); PG8_WAIT_L(0); PG8_BAR; PG8_MMA(1, 0, At, B0); PG8_MMA(1, 1, At, B1); PG8_BAR; PG8_SCHED;
;             PG8_LDB(B0, 1, 0); PG8_LDB(B1, 1, 1); PG8_SCHED; PG8_LDA(At, 1, 0); PG8_STAGE(PG8_SA(0, 1), a2 + hstep, voffA);
;             PG8_WAIT_V(8); PG8_WAIT_L(0); PG8_BAR; PG8_MMA(0, 0, At, B0); PG8_MMA(0, 1, At, B1); PG8_BAR; PG8_SCHED;
;             PG8_LDA(At, 1, 1); PG8_STAGE(PG8_SB(1, 0), b3, voffB); PG8_STAGE(PG8_SB(1, 1), b3 + hstep, voffB); PG8_STAGE(PG8_SA(1, 0), a3, voffA);
;             PG8_WAIT_V(8); PG8_WAIT_L(0); PG8_BAR; PG8_MMA(1, 0, At, B0); PG8_MMA(1, 1, At, B1); PG8_BAR; PG8_SCHED;
	s_waitcnt lgkmcnt(7)
	v_mfma_f32_16x16x32_bf16 v[70:73], v[62:65], v[158:161], v[70:73]
	v_mfma_f32_16x16x32_bf16 v[66:69], v[90:93], v[158:161], v[66:69]
	s_waitcnt lgkmcnt(5)
	v_mfma_f32_16x16x32_bf16 v[46:49], v[62:65], v[174:177], v[46:49]
	v_mfma_f32_16x16x32_bf16 v[42:45], v[90:93], v[174:177], v[42:45]
	s_waitcnt lgkmcnt(3)
	v_mfma_f32_16x16x32_bf16 v[30:33], v[62:65], v[182:185], v[30:33]
	v_mfma_f32_16x16x32_bf16 v[26:29], v[90:93], v[182:185], v[26:29]
	s_waitcnt lgkmcnt(1)
	v_mfma_f32_16x16x32_bf16 v[14:17], v[62:65], v[210:213], v[14:17]
	v_mfma_f32_16x16x32_bf16 v[10:13], v[90:93], v[210:213], v[10:13]
	v_mfma_f32_16x16x32_bf16 v[70:73], v[74:77], v[162:165], v[70:73]
	v_mfma_f32_16x16x32_bf16 v[66:69], v[98:101], v[162:165], v[66:69]
	v_mfma_f32_16x16x32_bf16 v[46:49], v[74:77], v[178:181], v[46:49]
	v_mfma_f32_16x16x32_bf16 v[42:45], v[98:101], v[178:181], v[42:45]
	v_mfma_f32_16x16x32_bf16 v[30:33], v[74:77], v[186:189], v[30:33]
	v_mfma_f32_16x16x32_bf16 v[26:29], v[98:101], v[186:189], v[26:29]
	s_waitcnt lgkmcnt(0)
	v_mfma_f32_16x16x32_bf16 v[14:17], v[74:77], v[230:233], v[14:17]
	v_mfma_f32_16x16x32_bf16 v[10:13], v[98:101], v[230:233], v[10:13]
	v_mfma_f32_16x16x32_bf16 v[58:61], v[114:117], v[158:161], v[58:61]
	v_mfma_f32_16x16x32_bf16 v[54:57], v[138:141], v[158:161], v[54:57]
	v_mfma_f32_16x16x32_bf16 v[38:41], v[114:117], v[174:177], v[38:41]
	v_mfma_f32_16x16x32_bf16 v[34:37], v[138:141], v[174:177], v[34:37]
	v_mfma_f32_16x16x32_bf16 v[22:25], v[114:117], v[182:185], v[22:25]
	v_mfma_f32_16x16x32_bf16 v[18:21], v[138:141], v[182:185], v[18:21]
	v_mfma_f32_16x16x32_bf16 v[6:9], v[114:117], v[210:213], v[6:9]
	v_mfma_f32_16x16x32_bf16 v[2:5], v[138:141], v[210:213], v[2:5]
	v_mfma_f32_16x16x32_bf16 v[58:61], v[122:125], v[162:165], v[58:61]
	v_mfma_f32_16x16x32_bf16 v[54:57], v[146:149], v[162:165], v[54:57]
	v_mfma_f32_16x16x32_bf16 v[38:41], v[122:125], v[178:181], v[38:41]
	v_mfma_f32_16x16x32_bf16 v[34:37], v[146:149], v[178:181], v[34:37]
	v_mfma_f32_16x16x32_bf16 v[22:25], v[122:125], v[186:189], v[22:25]
	v_mfma_f32_16x16x32_bf16 v[18:21], v[146:149], v[186:189], v[18:21]
	v_mfma_f32_16x16x32_bf16 v[6:9], v[122:125], v[230:233], v[6:9]
	v_mfma_f32_16x16x32_bf16 v[2:5], v[146:149], v[230:233], v[2:5]
	s_barrier
	v_add_u32_e32 v0, 0x18000, v227
	ds_read_b128 v[62:65], v0
	ds_read_b128 v[74:77], v0 offset:1024
	ds_read_b128 v[90:93], v0 offset:2048
	ds_read_b128 v[98:101], v0 offset:3072
	v_add_u32_e32 v0, 0x1c000, v227
	ds_read_b128 v[114:117], v0
	ds_read_b128 v[122:125], v0 offset:1024
	ds_read_b128 v[138:141], v0 offset:2048
	ds_read_b128 v[146:149], v0 offset:3072
	ds_read_b128 v[158:161], v228 offset:32768
	ds_read_b128 v[162:165], v228 offset:33792
	ds_read_b128 v[174:177], v228 offset:34816
	ds_read_b128 v[178:181], v228 offset:35840
	ds_read_b128 v[182:185], v228 offset:36864
	ds_read_b128 v[186:189], v228 offset:37888
	ds_read_b128 v[210:213], v228 offset:38912
	ds_read_b128 v[230:233], v228 offset:39936
	s_add_u32 s56, s56, 0xb0000
	s_addc_u32 s57, s57, 0
	v_lshl_add_u64 v[190:191], s[56:57], 0, v[198:199]
	s_mov_b32 s64, m0
	s_mov_b32 m0, s90
	s_nop 0
	global_load_lds_dwordx4 v[190:191], off
	s_mov_b32 m0, s64
	v_lshl_add_u64 v[190:191], s[56:57], 0, v[202:203]
	s_mov_b32 s56, m0
	s_mov_b32 m0, s91
	s_nop 0
	global_load_lds_dwordx4 v[190:191], off
	s_mov_b32 m0, s56
	s_waitcnt vmcnt(8)
	s_waitcnt lgkmcnt(0)
	s_barrier
	s_waitcnt lgkmcnt(7)
	v_mfma_f32_16x16x32_bf16 v[170:173], v[62:65], v[158:161], v[170:173]
	v_mfma_f32_16x16x32_bf16 v[166:169], v[90:93], v[158:161], v[166:169]
	s_waitcnt lgkmcnt(5)
	v_mfma_f32_16x16x32_bf16 v[142:145], v[62:65], v[174:177], v[142:145]
	v_mfma_f32_16x16x32_bf16 v[134:137], v[90:93], v[174:177], v[134:137]
	s_waitcnt lgkmcnt(3)
	v_mfma_f32_16x16x32_bf16 v[118:121], v[62:65], v[182:185], v[118:121]
	v_mfma_f32_16x16x32_bf16 v[110:113], v[90:93], v[182:185], v[110:113]
	s_waitcnt lgkmcnt(1)
	v_mfma_f32_16x16x32_bf16 v[94:97], v[62:65], v[210:213], v[94:97]
	v_mfma_f32_16x16x32_bf16 v[86:89], v[90:93], v[210:213], v[86:89]
	v_mfma_f32_16x16x32_bf16 v[170:173], v[74:77], v[162:165], v[170:173]
	v_mfma_f32_16x16x32_bf16 v[166:169], v[98:101], v[162:165], v[166:169]
	v_mfma_f32_16x16x32_bf16 v[142:145], v[74:77], v[178:181], v[142:145]
	v_mfma_f32_16x16x32_bf16 v[134:137], v[98:101], v[178:181], v[134:137]
	v_mfma_f32_16x16x32_bf16 v[118:121], v[74:77], v[186:189], v[118:121]
	v_mfma_f32_16x16x32_bf16 v[110:113], v[98:101], v[186:189], v[110:113]
	s_waitcnt lgkmcnt(0)
	v_mfma_f32_16x16x32_bf16 v[94:97], v[74:77], v[230:233], v[94:97]
	v_mfma_f32_16x16x32_bf16 v[86:89], v[98:101], v[230:233], v[86:89]
	v_mfma_f32_16x16x32_bf16 v[154:157], v[114:117], v[158:161], v[154:157]
	v_mfma_f32_16x16x32_bf16 v[150:153], v[138:141], v[158:161], v[150:153]
	v_mfma_f32_16x16x32_bf16 v[130:133], v[114:117], v[174:177], v[130:133]
	v_mfma_f32_16x16x32_bf16 v[126:129], v[138:141], v[174:177], v[126:129]
	v_mfma_f32_16x16x32_bf16 v[106:109], v[114:117], v[182:185], v[106:109]
	v_mfma_f32_16x16x32_bf16 v[102:105], v[138:141], v[182:185], v[102:105]
	v_mfma_f32_16x16x32_bf16 v[82:85], v[114:117], v[210:213], v[82:85]
	v_mfma_f32_16x16x32_bf16 v[78:81], v[138:141], v[210:213], v[78:81]
	v_mfma_f32_16x16x32_bf16 v[154:157], v[122:125], v[162:165], v[154:157]
	v_mfma_f32_16x16x32_bf16 v[150:153], v[146:149], v[162:165], v[150:153]
	v_mfma_f32_16x16x32_bf16 v[130:133], v[122:125], v[178:181], v[130:133]
	v_mfma_f32_16x16x32_bf16 v[126:129], v[146:149], v[178:181], v[126:129]
	v_mfma_f32_16x16x32_bf16 v[106:109], v[122:125], v[186:189], v[106:109]
	v_mfma_f32_16x16x32_bf16 v[102:105], v[146:149], v[186:189], v[102:105]
	v_mfma_f32_16x16x32_bf16 v[82:85], v[122:125], v[230:233], v[82:85]
	v_mfma_f32_16x16x32_bf16 v[78:81], v[146:149], v[230:233], v[78:81]
	s_barrier
; #define PG8_STAGE(bufoff, gbase, voff) do { _Pragma("unroll") for (int _i = 0; _i < 2; ++_i) \
;         glds16_asm((const char*)(gbase) + (voff)[_i], ldsb + (unsigned)((bufoff) + _i * 8192)); } while (0)
; #define PG8_LDA(dst, b, h) do { _Pragma("unroll") for (int m = 0; m < 4; ++m) _Pragma("unroll") for (int k = 0; k < 2; ++k) dst[m][k] = *(const PG8_LAS bf16x8*)(lds + PG8_SA(b, h) + aoff + m * 2048 + k * 1024); } while (0)
; #define PG8_LDB(dst, b, h) do { _Pragma("unroll") for (int n = 0; n < 2; ++n) _Pragma("unroll") for (int k = 0; k < 2; ++k) dst[n][k] = *(const PG8_LAS bf16x8*)(lds + PG8_SB(b, h) + boff + n * 2048 + k * 1024); } while (0)
; #define PG8_MMA(ai, bj, At, Bt) do { __builtin_amdgcn_s_setprio(1); _Pragma("unroll") for (int m = 0; m < 4; ++m) _Pragma("unroll") for (int n = 0; n < 2; ++n) _Pragma("unroll") for (int k = 0; k < 2; ++k) \
;         acc[ai][bj][m][n] = __builtin_amdgcn_mfma_f32_16x16x32_bf16(Bt[n][k], At[m][k], acc[ai][bj][m][n], 0, 0, 0); __builtin_amdgcn_s_setprio(0); } while (0)
; #define PG8_WAIT_V(n) asm volatile("s_waitcnt vmcnt(" #n ")" ::: "memory")
; #define PG8_BAR __builtin_amdgcn_s_barrier()
; template <class Epi, class Sched, bool ALIGN_EPI = false, bool SP2 = false>
; __device__ __forceinline__ void gemm_phase(PG8_LAS unsigned char* lds, const Gemm g, const Sched& S, const Epi& E, int wave_u) {
;     ...
;             PG8_LDB(B0, 0, 0); PG8_LDB(B1, 0, 1); PG8_SCHED; PG8_LDA(At, 0, 0); PG8_STAGE(PG8_SA(1, 1), a1 + hstep, voffA);
;             PG8_WAIT_V(8); PG8_WAIT_L(0); PG8_BAR; PG8_MMA(0, 0, At, B0); PG8_MMA(0, 1, At, B1); PG8_BAR; PG8_SCHED;
;             PG8_LDA(At, 0, 1); PG8_STAGE(PG8_SB(0, 0), b2, voffB); PG8_STAGE(PG8_SB(0, 1), b2 + hstep, voffB); PG8_STAGE(PG8_SA(0, 0), a2, voffA);
;             PG8_WAIT_V(8); PG8_WAIT_L(0); PG8_BAR; PG8_MMA(1, 0, At, B0); PG8_MMA(1, 1, At, B1); PG8_BAR; PG8_SCHED;
;             PG8_LDB(B0, 1, 0); PG8_LDB(B1, 1, 1); PG8_SCHED; PG8_LDA(At, 1, 0); PG8_STAGE(PG8_SA(0, 1), a2 + hstep, voffA);
;             PG8_WAIT_V(8); PG8_WAIT_L(0); PG8_BAR; PG8_MMA(0, 0, At, B0); PG8_MMA(0, 1, At, B1); PG8_BAR; PG8_SCHED;
;             PG8_LDA(At, 1, 1); PG8_STAGE(PG8_SB(1, 0), b3, voffB); PG8_STAGE(PG8_SB(1, 1), b3 + hstep, voffB); PG8_STAGE(PG8_SA(1, 0), a3, voffA);
;             PG8_WAIT_V(8); PG8_WAIT_L(0); PG8_BAR; PG8_MMA(1, 0, At, B0); PG8_MMA(1, 1, At, B1); PG8_BAR; PG8_SCHED;
	ds_read_b128 v[158:161], v228 offset:49152
	ds_read_b128 v[162:165], v228 offset:50176
	ds_read_b128 v[174:177], v228 offset:51200
	ds_read_b128 v[178:181], v228 offset:52224
	ds_read_b128 v[182:185], v228 offset:53248
	ds_read_b128 v[186:189], v228 offset:54272
	ds_read_b128 v[210:213], v228 offset:55296
	ds_read_b128 v[230:233], v228 offset:56320
	v_lshl_add_u64 v[190:191], s[48:49], 0, v[200:201]
	s_mov_b32 s56, m0
	s_mov_b32 m0, s62
	s_nop 0
	global_load_lds_dwordx4 v[190:191], off
	s_mov_b32 m0, s56
	s_add_u32 s44, s44, 0xb0080
	v_lshl_add_u64 v[190:191], s[48:49], 0, v[204:205]
	s_mov_b32 s48, m0
	s_mov_b32 m0, s63
	s_nop 0
	global_load_lds_dwordx4 v[190:191], off
	s_mov_b32 m0, s48
	s_addc_u32 s45, s45, 0
	v_lshl_add_u64 v[190:191], s[44:45], 0, v[200:201]
	s_mov_b32 s48, m0
	s_mov_b32 m0, s66
	s_nop 0
	global_load_lds_dwordx4 v[190:191], off
	s_mov_b32 m0, s48
	v_lshl_add_u64 v[190:191], s[44:45], 0, v[204:205]
	s_mov_b32 s44, m0
	s_mov_b32 m0, s67
	s_nop 0
	global_load_lds_dwordx4 v[190:191], off
	s_mov_b32 m0, s44
	v_lshl_add_u64 v[190:191], s[46:47], 0, v[198:199]
	s_mov_b32 s44, m0
	s_mov_b32 m0, s40
	s_nop 0
	global_load_lds_dwordx4 v[190:191], off
	s_mov_b32 m0, s44
	v_lshl_add_u64 v[190:191], s[46:47], 0, v[202:203]
	s_mov_b32 s44, m0
	s_mov_b32 m0, s41
	s_nop 0
	global_load_lds_dwordx4 v[190:191], off
	s_mov_b32 m0, s44
	s_waitcnt vmcnt(8)
	s_waitcnt lgkmcnt(0)
	s_barrier
	s_waitcnt lgkmcnt(7)
	v_mfma_f32_16x16x32_bf16 v[70:73], v[62:65], v[158:161], v[70:73]
	v_mfma_f32_16x16x32_bf16 v[66:69], v[90:93], v[158:161], v[66:69]
	s_waitcnt lgkmcnt(5)
	v_mfma_f32_16x16x32_bf16 v[46:49], v[62:65], v[174:177], v[46:49]
	v_mfma_f32_16x16x32_bf16 v[42:45], v[90:93], v[174:177], v[42:45]
	s_waitcnt lgkmcnt(3)
	v_mfma_f32_16x16x32_bf16 v[30:33], v[62:65], v[182:185], v[30:33]
	v_mfma_f32_16x16x32_bf16 v[26:29], v[90:93], v[182:185], v[26:29]
	s_waitcnt lgkmcnt(1)
	v_mfma_f32_16x16x32_bf16 v[14:17], v[62:65], v[210:213], v[14:17]
	v_mfma_f32_16x16x32_bf16 v[10:13], v[90:93], v[210:213], v[10:13]
	v_mfma_f32_16x16x32_bf16 v[70:73], v[74:77], v[162:165], v[70:73]
	v_mfma_f32_16x16x32_bf16 v[66:69], v[98:101], v[162:165], v[66:69]
	v_mfma_f32_16x16x32_bf16 v[46:49], v[74:77], v[178:181], v[46:49]
	v_mfma_f32_16x16x32_bf16 v[42:45], v[98:101], v[178:181], v[42:45]
	v_mfma_f32_16x16x32_bf16 v[30:33], v[74:77], v[186:189], v[30:33]
	v_mfma_f32_16x16x32_bf16 v[26:29], v[98:101], v[186:189], v[26:29]
	s_waitcnt lgkmcnt(0)
	v_mfma_f32_16x16x32_bf16 v[14:17], v[74:77], v[230:233], v[14:17]
	v_mfma_f32_16x16x32_bf16 v[10:13], v[98:101], v[230:233], v[10:13]
	v_mfma_f32_16x16x32_bf16 v[58:61], v[114:117], v[158:161], v[58:61]
	v_mfma_f32_16x16x32_bf16 v[54:57], v[138:141], v[158:161], v[54:57]
	v_mfma_f32_16x16x32_bf16 v[38:41], v[114:117], v[174:177], v[38:41]
	v_mfma_f32_16x16x32_bf16 v[34:37], v[138:141], v[174:177], v[34:37]
	v_mfma_f32_16x16x32_bf16 v[22:25], v[114:117], v[182:185], v[22:25]
	v_mfma_f32_16x16x32_bf16 v[18:21], v[138:141], v[182:185], v[18:21]
	v_mfma_f32_16x16x32_bf16 v[6:9], v[114:117], v[210:213], v[6:9]
	v_mfma_f32_16x16x32_bf16 v[2:5], v[138:141], v[210:213], v[2:5]
	v_mfma_f32_16x16x32_bf16 v[58:61], v[122:125], v[162:165], v[58:61]
	v_mfma_f32_16x16x32_bf16 v[54:57], v[146:149], v[162:165], v[54:57]
	v_mfma_f32_16x16x32_bf16 v[38:41], v[122:125], v[178:181], v[38:41]
	v_mfma_f32_16x16x32_bf16 v[34:37], v[146:149], v[178:181], v[34:37]
	v_mfma_f32_16x16x32_bf16 v[22:25], v[122:125], v[186:189], v[22:25]
	v_mfma_f32_16x16x32_bf16 v[18:21], v[146:149], v[186:189], v[18:21]
	v_mfma_f32_16x16x32_bf16 v[6:9], v[122:125], v[230:233], v[6:9]
	v_mfma_f32_16x16x32_bf16 v[2:5], v[146:149], v[230:233], v[2:5]
	s_barrier
	s_add_i32 s1, s1, 2
	s_add_u32 s28, s28, 0x100
	s_addc_u32 s29, s29, 0
	s_add_u32 s60, s60, 0x100
	s_addc_u32 s61, s61, 0
	s_cmp_gt_u32 s1, 41
	s_cbranch_scc1 .LBB0_1431

; #define PG8_WAIT_V(n) asm volatile("s_waitcnt vmcnt(" #n ")" ::: "memory")
; #define PG8_BAR __builtin_amdgcn_s_barrier()
; template <class Epi, class Sched, bool ALIGN_EPI = false, bool SP2 = false>
; __device__ __forceinline__ void gemm_phase(PG8_LAS unsigned char* lds, const Gemm g, const Sched& S, const Epi& E, int wave_u) {
;     ...
;     PG8_WAIT_V(0);
;     if constexpr (!ALIGN_EPI) { if (wr == 0) PG8_BAR; }
;     PG8_BAR;
.LBB0_1452:
	v_readlane_b32 s78, v255, 13
	s_setprio 0
	s_waitcnt vmcnt(0)
	v_readlane_b32 s79, v255, 14
	s_mov_b32 s92, s78
	v_readlane_b32 s64, v255, 16
	v_readlane_b32 s76, v255, 18
	v_readlane_b32 s78, v255, 20
	v_readlane_b32 s80, v255, 22
	v_readlane_b32 s82, v255, 24
	v_readlane_b32 s86, v255, 26
	v_readlane_b32 s88, v255, 28
	v_readlane_b32 s75, v255, 15
	v_readlane_b32 s65, v255, 17
	v_readlane_b32 s77, v255, 19
	v_readlane_b32 s79, v255, 21
	v_readlane_b32 s81, v255, 23
	v_readlane_b32 s83, v255, 25
	v_readlane_b32 s87, v255, 27
	v_readlane_b32 s89, v255, 29
	s_mov_b32 s96, 0x11000
	s_mov_b64 s[84:85], 0x100
	v_readlane_b32 s14, v255, 43
	v_readlane_b32 s15, v255, 45
	s_barrier
